# attention back-edge barrier sunk below the next unit's table-load issue (exit path keeps its own barrier)
# baseline (speedup 1.0000x reference)
; __device__ __forceinline__ void attn_phase_mfma(const Ctx& c, unsigned char* lds_raw, bool do_store) {
;     ...
;             const int rp = id % 192, dc8 = id / 192;
; #pragma unroll
;             for (int e = 0; e < 4; ++e) {
;                 Vt[(8 * dc8 + 2 * e) * 194 + rp] = __builtin_amdgcn_perm(vb[i][e], va[i][e], 0x05040100u);
;                 Vt[(8 * dc8 + 2 * e + 1) * 194 + rp] = __builtin_amdgcn_perm(vb[i][e], va[i][e], 0x07060302u);
;             }
.LBB0_358:
	s_or_b64 exec, exec, s[0:1]
	s_add_i32 s4, s4, s5
	s_waitcnt vmcnt(8)
	v_mov_b64_e32 v[10:11], v[142:143]
	s_waitcnt vmcnt(7)
	v_mov_b64_e32 v[2:3], v[138:139]
	s_waitcnt vmcnt(6)
	v_mov_b64_e32 v[14:15], v[134:135]
	s_waitcnt vmcnt(5)
	v_mov_b64_e32 v[6:7], v[130:131]
	s_cmpk_lt_i32 s33, 0x600
	v_mov_b64_e32 v[12:13], v[144:145]
	v_mov_b64_e32 v[4:5], v[140:141]
	v_mov_b64_e32 v[16:17], v[136:137]
	v_mov_b64_e32 v[8:9], v[132:133]
	s_cbranch_scc0 .Lattn_exit_bar_a
.LBB0_359:
	s_mul_hi_i32 s0, s33, 0x2aaaaaab
	s_lshr_b32 s1, s0, 31
	s_ashr_i32 s0, s0, 5
	s_add_i32 s90, s0, s1
	s_mul_i32 s0, s90, 0xffffff40
	s_add_i32 s91, s33, s0
	s_ashr_i32 s88, s91, 6
	s_lshl_b32 s96, s88, 1
	s_lshr_b32 s1, 16, s96
	s_and_b32 s0, s91, 15
	s_sub_i32 s2, 4, s96
	s_add_i32 s1, s1, -1
	s_lshr_b32 s2, s0, s2
	s_and_b32 s0, s1, s0
	s_lshl_b32 s9, s0, 8
	s_sub_i32 s89, s9, 64
	v_add_u32_e32 v18, s9, v180
	v_add_u32_e32 v34, s89, v1
	v_lshlrev_b32_e32 v18, s96, v18
	v_lshlrev_b32_e32 v34, s96, v34
	v_add_u32_e32 v58, s2, v18
	v_add_u32_e32 v34, s2, v34
	v_lshlrev_b32_e32 v18, 6, v58
	v_med3_i32 v34, v34, 0, v221
	v_ashrrev_i32_e32 v19, 31, v18
	v_lshlrev_b32_e32 v34, 7, v34
	v_mov_b32_e32 v35, v106
	v_lshl_add_u64 v[18:19], v[18:19], 1, v[170:171]
	v_lshl_add_u64 v[34:35], v[172:173], 0, v[34:35]
	global_load_dwordx4 v[30:33], v[18:19], off
	global_load_dwordx4 v[22:25], v[18:19], off offset:32
	global_load_dwordx4 v[26:29], v[18:19], off offset:64
	s_nop 0
	global_load_dwordx4 v[18:21], v[18:19], off offset:96
	s_nop 0
	global_load_dwordx4 v[54:57], v[34:35], off
	global_load_dwordx4 v[50:53], v[34:35], off offset:64
	v_add_u32_e32 v34, s89, v176
	v_lshlrev_b32_e32 v34, s96, v34
	v_add_u32_e32 v34, s2, v34
	v_med3_i32 v34, v34, 0, v221
	v_lshlrev_b32_e32 v34, 7, v34
	v_mov_b32_e32 v35, v106
	v_lshl_add_u64 v[34:35], v[172:173], 0, v[34:35]
	global_load_dwordx4 v[46:49], v[34:35], off
	global_load_dwordx4 v[42:45], v[34:35], off offset:64
	v_add_u32_e32 v34, s89, v178
	v_lshlrev_b32_e32 v34, s96, v34
	v_add_u32_e32 v34, s2, v34
	v_med3_i32 v34, v34, 0, v221
	v_lshlrev_b32_e32 v34, 7, v34
	v_mov_b32_e32 v35, v106
	v_lshl_add_u64 v[34:35], v[172:173], 0, v[34:35]
	global_load_dwordx4 v[38:41], v[34:35], off
	s_nop 0
	global_load_dwordx4 v[34:37], v[34:35], off offset:64
	s_barrier
	v_lshlrev_b32_e32 v62, 16, v86
	v_and_b32_e32 v63, 0xffff0000, v86
	v_lshlrev_b32_e32 v60, 16, v90
	v_and_b32_e32 v61, 0xffff0000, v90
	v_readlane_b32 s0, v255, 12
	s_add_i32 s33, s33, s0
	s_cmpk_gt_i32 s33, 0x5ff
	v_perm_b32 v250, v94, v82, s6
	v_perm_b32 v251, v94, v82, s7
	v_add_u32_e32 v252, 0xc000, v181
	ds_write2_b32 v252, v250, v251 offset1:194
	v_perm_b32 v250, v95, v83, s6
	v_perm_b32 v251, v95, v83, s7
	v_add_u32_e32 v252, 0xc600, v181
	ds_write2_b32 v252, v250, v251 offset0:4 offset1:198
	v_perm_b32 v250, v96, v84, s6
	v_perm_b32 v251, v96, v84, s7
	v_add_u32_e32 v252, 0xcc00, v181
	ds_write2_b32 v252, v250, v251 offset0:8 offset1:202
	v_perm_b32 v250, v97, v85, s6
	v_perm_b32 v251, v97, v85, s7
	v_add_u32_e32 v252, 0xd200, v181
	ds_write2_b32 v252, v250, v251 offset0:12 offset1:206
	v_perm_b32 v250, v114, v110, s6
	v_perm_b32 v251, v114, v110, s7
	v_add_u32_e32 v252, 0xc800, v182
	ds_write2_b32 v252, v250, v251 offset1:194
	v_perm_b32 v250, v115, v111, s6
	v_perm_b32 v251, v115, v111, s7
	v_add_u32_e32 v252, 0xce00, v182
	ds_write2_b32 v252, v250, v251 offset0:4 offset1:198
	v_perm_b32 v250, v116, v112, s6
	v_perm_b32 v251, v116, v112, s7
	v_add_u32_e32 v252, 0xd400, v182
	ds_write2_b32 v252, v250, v251 offset0:8 offset1:202
	v_perm_b32 v250, v117, v113, s6
	v_perm_b32 v251, v117, v113, s7
	v_add_u32_e32 v252, 0xda00, v182
	ds_write2_b32 v252, v250, v251 offset0:12 offset1:206
	v_perm_b32 v250, v146, v126, s6
	v_perm_b32 v251, v146, v126, s7
	v_add_u32_e32 v252, 0xd000, v183
	ds_write2_b32 v252, v250, v251 offset1:194
	v_perm_b32 v250, v147, v127, s6
	v_perm_b32 v251, v147, v127, s7
	v_add_u32_e32 v252, 0xd600, v183
	ds_write2_b32 v252, v250, v251 offset0:4 offset1:198
	v_perm_b32 v250, v148, v128, s6
	v_perm_b32 v251, v148, v128, s7
	v_add_u32_e32 v252, 0xdc00, v183
	ds_write2_b32 v252, v250, v251 offset0:8 offset1:202
	v_perm_b32 v250, v149, v129, s6
	v_perm_b32 v251, v149, v129, s7
	v_add_u32_e32 v252, 0xe200, v183
	ds_write2_b32 v252, v250, v251 offset0:12 offset1:206
	s_waitcnt vmcnt(5)
	v_cvt_f32_f16_e32 v64, v54
	s_waitcnt vmcnt(4)
; __device__ __forceinline__ float bflo(unsigned w) { return __uint_as_float(w << 16); }
; __device__ __forceinline__ float bfhi(unsigned w) { return __uint_as_float(w & 0xffff0000u); }
; __device__ __forceinline__ unsigned pk2(float lo, float hi) { const f32x2n v = {lo, hi}; return __builtin_bit_cast(unsigned, __builtin_convertvector(v, bf16x2n)); }
; #define LASP __attribute__((address_space(3)))
; __device__ __forceinline__ void attn_phase_mfma(const Ctx& c, unsigned char* lds_raw, bool do_store) {
;     ...
;         for (int i = 0; i < 3; ++i) {
;             const int id = t + 512 * i, row = id >> 2, dc = id & 3;
;             const h16x8 kcv = tkc[i], ksv = tks[i];
;             u32x4 olo, ohi;
; #pragma unroll
;             for (int e = 0; e < 4; ++e) {
;                 const float l0 = bflo(ka[i][e]), l1 = bfhi(ka[i][e]), h0 = bflo(kb2[i][e]), h1 = bfhi(kb2[i][e]);
;                 const float cc0 = (float)kcv[2 * e], cc1 = (float)kcv[2 * e + 1], ss0 = (float)ksv[2 * e], ss1 = (float)ksv[2 * e + 1];
;                 olo[e] = pk2(l0 * cc0 - h0 * ss0, l1 * cc1 - h1 * ss1);
;                 ohi[e] = pk2(h0 * cc0 + l0 * ss0, h1 * cc1 + l1 * ss1);
;             }
;             *(LASP u32x4*)(Kt + row * 128 + ((dc ^ (row & 7)) << 4)) = olo;
;             *(LASP u32x4*)(Kt + row * 128 + (((4 + dc) ^ (row & 7)) << 4)) = ohi;
	v_cvt_f32_f16_e32 v66, v50
	v_cvt_f32_f16_sdwa v67, v50 dst_sel:DWORD dst_unused:UNUSED_PAD src0_sel:WORD_1
	v_cvt_f32_f16_sdwa v65, v54 dst_sel:DWORD dst_unused:UNUSED_PAD src0_sel:WORD_1
	v_pk_mul_f32 v[68:69], v[62:63], v[66:67]
	s_nop 0
	v_pk_fma_f32 v[68:69], v[60:61], v[64:65], v[68:69] neg_lo:[0,0,1] neg_hi:[0,0,1]
	v_pk_mul_f32 v[60:61], v[60:61], v[66:67]
	v_cvt_f32_f16_e32 v66, v51
	v_cvt_f32_f16_sdwa v67, v51 dst_sel:DWORD dst_unused:UNUSED_PAD src0_sel:WORD_1
	v_pk_fma_f32 v[60:61], v[62:63], v[64:65], v[60:61]
	v_cvt_f32_f16_e32 v64, v55
	v_cvt_f32_f16_sdwa v65, v55 dst_sel:DWORD dst_unused:UNUSED_PAD src0_sel:WORD_1
	v_lshlrev_b32_e32 v62, 16, v87
	v_and_b32_e32 v63, 0xffff0000, v87
	v_cvt_pk_bf16_f32 v50, v68, v69
	v_cvt_pk_bf16_f32 v54, v60, v61
	v_lshlrev_b32_e32 v60, 16, v91
	v_and_b32_e32 v61, 0xffff0000, v91
	v_pk_mul_f32 v[68:69], v[62:63], v[66:67]
	s_nop 0
	v_pk_fma_f32 v[68:69], v[60:61], v[64:65], v[68:69] neg_lo:[0,0,1] neg_hi:[0,0,1]
	v_pk_mul_f32 v[60:61], v[60:61], v[66:67]
	v_cvt_f32_f16_e32 v66, v52
	v_cvt_f32_f16_sdwa v67, v52 dst_sel:DWORD dst_unused:UNUSED_PAD src0_sel:WORD_1
	v_pk_fma_f32 v[60:61], v[62:63], v[64:65], v[60:61]
	v_cvt_f32_f16_e32 v64, v56
	v_cvt_f32_f16_sdwa v65, v56 dst_sel:DWORD dst_unused:UNUSED_PAD src0_sel:WORD_1
	v_lshlrev_b32_e32 v62, 16, v88
	v_and_b32_e32 v63, 0xffff0000, v88
	v_cvt_pk_bf16_f32 v51, v68, v69
	v_cvt_pk_bf16_f32 v55, v60, v61
	v_lshlrev_b32_e32 v60, 16, v92
	v_and_b32_e32 v61, 0xffff0000, v92
	v_pk_mul_f32 v[68:69], v[62:63], v[66:67]
	s_nop 0
	v_pk_fma_f32 v[68:69], v[60:61], v[64:65], v[68:69] neg_lo:[0,0,1] neg_hi:[0,0,1]
	v_pk_mul_f32 v[60:61], v[60:61], v[66:67]
	v_cvt_f32_f16_e32 v66, v53
	v_cvt_f32_f16_sdwa v67, v53 dst_sel:DWORD dst_unused:UNUSED_PAD src0_sel:WORD_1
	v_pk_fma_f32 v[60:61], v[62:63], v[64:65], v[60:61]
	v_cvt_f32_f16_e32 v64, v57
	v_cvt_f32_f16_sdwa v65, v57 dst_sel:DWORD dst_unused:UNUSED_PAD src0_sel:WORD_1
	v_lshlrev_b32_e32 v62, 16, v89
	v_and_b32_e32 v63, 0xffff0000, v89
	v_cvt_pk_bf16_f32 v52, v68, v69
	v_cvt_pk_bf16_f32 v56, v60, v61
	v_lshlrev_b32_e32 v60, 16, v93
	v_and_b32_e32 v61, 0xffff0000, v93
	v_pk_mul_f32 v[68:69], v[62:63], v[66:67]
	s_nop 0
	v_pk_fma_f32 v[68:69], v[60:61], v[64:65], v[68:69] neg_lo:[0,0,1] neg_hi:[0,0,1]
	v_pk_mul_f32 v[60:61], v[60:61], v[66:67]
	v_cvt_pk_bf16_f32 v53, v68, v69
	v_pk_fma_f32 v[60:61], v[62:63], v[64:65], v[60:61]
	s_nop 0
	v_cvt_pk_bf16_f32 v57, v60, v61
	ds_write_b128 v210, v[50:53]
	ds_write_b128 v211, v[54:57]
	s_waitcnt vmcnt(2)
	v_cvt_f32_f16_e32 v56, v42
	v_cvt_f32_f16_sdwa v57, v42 dst_sel:DWORD dst_unused:UNUSED_PAD src0_sel:WORD_1
	v_cvt_f32_f16_e32 v54, v46
	v_cvt_f32_f16_sdwa v55, v46 dst_sel:DWORD dst_unused:UNUSED_PAD src0_sel:WORD_1
	v_lshlrev_b32_e32 v52, 16, v98
	v_and_b32_e32 v53, 0xffff0000, v98
	v_lshlrev_b32_e32 v50, 16, v102
	v_and_b32_e32 v51, 0xffff0000, v102
	v_pk_mul_f32 v[60:61], v[52:53], v[56:57]
	s_nop 0
	v_pk_fma_f32 v[60:61], v[50:51], v[54:55], v[60:61] neg_lo:[0,0,1] neg_hi:[0,0,1]
	v_pk_mul_f32 v[50:51], v[50:51], v[56:57]
	v_cvt_f32_f16_e32 v56, v43
	v_cvt_f32_f16_sdwa v57, v43 dst_sel:DWORD dst_unused:UNUSED_PAD src0_sel:WORD_1
	v_pk_fma_f32 v[50:51], v[52:53], v[54:55], v[50:51]
	v_cvt_f32_f16_e32 v54, v47
	v_cvt_f32_f16_sdwa v55, v47 dst_sel:DWORD dst_unused:UNUSED_PAD src0_sel:WORD_1
	v_lshlrev_b32_e32 v52, 16, v99
	v_and_b32_e32 v53, 0xffff0000, v99
	v_cvt_pk_bf16_f32 v42, v60, v61
	v_cvt_pk_bf16_f32 v46, v50, v51
	v_lshlrev_b32_e32 v50, 16, v103
	v_and_b32_e32 v51, 0xffff0000, v103
	v_pk_mul_f32 v[60:61], v[52:53], v[56:57]
	s_nop 0
	v_pk_fma_f32 v[60:61], v[50:51], v[54:55], v[60:61] neg_lo:[0,0,1] neg_hi:[0,0,1]
	v_pk_mul_f32 v[50:51], v[50:51], v[56:57]
	v_cvt_f32_f16_e32 v56, v44
	v_cvt_f32_f16_sdwa v57, v44 dst_sel:DWORD dst_unused:UNUSED_PAD src0_sel:WORD_1
	v_pk_fma_f32 v[50:51], v[52:53], v[54:55], v[50:51]
	v_cvt_f32_f16_e32 v54, v48
	v_cvt_f32_f16_sdwa v55, v48 dst_sel:DWORD dst_unused:UNUSED_PAD src0_sel:WORD_1
	v_lshlrev_b32_e32 v52, 16, v100
	v_and_b32_e32 v53, 0xffff0000, v100
	v_cvt_pk_bf16_f32 v43, v60, v61
	v_cvt_pk_bf16_f32 v47, v50, v51
	v_lshlrev_b32_e32 v50, 16, v104
	v_and_b32_e32 v51, 0xffff0000, v104
	v_pk_mul_f32 v[60:61], v[52:53], v[56:57]
	s_nop 0
	v_pk_fma_f32 v[60:61], v[50:51], v[54:55], v[60:61] neg_lo:[0,0,1] neg_hi:[0,0,1]
	v_pk_mul_f32 v[50:51], v[50:51], v[56:57]
	v_cvt_f32_f16_e32 v56, v45
	v_cvt_f32_f16_sdwa v57, v45 dst_sel:DWORD dst_unused:UNUSED_PAD src0_sel:WORD_1
	v_pk_fma_f32 v[50:51], v[52:53], v[54:55], v[50:51]
	v_cvt_f32_f16_e32 v54, v49
	v_cvt_f32_f16_sdwa v55, v49 dst_sel:DWORD dst_unused:UNUSED_PAD src0_sel:WORD_1
	v_lshlrev_b32_e32 v52, 16, v101
	v_and_b32_e32 v53, 0xffff0000, v101
	v_cvt_pk_bf16_f32 v44, v60, v61
	v_cvt_pk_bf16_f32 v48, v50, v51
	v_lshlrev_b32_e32 v50, 16, v105
	v_and_b32_e32 v51, 0xffff0000, v105
	v_pk_mul_f32 v[60:61], v[52:53], v[56:57]
	s_nop 0
	v_pk_fma_f32 v[60:61], v[50:51], v[54:55], v[60:61] neg_lo:[0,0,1] neg_hi:[0,0,1]
	v_pk_mul_f32 v[50:51], v[50:51], v[56:57]
	v_cvt_pk_bf16_f32 v45, v60, v61
	v_pk_fma_f32 v[50:51], v[52:53], v[54:55], v[50:51]
	s_nop 0
	v_cvt_pk_bf16_f32 v49, v50, v51
	ds_write_b128 v212, v[42:45]
	ds_write_b128 v213, v[46:49]
	s_waitcnt vmcnt(0)
; __device__ __forceinline__ float bflo(unsigned w) { return __uint_as_float(w << 16); }
; __device__ __forceinline__ float bfhi(unsigned w) { return __uint_as_float(w & 0xffff0000u); }
; __device__ __forceinline__ unsigned pk2(float lo, float hi) { const f32x2n v = {lo, hi}; return __builtin_bit_cast(unsigned, __builtin_convertvector(v, bf16x2n)); }
; #define LASP __attribute__((address_space(3)))
; __device__ __forceinline__ void attn_phase_mfma(const Ctx& c, unsigned char* lds_raw, bool do_store) {
;     ...
;             for (int e = 0; e < 4; ++e) {
;                 const float l0 = bflo(ka[i][e]), l1 = bfhi(ka[i][e]), h0 = bflo(kb2[i][e]), h1 = bfhi(kb2[i][e]);
;                 const float cc0 = (float)kcv[2 * e], cc1 = (float)kcv[2 * e + 1], ss0 = (float)ksv[2 * e], ss1 = (float)ksv[2 * e + 1];
;                 olo[e] = pk2(l0 * cc0 - h0 * ss0, l1 * cc1 - h1 * ss1);
;                 ohi[e] = pk2(h0 * cc0 + l0 * ss0, h1 * cc1 + l1 * ss1);
;             }
;             *(LASP u32x4*)(Kt + row * 128 + ((dc ^ (row & 7)) << 4)) = olo;
;             *(LASP u32x4*)(Kt + row * 128 + (((4 + dc) ^ (row & 7)) << 4)) = ohi;
	v_cvt_f32_f16_e32 v48, v34
	v_cvt_f32_f16_sdwa v49, v34 dst_sel:DWORD dst_unused:UNUSED_PAD src0_sel:WORD_1
	v_cvt_f32_f16_e32 v46, v38
	v_cvt_f32_f16_sdwa v47, v38 dst_sel:DWORD dst_unused:UNUSED_PAD src0_sel:WORD_1
	v_lshlrev_b32_e32 v44, 16, v118
	v_and_b32_e32 v45, 0xffff0000, v118
	v_lshlrev_b32_e32 v42, 16, v122
	v_and_b32_e32 v43, 0xffff0000, v122
	v_pk_mul_f32 v[50:51], v[44:45], v[48:49]
	s_nop 0
	v_pk_fma_f32 v[50:51], v[42:43], v[46:47], v[50:51] neg_lo:[0,0,1] neg_hi:[0,0,1]
	v_pk_mul_f32 v[42:43], v[42:43], v[48:49]
	v_cvt_f32_f16_e32 v48, v35
	v_cvt_f32_f16_sdwa v49, v35 dst_sel:DWORD dst_unused:UNUSED_PAD src0_sel:WORD_1
	v_pk_fma_f32 v[42:43], v[44:45], v[46:47], v[42:43]
	v_cvt_f32_f16_e32 v46, v39
	v_cvt_f32_f16_sdwa v47, v39 dst_sel:DWORD dst_unused:UNUSED_PAD src0_sel:WORD_1
	v_lshlrev_b32_e32 v44, 16, v119
	v_and_b32_e32 v45, 0xffff0000, v119
	v_cvt_pk_bf16_f32 v34, v50, v51
	v_cvt_pk_bf16_f32 v38, v42, v43
	v_lshlrev_b32_e32 v42, 16, v123
	v_and_b32_e32 v43, 0xffff0000, v123
	v_pk_mul_f32 v[50:51], v[44:45], v[48:49]
	s_nop 0
	v_pk_fma_f32 v[50:51], v[42:43], v[46:47], v[50:51] neg_lo:[0,0,1] neg_hi:[0,0,1]
	v_pk_mul_f32 v[42:43], v[42:43], v[48:49]
	v_cvt_f32_f16_e32 v48, v36
	v_cvt_f32_f16_sdwa v49, v36 dst_sel:DWORD dst_unused:UNUSED_PAD src0_sel:WORD_1
	v_pk_fma_f32 v[42:43], v[44:45], v[46:47], v[42:43]
	v_cvt_f32_f16_e32 v46, v40
	v_cvt_f32_f16_sdwa v47, v40 dst_sel:DWORD dst_unused:UNUSED_PAD src0_sel:WORD_1
	v_lshlrev_b32_e32 v44, 16, v120
	v_and_b32_e32 v45, 0xffff0000, v120
	v_cvt_pk_bf16_f32 v35, v50, v51
	v_cvt_pk_bf16_f32 v39, v42, v43
	v_lshlrev_b32_e32 v42, 16, v124
	v_and_b32_e32 v43, 0xffff0000, v124
	v_pk_mul_f32 v[50:51], v[44:45], v[48:49]
	s_nop 0
	v_pk_fma_f32 v[50:51], v[42:43], v[46:47], v[50:51] neg_lo:[0,0,1] neg_hi:[0,0,1]
	v_pk_mul_f32 v[42:43], v[42:43], v[48:49]
	v_cvt_f32_f16_e32 v48, v37
	v_cvt_f32_f16_sdwa v49, v37 dst_sel:DWORD dst_unused:UNUSED_PAD src0_sel:WORD_1
	v_pk_fma_f32 v[42:43], v[44:45], v[46:47], v[42:43]
	v_cvt_f32_f16_e32 v46, v41
	v_cvt_f32_f16_sdwa v47, v41 dst_sel:DWORD dst_unused:UNUSED_PAD src0_sel:WORD_1
	v_lshlrev_b32_e32 v44, 16, v121
	v_and_b32_e32 v45, 0xffff0000, v121
	v_cvt_pk_bf16_f32 v36, v50, v51
	v_cvt_pk_bf16_f32 v40, v42, v43
	v_lshlrev_b32_e32 v42, 16, v125
	v_and_b32_e32 v43, 0xffff0000, v125
	v_pk_mul_f32 v[50:51], v[44:45], v[48:49]
	s_nop 0
	v_pk_fma_f32 v[50:51], v[42:43], v[46:47], v[50:51] neg_lo:[0,0,1] neg_hi:[0,0,1]
	v_pk_mul_f32 v[42:43], v[42:43], v[48:49]
	v_cvt_pk_bf16_f32 v37, v50, v51
	v_pk_fma_f32 v[42:43], v[44:45], v[46:47], v[42:43]
	s_nop 0
	v_cvt_pk_bf16_f32 v41, v42, v43
	ds_write_b128 v214, v[34:37]
	ds_write_b128 v215, v[38:41]
	s_waitcnt lgkmcnt(0)
	s_barrier
	s_cbranch_scc1 .LBB0_379
	s_mul_hi_i32 s0, s33, 0x2aaaaaab
	s_lshr_b32 s1, s0, 31
	s_ashr_i32 s0, s0, 5
	s_add_i32 s0, s0, s1
	s_mul_i32 s1, s0, 0xffffff40
	s_add_i32 s1, s33, s1
	s_ashr_i32 s11, s1, 6
	s_lshl_b32 s10, s11, 1
	s_lshr_b32 s2, 16, s10
	s_and_b32 s1, s1, 15
	s_sub_i32 s3, 4, s10
	s_add_i32 s2, s2, -1
	s_lshr_b32 s12, s1, s3
	s_and_b32 s1, s2, s1
	s_lshl_b32 s13, s1, 8
	s_ashr_i32 s1, s0, 31
	v_add_u32_e32 v34, s13, v180
	s_lshl_b64 s[2:3], s[0:1], 12
	v_lshlrev_b32_e32 v34, s10, v34
	s_or_b32 s0, s2, s12
	s_mov_b32 s1, s3
	v_ashrrev_i32_e32 v35, 31, v34
	v_lshl_add_u64 v[34:35], s[0:1], 0, v[34:35]
	v_mov_b64_e32 v[36:37], s[92:93]
	v_mad_u64_u32 v[36:37], s[74:75], v34, s8, v[36:37]
	s_lshl_b32 s11, s11, 8
	s_and_b32 s74, s4, 0xc0
	s_or_b32 s94, s11, s74
	v_mad_i32_i24 v37, v35, s8, v37
	s_ashr_i32 s95, s94, 31
	v_lshl_add_u64 v[34:35], s[94:95], 1, v[36:37]
	v_mov_b32_e32 v169, v106
	v_lshl_add_u64 v[34:35], v[34:35], 0, v[168:169]
	global_load_dwordx4 v[142:145], v[34:35], off offset:1536
	global_load_dwordx4 v[138:141], v[34:35], off offset:1568
	global_load_dwordx4 v[134:137], v[34:35], off offset:1600
	global_load_dwordx4 v[130:133], v[34:35], off offset:1632
	s_sub_i32 s13, s13, 64
	s_lshr_b32 s11, 0x1000, s10
	v_add_u32_e32 v34, s13, v1
	v_mov_b32_e32 v84, v106
	v_mov_b32_e32 v85, v106
	v_cmp_lt_i32_e32 vcc, -1, v34
	v_cmp_gt_i32_e64 s[74:75], s11, v34
	v_mov_b32_e32 v82, v106
	v_mov_b32_e32 v83, v106
	v_mov_b64_e32 v[88:89], v[84:85]
	v_mov_b64_e32 v[92:93], v[84:85]
	s_and_b64 vcc, vcc, s[74:75]
	v_mov_b64_e32 v[86:87], v[82:83]
	v_mov_b64_e32 v[90:91], v[82:83]
	s_and_saveexec_b64 s[74:75], vcc
	s_cbranch_execz .LBB0_362
	v_lshlrev_b32_e32 v34, s10, v34
	v_add_u32_e32 v34, s12, v34
	v_mov_b32_e32 v35, v106
	v_lshl_add_u64 v[34:35], s[2:3], 0, v[34:35]
	v_mov_b64_e32 v[36:37], s[92:93]
	v_mad_u64_u32 v[36:37], vcc, v34, s8, v[36:37]
	v_mad_i32_i24 v37, v35, s8, v37
	v_lshl_add_u64 v[34:35], s[94:95], 1, v[36:37]
	v_mov_b32_e32 v159, v106
	v_lshl_add_u64 v[34:35], v[34:35], 0, v[158:159]
	global_load_dwordx4 v[90:93], v[34:35], off offset:3072
	global_load_dwordx4 v[86:89], v[34:35], off offset:3136

; __device__ __forceinline__ float bflo(unsigned w) { return __uint_as_float(w << 16); }
; __device__ __forceinline__ float bfhi(unsigned w) { return __uint_as_float(w & 0xffff0000u); }
; #define LASP __attribute__((address_space(3)))
; __device__ __forceinline__ void attn_phase_mfma(const Ctx& c, unsigned char* lds_raw, bool do_store) {
;     ...
;         const AttnU A = attn_decode(u);
;     ...
;         const int iq = i0 + 32 * wave + rq, posq = r + d * iq;
;         const size_t tokq = (size_t)b * SEQ + posq;
;         bf16_t* qrow = c.Z + tokq * DIN + ZQ + hh * 64;
;         bf16x8 qf[4];
;         {
;             const u32x4 q0 = qn[0], q1 = qn[1], q2 = qn[2], q3 = qn[3];
;             const h16x8 cav = tq[0], cbv = tq[1], sav = tq[2], sbv = tq[3];
;             const float sc = 0.125f * 1.44269504f;
;             u32x4 o0, o1, o2, o3;
;     #pragma unroll
;             for (int e = 0; e < 4; ++e) {
;                 const float ca_0 = (float)cav[2 * e], ca_1 = (float)cav[2 * e + 1], sa_0 = (float)sav[2 * e], sa_1 = (float)sav[2 * e + 1];
;                 const float cb_0 = (float)cbv[2 * e], cb_1 = (float)cbv[2 * e + 1], sb_0 = (float)sbv[2 * e], sb_1 = (float)sbv[2 * e + 1];
;                 const float a0 = bflo(q0[e]), a1 = bfhi(q0[e]), b0 = bflo(q2[e]), b1 = bfhi(q2[e]);
;                 const float e0 = bflo(q1[e]), e1 = bfhi(q1[e]), f0 = bflo(q3[e]), f1 = bfhi(q3[e]);
;                 o0[e] = pk2((a0 * ca_0 - b0 * sa_0) * sc, (a1 * ca_1 - b1 * sa_1) * sc);
;                 o2[e] = pk2((b0 * ca_0 + a0 * sa_0) * sc, (b1 * ca_1 + a1 * sa_1) * sc);
;                 o1[e] = pk2((e0 * cb_0 - f0 * sb_0) * sc, (e1 * cb_1 - f1 * sb_1) * sc);
;                 o3[e] = pk2((f0 * cb_0 + e0 * sb_0) * sc, (f1 * cb_1 + e1 * sb_1) * sc);
;             }
;             qf[0] = __builtin_bit_cast(bf16x8, o0); qf[1] = __builtin_bit_cast(bf16x8, o1); qf[2] = __builtin_bit_cast(bf16x8, o2); qf[3] = __builtin_bit_cast(bf16x8, o3);
;         }
;     ...
;         for (int s4 = 0; s4 < 4; ++s4) {
;     #pragma unroll
;             for (int kb = 0; kb < 5; ++kb) {
;                 const int row = 32 * wave + 32 * kb + rq;
;                 const bf16x8 kf = *(const LASP bf16x8*)(Kt + row * 128 + (((2 * s4 + h) ^ (row & 7)) << 4));
;                 sacc[kb] = mfma32_g(kf, qf[s4], sacc[kb]);
.LBB0_379:
	s_bfe_u32 s2, s91, 0x20004
	s_ashr_i32 s91, s90, 31
	s_lshl_b64 s[0:1], s[90:91], 12
	v_ashrrev_i32_e32 v59, 31, v58
	v_lshl_add_u64 v[108:109], s[0:1], 0, v[58:59]
	v_mov_b64_e32 v[34:35], s[92:93]
	v_cvt_f32_f16_sdwa v37, v26 dst_sel:DWORD dst_unused:UNUSED_PAD src0_sel:WORD_1
	v_cvt_f32_f16_e32 v36, v26
	v_mad_u64_u32 v[174:175], s[0:1], v108, s8, v[34:35]
	v_cvt_f32_f16_sdwa v35, v30 dst_sel:DWORD dst_unused:UNUSED_PAD src0_sel:WORD_1
	v_cvt_f32_f16_e32 v34, v30
	v_lshlrev_b32_e32 v38, 16, v10
	v_and_b32_e32 v39, 0xffff0000, v10
	v_lshlrev_b32_e32 v40, 16, v14
	v_and_b32_e32 v41, 0xffff0000, v14
	v_pk_mul_f32 v[42:43], v[40:41], v[36:37]
	v_pk_mul_f32 v[36:37], v[38:39], v[36:37]
	v_pk_fma_f32 v[42:43], v[38:39], v[34:35], v[42:43] neg_lo:[0,0,1] neg_hi:[0,0,1]
	v_pk_fma_f32 v[34:35], v[40:41], v[34:35], v[36:37]
	v_cvt_f32_f16_sdwa v37, v18 dst_sel:DWORD dst_unused:UNUSED_PAD src0_sel:WORD_1
	v_pk_mul_f32 v[34:35], v[34:35], s[72:73] op_sel_hi:[1,0]
	v_cvt_f32_f16_e32 v36, v18
	v_cvt_pk_bf16_f32 v150, v34, v35
	v_cvt_f32_f16_sdwa v35, v22 dst_sel:DWORD dst_unused:UNUSED_PAD src0_sel:WORD_1
	v_cvt_f32_f16_e32 v34, v22
	v_pk_mul_f32 v[42:43], v[42:43], s[72:73] op_sel_hi:[1,0]
	v_lshlrev_b32_e32 v38, 16, v2
	v_and_b32_e32 v39, 0xffff0000, v2
	v_lshlrev_b32_e32 v40, 16, v6
	v_and_b32_e32 v41, 0xffff0000, v6
	v_cvt_pk_bf16_f32 v224, v42, v43
	v_pk_mul_f32 v[42:43], v[40:41], v[36:37]
	v_pk_mul_f32 v[36:37], v[38:39], v[36:37]
	v_pk_fma_f32 v[42:43], v[38:39], v[34:35], v[42:43] neg_lo:[0,0,1] neg_hi:[0,0,1]
	v_pk_fma_f32 v[34:35], v[40:41], v[34:35], v[36:37]
	v_cvt_f32_f16_e32 v30, v27
	v_pk_mul_f32 v[34:35], v[34:35], s[72:73] op_sel_hi:[1,0]
	v_lshlrev_b32_e32 v14, 16, v15
	v_cvt_pk_bf16_f32 v154, v34, v35
	v_cvt_f32_f16_sdwa v35, v31 dst_sel:DWORD dst_unused:UNUSED_PAD src0_sel:WORD_1
	v_cvt_f32_f16_e32 v34, v31
	v_cvt_f32_f16_sdwa v31, v27 dst_sel:DWORD dst_unused:UNUSED_PAD src0_sel:WORD_1
	v_and_b32_e32 v15, 0xffff0000, v15
	v_lshlrev_b32_e32 v10, 16, v11
	v_and_b32_e32 v11, 0xffff0000, v11
	v_pk_mul_f32 v[26:27], v[14:15], v[30:31]
	v_lshlrev_b32_e32 v6, 16, v7
	v_pk_fma_f32 v[26:27], v[10:11], v[34:35], v[26:27] neg_lo:[0,0,1] neg_hi:[0,0,1]
	v_pk_mul_f32 v[10:11], v[10:11], v[30:31]
	v_and_b32_e32 v7, 0xffff0000, v7
	v_pk_fma_f32 v[10:11], v[14:15], v[34:35], v[10:11]
	v_cvt_f32_f16_sdwa v15, v19 dst_sel:DWORD dst_unused:UNUSED_PAD src0_sel:WORD_1
	v_pk_mul_f32 v[10:11], v[10:11], s[72:73] op_sel_hi:[1,0]
	v_cvt_f32_f16_e32 v14, v19
	v_cvt_pk_bf16_f32 v151, v10, v11
	v_cvt_f32_f16_sdwa v11, v23 dst_sel:DWORD dst_unused:UNUSED_PAD src0_sel:WORD_1
	v_cvt_f32_f16_e32 v10, v23
	v_lshlrev_b32_e32 v2, 16, v3
	v_and_b32_e32 v3, 0xffff0000, v3
	v_pk_mul_f32 v[18:19], v[6:7], v[14:15]
	v_pk_mul_f32 v[26:27], v[26:27], s[72:73] op_sel_hi:[1,0]
	v_pk_fma_f32 v[18:19], v[2:3], v[10:11], v[18:19] neg_lo:[0,0,1] neg_hi:[0,0,1]
	v_pk_mul_f32 v[2:3], v[2:3], v[14:15]
	v_pk_mul_f32 v[18:19], v[18:19], s[72:73] op_sel_hi:[1,0]
	v_pk_fma_f32 v[2:3], v[6:7], v[10:11], v[2:3]
	v_cvt_f32_f16_sdwa v7, v28 dst_sel:DWORD dst_unused:UNUSED_PAD src0_sel:WORD_1
	v_pk_mul_f32 v[2:3], v[2:3], s[72:73] op_sel_hi:[1,0]
	v_cvt_f32_f16_e32 v6, v28
	v_cvt_pk_bf16_f32 v155, v2, v3
	v_cvt_f32_f16_sdwa v3, v32 dst_sel:DWORD dst_unused:UNUSED_PAD src0_sel:WORD_1
	v_cvt_f32_f16_e32 v2, v32
	v_lshlrev_b32_e32 v14, 16, v16
	v_and_b32_e32 v15, 0xffff0000, v16
	v_cvt_pk_bf16_f32 v229, v18, v19
	v_lshlrev_b32_e32 v10, 16, v12
	v_and_b32_e32 v11, 0xffff0000, v12
	v_pk_mul_f32 v[18:19], v[14:15], v[6:7]
	v_cvt_pk_bf16_f32 v225, v26, v27
	v_pk_fma_f32 v[18:19], v[10:11], v[2:3], v[18:19] neg_lo:[0,0,1] neg_hi:[0,0,1]
	v_cvt_f32_f16_sdwa v23, v29 dst_sel:DWORD dst_unused:UNUSED_PAD src0_sel:WORD_1
	v_cvt_f32_f16_e32 v22, v29
	ds_read_b128 v[26:29], v216
	v_pk_mul_f32 v[18:19], v[18:19], s[72:73] op_sel_hi:[1,0]
	v_lshlrev_b32_e32 v16, 16, v17
	v_cvt_pk_bf16_f32 v226, v18, v19
	v_cvt_f32_f16_sdwa v19, v33 dst_sel:DWORD dst_unused:UNUSED_PAD src0_sel:WORD_1
	v_cvt_f32_f16_e32 v18, v33
	v_and_b32_e32 v17, 0xffff0000, v17
	v_pk_mul_f32 v[6:7], v[10:11], v[6:7]
	v_lshlrev_b32_e32 v30, 16, v13
	v_and_b32_e32 v31, 0xffff0000, v13
	v_pk_mul_f32 v[10:11], v[16:17], v[22:23]
	v_pk_fma_f32 v[2:3], v[14:15], v[2:3], v[6:7]
	v_pk_fma_f32 v[10:11], v[30:31], v[18:19], v[10:11] neg_lo:[0,0,1] neg_hi:[0,0,1]
	v_pk_mul_f32 v[42:43], v[42:43], s[72:73] op_sel_hi:[1,0]
	v_pk_mul_f32 v[10:11], v[10:11], s[72:73] op_sel_hi:[1,0]
	v_pk_mul_f32 v[2:3], v[2:3], s[72:73] op_sel_hi:[1,0]
	v_cvt_pk_bf16_f32 v227, v10, v11
	v_cvt_f32_f16_sdwa v7, v20 dst_sel:DWORD dst_unused:UNUSED_PAD src0_sel:WORD_1
	v_cvt_f32_f16_e32 v6, v20
	s_waitcnt lgkmcnt(0)
	v_mfma_f32_32x32x16_bf16 v[66:81], v[26:29], v[224:227], 0
	ds_read_b128 v[10:13], v216 offset:4096
	v_cvt_pk_bf16_f32 v228, v42, v43
	v_cvt_pk_bf16_f32 v152, v2, v3
	v_cvt_f32_f16_sdwa v3, v24 dst_sel:DWORD dst_unused:UNUSED_PAD src0_sel:WORD_1
	v_cvt_f32_f16_e32 v2, v24
	v_lshlrev_b32_e32 v14, 16, v4
	s_waitcnt lgkmcnt(0)
	v_mfma_f32_32x32x16_bf16 v[50:65], v[10:13], v[224:227], 0
	ds_read_b128 v[10:13], v216 offset:8192
	v_and_b32_e32 v15, 0xffff0000, v4
	v_lshlrev_b32_e32 v26, 16, v8
	v_and_b32_e32 v27, 0xffff0000, v8
	v_pk_mul_f32 v[28:29], v[26:27], v[6:7]
	v_pk_mul_f32 v[6:7], v[14:15], v[6:7]
	s_waitcnt lgkmcnt(0)
; #define LASP __attribute__((address_space(3)))
; __device__ __forceinline__ void attn_phase_mfma(const Ctx& c, unsigned char* lds_raw, bool do_store) {
;     ...
;         for (int s4 = 0; s4 < 4; ++s4) {
;     #pragma unroll
;             for (int kb = 0; kb < 5; ++kb) {
;                 const int row = 32 * wave + 32 * kb + rq;
;                 const bf16x8 kf = *(const LASP bf16x8*)(Kt + row * 128 + (((2 * s4 + h) ^ (row & 7)) << 4));
;                 sacc[kb] = mfma32_g(kf, qf[s4], sacc[kb]);
;             }
;             __builtin_amdgcn_sched_barrier(0);
;         }
;         asm volatile("s_nop 15\n\ts_nop 15" : "+v"(sacc[0]), "+v"(sacc[1]), "+v"(sacc[2]), "+v"(sacc[3]), "+v"(sacc[4]));
;         const int jbase = i0 - 64 + 32 * wave;
;         float mx = -1e30f;
;     #pragma unroll
;         for (int kb = 0; kb < 5; ++kb)
;     #pragma unroll
;             for (int e = 0; e < 16; ++e) {
;                 const int row = (e & 3) + 8 * (e >> 2) + 4 * h, rel = 32 * kb + row - rq, j = jbase + 32 * kb + row;
;                 const bool valid = (rel >= 0) && (rel <= 128) && (j >= 0) && (j < L);
;                 const float sv = valid ? sacc[kb][e] : -1e30f;
;                 sacc[kb][e] = sv; mx = fmaxf(mx, sv);
;             }
	v_mfma_f32_32x32x16_bf16 v[34:49], v[10:13], v[224:227], 0
	ds_read_b128 v[10:13], v216 offset:12288
	v_pk_fma_f32 v[28:29], v[14:15], v[2:3], v[28:29] neg_lo:[0,0,1] neg_hi:[0,0,1]
	v_pk_fma_f32 v[2:3], v[26:27], v[2:3], v[6:7]
	v_pk_mul_f32 v[28:29], v[28:29], s[72:73] op_sel_hi:[1,0]
	v_pk_mul_f32 v[2:3], v[2:3], s[72:73] op_sel_hi:[1,0]
	v_cvt_pk_bf16_f32 v230, v28, v29
	v_cvt_pk_bf16_f32 v156, v2, v3
	v_pk_mul_f32 v[2:3], v[30:31], v[22:23]
	v_cvt_f32_f16_sdwa v7, v21 dst_sel:DWORD dst_unused:UNUSED_PAD src0_sel:WORD_1
	v_pk_fma_f32 v[2:3], v[16:17], v[18:19], v[2:3]
	v_cvt_f32_f16_e32 v6, v21
	v_pk_mul_f32 v[2:3], v[2:3], s[72:73] op_sel_hi:[1,0]
	v_lshlrev_b32_e32 v8, 16, v9
	v_cvt_pk_bf16_f32 v153, v2, v3
	v_cvt_f32_f16_sdwa v3, v25 dst_sel:DWORD dst_unused:UNUSED_PAD src0_sel:WORD_1
	v_cvt_f32_f16_e32 v2, v25
	s_waitcnt lgkmcnt(0)
	v_mfma_f32_32x32x16_bf16 v[18:33], v[10:13], v[224:227], 0
	ds_read_b128 v[232:235], v216 offset:16384
	v_and_b32_e32 v9, 0xffff0000, v9
	v_lshlrev_b32_e32 v4, 16, v5
	v_and_b32_e32 v5, 0xffff0000, v5
	v_pk_mul_f32 v[14:15], v[8:9], v[6:7]
	s_lshl_b32 s0, s88, 8
	s_lshl_b32 s1, s2, 6
	v_pk_fma_f32 v[14:15], v[4:5], v[2:3], v[14:15] neg_lo:[0,0,1] neg_hi:[0,0,1]
	v_pk_mul_f32 v[4:5], v[4:5], v[6:7]
	s_or_b32 s0, s1, s0
	v_pk_fma_f32 v[2:3], v[8:9], v[2:3], v[4:5]
	v_mad_i32_i24 v175, v109, s8, v175
	s_ashr_i32 s1, s0, 31
	v_pk_mul_f32 v[10:11], v[14:15], s[72:73] op_sel_hi:[1,0]
	v_pk_mul_f32 v[2:3], v[2:3], s[72:73] op_sel_hi:[1,0]
	v_cvt_pk_bf16_f32 v231, v10, v11
	v_cvt_pk_bf16_f32 v157, v2, v3
	s_lshr_b32 s3, 0x1000, s96
	v_lshl_add_u64 v[174:175], s[0:1], 1, v[174:175]
	s_waitcnt lgkmcnt(0)
	v_mfma_f32_32x32x16_bf16 v[2:17], v[232:235], v[224:227], 0
	ds_read_b128 v[224:227], v217
	ds_read_b128 v[250:253], v217 offset:4096
	s_waitcnt lgkmcnt(1)
	v_mfma_f32_32x32x16_bf16 v[66:81], v[224:227], v[228:231], v[66:81]
	ds_read_b128 v[224:227], v217 offset:8192
	s_waitcnt lgkmcnt(1)
	v_mfma_f32_32x32x16_bf16 v[50:65], v[250:253], v[228:231], v[50:65]
	ds_read_b128 v[250:253], v217 offset:12288
	s_waitcnt lgkmcnt(1)
	v_mfma_f32_32x32x16_bf16 v[34:49], v[224:227], v[228:231], v[34:49]
	ds_read_b128 v[224:227], v217 offset:16384
	s_waitcnt lgkmcnt(1)
	v_mfma_f32_32x32x16_bf16 v[18:33], v[250:253], v[228:231], v[18:33]
	s_waitcnt lgkmcnt(0)
	v_mfma_f32_32x32x16_bf16 v[2:17], v[224:227], v[228:231], v[2:17]
	ds_read_b128 v[224:227], v218
	ds_read_b128 v[250:253], v218 offset:4096
	s_waitcnt lgkmcnt(1)
	v_mfma_f32_32x32x16_bf16 v[66:81], v[224:227], v[150:153], v[66:81]
	ds_read_b128 v[224:227], v218 offset:8192
	s_waitcnt lgkmcnt(1)
	v_mfma_f32_32x32x16_bf16 v[50:65], v[250:253], v[150:153], v[50:65]
	ds_read_b128 v[250:253], v218 offset:12288
	s_waitcnt lgkmcnt(1)
	v_mfma_f32_32x32x16_bf16 v[34:49], v[224:227], v[150:153], v[34:49]
	ds_read_b128 v[224:227], v218 offset:16384
	s_waitcnt lgkmcnt(1)
	v_mfma_f32_32x32x16_bf16 v[18:33], v[250:253], v[150:153], v[18:33]
	s_waitcnt lgkmcnt(0)
	v_mfma_f32_32x32x16_bf16 v[2:17], v[224:227], v[150:153], v[2:17]
	ds_read_b128 v[150:153], v219
	ds_read_b128 v[250:253], v219 offset:4096
	s_waitcnt lgkmcnt(1)
	v_mfma_f32_32x32x16_bf16 v[66:81], v[150:153], v[154:157], v[66:81]
	ds_read_b128 v[150:153], v219 offset:8192
	s_waitcnt lgkmcnt(1)
	v_mfma_f32_32x32x16_bf16 v[50:65], v[250:253], v[154:157], v[50:65]
	ds_read_b128 v[250:253], v219 offset:12288
	s_waitcnt lgkmcnt(1)
	v_mfma_f32_32x32x16_bf16 v[34:49], v[150:153], v[154:157], v[34:49]
	ds_read_b128 v[150:153], v219 offset:16384
	s_waitcnt lgkmcnt(1)
	v_mfma_f32_32x32x16_bf16 v[18:33], v[250:253], v[154:157], v[18:33]
	s_waitcnt lgkmcnt(0)
	v_mfma_f32_32x32x16_bf16 v[2:17], v[150:153], v[154:157], v[2:17]
	s_add_i32 s0, s89, s73
	s_cmp_gt_i32 s0, -1
	v_readlane_b32 s12, v255, 17
	s_cselect_b64 s[10:11], -1, 0
	v_or_b32_e32 v107, s0, v166
	v_readlane_b32 s13, v255, 18
	s_and_b64 s[12:13], s[12:13], s[10:11]
	v_cmp_gt_i32_e32 vcc, s3, v107
	s_nop 15
	s_nop 15
	s_and_b64 vcc, s[12:13], vcc
	v_readlane_b32 s12, v255, 19
	v_cndmask_b32_e32 v107, v222, v66, vcc
	v_or_b32_e32 v66, s0, v184
	v_readlane_b32 s13, v255, 20
	s_and_b64 s[12:13], s[12:13], s[10:11]
	v_cmp_gt_i32_e32 vcc, s3, v66
	s_and_b64 vcc, s[12:13], vcc
	v_readlane_b32 s12, v255, 21
	v_or_b32_e32 v150, s0, v185
	v_readlane_b32 s13, v255, 22
	v_cndmask_b32_e32 v67, v222, v67, vcc
	s_and_b64 s[12:13], s[12:13], s[10:11]
	v_cmp_gt_i32_e32 vcc, s3, v150
	s_and_b64 vcc, s[12:13], vcc
	v_readlane_b32 s12, v255, 23
	v_or_b32_e32 v150, s0, v186
	v_readlane_b32 s13, v255, 24
	v_cndmask_b32_e32 v68, v222, v68, vcc
	s_and_b64 s[12:13], s[12:13], s[10:11]
	v_cmp_gt_i32_e32 vcc, s3, v150
	s_and_b64 vcc, s[12:13], vcc
	v_or_b32_e32 v150, s0, v187
	v_cndmask_b32_e32 v69, v222, v69, vcc
	s_and_b64 s[12:13], s[14:15], s[10:11]
	v_cmp_gt_i32_e32 vcc, s3, v150
	s_and_b64 vcc, s[12:13], vcc
	v_or_b32_e32 v150, s0, v188
	v_cndmask_b32_e32 v70, v222, v70, vcc
	s_and_b64 s[12:13], s[16:17], s[10:11]
	v_cmp_gt_i32_e32 vcc, s3, v150
	s_and_b64 vcc, s[12:13], vcc
	v_or_b32_e32 v150, s0, v189
	v_cndmask_b32_e32 v71, v222, v71, vcc
	s_and_b64 s[12:13], s[18:19], s[10:11]
	v_cmp_gt_i32_e32 vcc, s3, v150
	s_and_b64 vcc, s[12:13], vcc
	v_or_b32_e32 v150, s0, v190
	v_cndmask_b32_e32 v72, v222, v72, vcc
	s_and_b64 s[12:13], s[20:21], s[10:11]
	v_cmp_gt_i32_e32 vcc, s3, v150
	s_and_b64 vcc, s[12:13], vcc
	v_or_b32_e32 v150, s0, v191
	v_cndmask_b32_e32 v73, v222, v73, vcc
	s_and_b64 s[12:13], s[22:23], s[10:11]
	v_cmp_gt_i32_e32 vcc, s3, v150
	s_and_b64 vcc, s[12:13], vcc
	v_or_b32_e32 v150, s0, v192
	v_cndmask_b32_e32 v74, v222, v74, vcc
	s_and_b64 s[12:13], s[24:25], s[10:11]
; __device__ __forceinline__ void attn_phase_mfma(const Ctx& c, unsigned char* lds_raw, bool do_store) {
;     ...
;         const int jbase = i0 - 64 + 32 * wave;
;         float mx = -1e30f;
;     #pragma unroll
;         for (int kb = 0; kb < 5; ++kb)
;     #pragma unroll
;             for (int e = 0; e < 16; ++e) {
;                 const int row = (e & 3) + 8 * (e >> 2) + 4 * h, rel = 32 * kb + row - rq, j = jbase + 32 * kb + row;
;                 const bool valid = (rel >= 0) && (rel <= 128) && (j >= 0) && (j < L);
;                 const float sv = valid ? sacc[kb][e] : -1e30f;
;                 sacc[kb][e] = sv; mx = fmaxf(mx, sv);
;             }
	v_cmp_gt_i32_e32 vcc, s3, v150
	s_and_b64 vcc, s[12:13], vcc
	v_or_b32_e32 v150, s0, v193
	v_cndmask_b32_e32 v75, v222, v75, vcc
	s_and_b64 s[12:13], s[26:27], s[10:11]
	v_cmp_gt_i32_e32 vcc, s3, v150
	s_and_b64 vcc, s[12:13], vcc
	v_or_b32_e32 v150, s0, v194
	v_cndmask_b32_e32 v76, v222, v76, vcc
	s_and_b64 s[12:13], s[28:29], s[10:11]
	v_cmp_gt_i32_e32 vcc, s3, v150
	s_and_b64 vcc, s[12:13], vcc
	v_or_b32_e32 v150, s0, v195
	v_cndmask_b32_e32 v77, v222, v77, vcc
	s_and_b64 s[12:13], s[30:31], s[10:11]
	v_cmp_gt_i32_e32 vcc, s3, v150
	s_and_b64 vcc, s[12:13], vcc
	v_or_b32_e32 v150, s0, v196
	v_cndmask_b32_e32 v78, v222, v78, vcc
	s_and_b64 s[12:13], s[34:35], s[10:11]
	v_cmp_gt_i32_e32 vcc, s3, v150
	s_and_b64 vcc, s[12:13], vcc
	v_or_b32_e32 v150, s0, v197
	v_cndmask_b32_e32 v79, v222, v79, vcc
	s_and_b64 s[12:13], s[36:37], s[10:11]
	v_cmp_gt_i32_e32 vcc, s3, v150
	s_and_b64 vcc, s[12:13], vcc
	v_or_b32_e32 v150, s0, v198
	s_mov_b32 s1, 0xf149f2ca
	v_cndmask_b32_e32 v80, v222, v80, vcc
	s_and_b64 s[10:11], s[38:39], s[10:11]
	v_cmp_gt_i32_e32 vcc, s3, v150
	v_max3_f32 v66, v107, s1, v67
	s_and_b64 vcc, s[10:11], vcc
	s_add_i32 s1, s0, 32
	s_cmpk_gt_i32 s0, 0xffdf
	v_or_b32_e32 v150, s1, v166
	v_cndmask_b32_e32 v81, v222, v81, vcc
	s_cselect_b64 s[10:11], -1, 0
	v_cmp_gt_i32_e32 vcc, s3, v150
	s_and_b64 vcc, s[10:11], vcc
	s_add_i32 s9, s9, s73
	v_cndmask_b32_e32 v150, v222, v50, vcc
	v_or_b32_e32 v50, s1, v184
	v_cmp_gt_i32_e32 vcc, s3, v50
	s_and_b64 vcc, s[10:11], vcc
	v_max3_f32 v66, v66, v68, v69
	v_cndmask_b32_e32 v151, v222, v51, vcc
	v_or_b32_e32 v51, s1, v185
	v_cmp_gt_i32_e32 vcc, s3, v51
	s_and_b64 vcc, s[10:11], vcc
	v_or_b32_e32 v51, s1, v186
	v_cndmask_b32_e32 v152, v222, v52, vcc
	v_cmp_gt_i32_e32 vcc, s3, v51
	s_and_b64 vcc, s[10:11], vcc
	v_or_b32_e32 v51, s1, v187
	v_cndmask_b32_e32 v153, v222, v53, vcc
	v_cmp_gt_i32_e32 vcc, s3, v51
	s_and_b64 vcc, s[10:11], vcc
	v_or_b32_e32 v51, s1, v188
	v_cndmask_b32_e32 v154, v222, v54, vcc
	v_cmp_gt_i32_e32 vcc, s3, v51
	s_and_b64 vcc, s[10:11], vcc
	v_or_b32_e32 v51, s1, v189
	v_cndmask_b32_e32 v155, v222, v55, vcc
	v_cmp_gt_i32_e32 vcc, s3, v51
	s_and_b64 vcc, s[10:11], vcc
	v_or_b32_e32 v51, s1, v190
	v_cndmask_b32_e32 v156, v222, v56, vcc
	v_cmp_gt_i32_e32 vcc, s3, v51
	s_and_b64 vcc, s[10:11], vcc
	v_or_b32_e32 v51, s1, v191
	v_cndmask_b32_e32 v157, v222, v57, vcc
	v_cmp_gt_i32_e32 vcc, s3, v51
	s_and_b64 vcc, s[10:11], vcc
	v_or_b32_e32 v51, s1, v192
	v_cndmask_b32_e32 v159, v222, v58, vcc
	v_cmp_gt_i32_e32 vcc, s3, v51
	s_and_b64 vcc, s[10:11], vcc
	v_or_b32_e32 v51, s1, v193
	v_cndmask_b32_e32 v169, v222, v59, vcc
	v_cmp_gt_i32_e32 vcc, s3, v51
	s_and_b64 vcc, s[10:11], vcc
	v_or_b32_e32 v51, s1, v194
	v_cndmask_b32_e32 v224, v222, v60, vcc
	v_cmp_gt_i32_e32 vcc, s3, v51
	s_and_b64 vcc, s[10:11], vcc
	v_or_b32_e32 v51, s1, v195
	v_cndmask_b32_e32 v225, v222, v61, vcc
	v_cmp_gt_i32_e32 vcc, s3, v51
	s_and_b64 vcc, s[10:11], vcc
	v_or_b32_e32 v51, s1, v196
	v_cndmask_b32_e32 v226, v222, v62, vcc
	v_cmp_gt_i32_e32 vcc, s3, v51
	s_and_b64 vcc, s[10:11], vcc
	v_or_b32_e32 v51, s1, v197
	v_cndmask_b32_e32 v227, v222, v63, vcc
	v_cmp_gt_i32_e32 vcc, s3, v51
	s_and_b64 vcc, s[10:11], vcc
	v_or_b32_e32 v51, s1, v198
	v_cndmask_b32_e32 v228, v222, v64, vcc
	v_cmp_gt_i32_e32 vcc, s3, v51
	s_and_b64 vcc, s[10:11], vcc
	s_cmp_gt_i32 s9, -1
	v_or_b32_e32 v51, s9, v166
	v_cndmask_b32_e32 v229, v222, v65, vcc
	s_cselect_b64 s[10:11], -1, 0
	v_cmp_gt_i32_e32 vcc, s3, v51
	s_and_b64 vcc, s[10:11], vcc
	s_add_i32 s1, s0, 0x60
	v_cndmask_b32_e32 v230, v222, v34, vcc
	v_or_b32_e32 v34, s9, v184
	v_cmp_gt_i32_e32 vcc, s3, v34
	s_and_b64 vcc, s[10:11], vcc
	v_max3_f32 v66, v66, v70, v71
	v_cndmask_b32_e32 v231, v222, v35, vcc
	v_or_b32_e32 v35, s9, v185
	v_cmp_gt_i32_e32 vcc, s3, v35
	s_and_b64 vcc, s[10:11], vcc
	v_or_b32_e32 v35, s9, v186
	v_cndmask_b32_e32 v232, v222, v36, vcc
	v_cmp_gt_i32_e32 vcc, s3, v35
	s_and_b64 vcc, s[10:11], vcc
	v_or_b32_e32 v35, s9, v187
	v_cndmask_b32_e32 v233, v222, v37, vcc
	v_cmp_gt_i32_e32 vcc, s3, v35
	s_and_b64 vcc, s[10:11], vcc
	v_or_b32_e32 v35, s9, v188
	v_cndmask_b32_e32 v234, v222, v38, vcc
	v_cmp_gt_i32_e32 vcc, s3, v35
	s_and_b64 vcc, s[10:11], vcc
	v_or_b32_e32 v35, s9, v189
	v_cndmask_b32_e32 v235, v222, v39, vcc
	v_cmp_gt_i32_e32 vcc, s3, v35
	s_and_b64 vcc, s[10:11], vcc
	v_or_b32_e32 v35, s9, v190
	v_cndmask_b32_e32 v236, v222, v40, vcc
	v_cmp_gt_i32_e32 vcc, s3, v35
	s_and_b64 vcc, s[10:11], vcc
	v_or_b32_e32 v35, s9, v191
	v_cndmask_b32_e32 v237, v222, v41, vcc
	v_cmp_gt_i32_e32 vcc, s3, v35
	s_and_b64 vcc, s[10:11], vcc
	v_or_b32_e32 v35, s9, v192
	v_cndmask_b32_e32 v238, v222, v42, vcc
	v_cmp_gt_i32_e32 vcc, s3, v35
	s_and_b64 vcc, s[10:11], vcc
	v_or_b32_e32 v35, s9, v193
	v_cndmask_b32_e32 v239, v222, v43, vcc
	v_cmp_gt_i32_e32 vcc, s3, v35
	s_and_b64 vcc, s[10:11], vcc
	v_or_b32_e32 v35, s9, v194
	v_cndmask_b32_e32 v240, v222, v44, vcc
	v_cmp_gt_i32_e32 vcc, s3, v35
	s_and_b64 vcc, s[10:11], vcc
	v_or_b32_e32 v35, s9, v195
	v_cndmask_b32_e32 v241, v222, v45, vcc
	v_cmp_gt_i32_e32 vcc, s3, v35
	s_and_b64 vcc, s[10:11], vcc
	v_or_b32_e32 v35, s9, v196
	v_cndmask_b32_e32 v242, v222, v46, vcc
	v_cmp_gt_i32_e32 vcc, s3, v35
	s_and_b64 vcc, s[10:11], vcc
	v_or_b32_e32 v35, s9, v197
	v_cndmask_b32_e32 v243, v222, v47, vcc
	v_cmp_gt_i32_e32 vcc, s3, v35
	s_and_b64 vcc, s[10:11], vcc
	v_or_b32_e32 v35, s9, v198
	v_cndmask_b32_e32 v244, v222, v48, vcc
	v_cmp_gt_i32_e32 vcc, s3, v35
	s_and_b64 vcc, s[10:11], vcc
	s_cmpk_gt_i32 s0, 0xff9f
	v_or_b32_e32 v35, s1, v166
	v_cndmask_b32_e32 v245, v222, v49, vcc
	s_cselect_b64 s[10:11], -1, 0
; __device__ __forceinline__ void attn_phase_mfma(const Ctx& c, unsigned char* lds_raw, bool do_store) {
;     ...
;         const int jbase = i0 - 64 + 32 * wave;
;         float mx = -1e30f;
;     #pragma unroll
;         for (int kb = 0; kb < 5; ++kb)
;     #pragma unroll
;             for (int e = 0; e < 16; ++e) {
;                 const int row = (e & 3) + 8 * (e >> 2) + 4 * h, rel = 32 * kb + row - rq, j = jbase + 32 * kb + row;
;                 const bool valid = (rel >= 0) && (rel <= 128) && (j >= 0) && (j < L);
;                 const float sv = valid ? sacc[kb][e] : -1e30f;
;                 sacc[kb][e] = sv; mx = fmaxf(mx, sv);
;             }
;         mx = fmaxf(mx, __shfl_xor(mx, 32));
	v_cmp_gt_i32_e32 vcc, s3, v35
	s_and_b64 vcc, s[10:11], vcc
	v_max3_f32 v66, v66, v72, v73
	v_cndmask_b32_e32 v246, v222, v18, vcc
	v_or_b32_e32 v18, s1, v184
	v_cmp_gt_i32_e32 vcc, s3, v18
	v_max3_f32 v66, v66, v74, v75
	s_and_b64 vcc, s[10:11], vcc
	v_max3_f32 v66, v66, v76, v77
	v_cndmask_b32_e32 v65, v222, v19, vcc
	v_or_b32_e32 v19, s1, v185
	v_max3_f32 v66, v66, v78, v79
	v_cmp_gt_i32_e32 vcc, s3, v19
	v_max3_f32 v66, v66, v80, v81
	s_and_b64 vcc, s[10:11], vcc
	v_or_b32_e32 v19, s1, v186
	v_max3_f32 v50, v66, v150, v151
	v_cndmask_b32_e32 v66, v222, v20, vcc
	v_cmp_gt_i32_e32 vcc, s3, v19
	s_and_b64 vcc, s[10:11], vcc
	v_or_b32_e32 v19, s1, v187
	v_cndmask_b32_e32 v63, v222, v21, vcc
	v_cmp_gt_i32_e32 vcc, s3, v19
	s_and_b64 vcc, s[10:11], vcc
	v_or_b32_e32 v19, s1, v188
	v_cndmask_b32_e32 v64, v222, v22, vcc
	v_cmp_gt_i32_e32 vcc, s3, v19
	s_and_b64 vcc, s[10:11], vcc
	v_or_b32_e32 v19, s1, v189
	v_cndmask_b32_e32 v61, v222, v23, vcc
	v_cmp_gt_i32_e32 vcc, s3, v19
	s_and_b64 vcc, s[10:11], vcc
	v_or_b32_e32 v19, s1, v190
	v_cndmask_b32_e32 v62, v222, v24, vcc
	v_cmp_gt_i32_e32 vcc, s3, v19
	s_and_b64 vcc, s[10:11], vcc
	v_or_b32_e32 v19, s1, v191
	v_cndmask_b32_e32 v59, v222, v25, vcc
	v_cmp_gt_i32_e32 vcc, s3, v19
	s_and_b64 vcc, s[10:11], vcc
	v_or_b32_e32 v19, s1, v192
	v_cndmask_b32_e32 v60, v222, v26, vcc
	v_cmp_gt_i32_e32 vcc, s3, v19
	s_and_b64 vcc, s[10:11], vcc
	v_or_b32_e32 v19, s1, v193
	v_cndmask_b32_e32 v57, v222, v27, vcc
	v_cmp_gt_i32_e32 vcc, s3, v19
	s_and_b64 vcc, s[10:11], vcc
	v_or_b32_e32 v19, s1, v194
	v_cndmask_b32_e32 v58, v222, v28, vcc
	v_cmp_gt_i32_e32 vcc, s3, v19
	s_and_b64 vcc, s[10:11], vcc
	v_or_b32_e32 v19, s1, v195
	v_cndmask_b32_e32 v55, v222, v29, vcc
	v_cmp_gt_i32_e32 vcc, s3, v19
	s_and_b64 vcc, s[10:11], vcc
	v_or_b32_e32 v19, s1, v196
	v_cndmask_b32_e32 v56, v222, v30, vcc
	v_cmp_gt_i32_e32 vcc, s3, v19
	s_and_b64 vcc, s[10:11], vcc
	v_or_b32_e32 v19, s1, v197
	v_cndmask_b32_e32 v53, v222, v31, vcc
	v_cmp_gt_i32_e32 vcc, s3, v19
	s_and_b64 vcc, s[10:11], vcc
	v_or_b32_e32 v19, s1, v198
	v_cndmask_b32_e32 v54, v222, v32, vcc
	v_cmp_gt_i32_e32 vcc, s3, v19
	s_and_b64 vcc, s[10:11], vcc
	s_add_i32 s9, s0, 0x80
	s_cmpk_gt_i32 s0, 0xff7f
	s_cselect_b64 s[0:1], -1, 0
	v_or_b32_e32 v19, s9, v166
	v_cndmask_b32_e32 v51, v222, v33, vcc
	s_and_b64 s[10:11], s[40:41], s[0:1]
	v_cmp_gt_i32_e32 vcc, s3, v19
	v_max3_f32 v50, v50, v152, v153
	s_and_b64 vcc, s[10:11], vcc
	v_max3_f32 v50, v50, v154, v155
	v_cndmask_b32_e32 v52, v222, v2, vcc
	v_or_b32_e32 v2, s9, v184
	v_max3_f32 v50, v50, v156, v157
	s_and_b64 s[10:11], s[42:43], s[0:1]
	v_cmp_gt_i32_e32 vcc, s3, v2
	v_max3_f32 v50, v50, v159, v169
	s_and_b64 vcc, s[10:11], vcc
	v_max3_f32 v50, v50, v224, v225
	v_cndmask_b32_e32 v49, v222, v3, vcc
	v_or_b32_e32 v3, s9, v185
	v_max3_f32 v50, v50, v226, v227
	s_and_b64 s[10:11], s[44:45], s[0:1]
	v_cmp_gt_i32_e32 vcc, s3, v3
	v_max3_f32 v50, v50, v228, v229
	s_and_b64 vcc, s[10:11], vcc
	v_or_b32_e32 v3, s9, v186
	v_max3_f32 v34, v50, v230, v231
	v_cndmask_b32_e32 v50, v222, v4, vcc
	s_and_b64 s[10:11], s[46:47], s[0:1]
	v_cmp_gt_i32_e32 vcc, s3, v3
	s_and_b64 vcc, s[10:11], vcc
	v_or_b32_e32 v3, s9, v187
	v_cndmask_b32_e32 v47, v222, v5, vcc
	s_and_b64 s[10:11], s[48:49], s[0:1]
	v_cmp_gt_i32_e32 vcc, s3, v3
	s_and_b64 vcc, s[10:11], vcc
	v_or_b32_e32 v3, s9, v188
	v_cndmask_b32_e32 v48, v222, v6, vcc
	s_and_b64 s[10:11], s[50:51], s[0:1]
	v_cmp_gt_i32_e32 vcc, s3, v3
	s_and_b64 vcc, s[10:11], vcc
	v_or_b32_e32 v3, s9, v189
	v_max3_f32 v34, v34, v232, v233
	v_cndmask_b32_e32 v45, v222, v7, vcc
	s_and_b64 s[10:11], s[52:53], s[0:1]
	v_cmp_gt_i32_e32 vcc, s3, v3
	v_max3_f32 v34, v34, v234, v235
	s_and_b64 vcc, s[10:11], vcc
	v_or_b32_e32 v3, s9, v190
	v_max3_f32 v34, v34, v236, v237
	v_cndmask_b32_e32 v46, v222, v8, vcc
	s_and_b64 s[10:11], s[54:55], s[0:1]
	v_cmp_gt_i32_e32 vcc, s3, v3
	v_max3_f32 v34, v34, v238, v239
	s_and_b64 vcc, s[10:11], vcc
	v_or_b32_e32 v3, s9, v191
	v_max3_f32 v34, v34, v240, v241
	v_cndmask_b32_e32 v43, v222, v9, vcc
	s_and_b64 s[10:11], s[56:57], s[0:1]
	v_cmp_gt_i32_e32 vcc, s3, v3
	v_max3_f32 v34, v34, v242, v243
	s_and_b64 vcc, s[10:11], vcc
	v_or_b32_e32 v3, s9, v192
	v_max3_f32 v34, v34, v244, v245
	v_cndmask_b32_e32 v44, v222, v10, vcc
	s_and_b64 s[10:11], s[58:59], s[0:1]
	v_cmp_gt_i32_e32 vcc, s3, v3
	v_max3_f32 v18, v34, v246, v65
	s_and_b64 vcc, s[10:11], vcc
	v_or_b32_e32 v3, s9, v193
	v_max3_f32 v18, v18, v66, v63
	v_cndmask_b32_e32 v41, v222, v11, vcc
	s_and_b64 s[10:11], s[60:61], s[0:1]
	v_cmp_gt_i32_e32 vcc, s3, v3
	v_max3_f32 v18, v18, v64, v61
	s_and_b64 vcc, s[10:11], vcc
	v_or_b32_e32 v3, s9, v194
	v_max3_f32 v18, v18, v62, v59
	v_cndmask_b32_e32 v42, v222, v12, vcc
	s_and_b64 s[10:11], s[62:63], s[0:1]
	v_cmp_gt_i32_e32 vcc, s3, v3
	v_max3_f32 v18, v18, v60, v57
	s_and_b64 vcc, s[10:11], vcc
	v_or_b32_e32 v3, s9, v195
	v_max3_f32 v18, v18, v58, v55
	v_cndmask_b32_e32 v39, v222, v13, vcc
	s_and_b64 s[10:11], s[64:65], s[0:1]
	v_cmp_gt_i32_e32 vcc, s3, v3
	v_max3_f32 v18, v18, v56, v53
	s_and_b64 vcc, s[10:11], vcc
	v_or_b32_e32 v3, s9, v196
	v_max3_f32 v18, v18, v54, v51
	v_cndmask_b32_e32 v40, v222, v14, vcc
	s_and_b64 s[10:11], s[66:67], s[0:1]
	v_cmp_gt_i32_e32 vcc, s3, v3
	v_max3_f32 v2, v18, v52, v49
	s_and_b64 vcc, s[10:11], vcc
	v_or_b32_e32 v3, s9, v197
	v_max3_f32 v2, v2, v50, v47
	v_cndmask_b32_e32 v36, v222, v15, vcc
	s_and_b64 s[10:11], s[68:69], s[0:1]
	v_cmp_gt_i32_e32 vcc, s3, v3
	v_max3_f32 v2, v2, v48, v45
	s_and_b64 vcc, s[10:11], vcc
	v_or_b32_e32 v3, s9, v198
	v_max3_f32 v2, v2, v46, v43
	v_cndmask_b32_e32 v37, v222, v16, vcc
	s_and_b64 s[0:1], s[70:71], s[0:1]
	v_cmp_gt_i32_e32 vcc, s3, v3
	v_and_b32_e32 v4, 64, v220
	v_max3_f32 v2, v2, v44, v41
	s_and_b64 vcc, s[0:1], vcc
	v_xor_b32_e32 v3, 32, v220
	v_add_u32_e32 v4, 64, v4
	v_max3_f32 v2, v2, v42, v39
	v_cndmask_b32_e32 v38, v222, v17, vcc
	v_cmp_lt_i32_e32 vcc, v3, v4
	v_max3_f32 v2, v2, v40, v36
	v_max3_f32 v2, v2, v37, v38
	v_cndmask_b32_e32 v3, v220, v3, vcc
	v_lshlrev_b32_e32 v35, 2, v3
	ds_bpermute_b32 v3, v35, v2
	s_waitcnt lgkmcnt(0)
; #define LASP __attribute__((address_space(3)))
; __device__ __forceinline__ unsigned cvtpk(float lo, float hi) { return pk2(lo, hi); }
; __device__ __forceinline__ void attn_phase_mfma(const Ctx& c, unsigned char* lds_raw, bool do_store) {
;     ...
;         float lsum = 0.f;
;     #pragma unroll
;         for (int kb = 0; kb < 5; ++kb)
;     #pragma unroll
;             for (int e = 0; e < 16; ++e) { const float p = __builtin_amdgcn_exp2f(sacc[kb][e] - mx); sacc[kb][e] = p; lsum += p; }
;         lsum += __shfl_xor(lsum, 32);
;         f32x16 oacc[2];
;     #pragma unroll
;         for (int db = 0; db < 2; ++db)
;     #pragma unroll
;             for (int e = 0; e < 16; ++e) oacc[db][e] = 0.f;
;     #pragma unroll
;         for (int kb = 0; kb < 5; ++kb)
;     #pragma unroll
;             for (int s2 = 0; s2 < 2; ++s2) {
;                 u32x4 pw;
;     #pragma unroll
;                 for (int e = 0; e < 4; ++e) pw[e] = cvtpk(sacc[kb][8 * s2 + 2 * e], sacc[kb][8 * s2 + 2 * e + 1]);
;                 const bf16x8 pf = __builtin_bit_cast(bf16x8, pw);
;                 const int kp = (32 * wave + 32 * kb + 16 * s2 + 4 * h) >> 1;
;     #pragma unroll
;                 for (int db = 0; db < 2; ++db) {
;                     const LASP unsigned* vp = Vt + (32 * db + rq) * 194 + kp;
;                     const u32x2 g0 = *(const LASP u32x2*)vp, g1 = *(const LASP u32x2*)(vp + 4);
;                     const u32x4 aw = (u32x4){g0.x, g0.y, g1.x, g1.y};
;                     oacc[db] = mfma32_g(__builtin_bit_cast(bf16x8, aw), pf, oacc[db]);
;                 }
;             }
	v_max_f32_e32 v3, v3, v3
	v_max_f32_e32 v34, v2, v3
	v_sub_f32_e32 v2, v107, v34
	v_exp_f32_e32 v6, v2
	v_sub_f32_e32 v2, v67, v34
	v_exp_f32_e32 v7, v2
	v_sub_f32_e32 v2, v68, v34
	v_exp_f32_e32 v8, v2
	v_sub_f32_e32 v3, v69, v34
	v_exp_f32_e32 v9, v3
	v_sub_f32_e32 v3, v70, v34
	v_add_f32_e32 v2, 0, v6
	v_exp_f32_e32 v10, v3
	v_sub_f32_e32 v3, v71, v34
	v_add_f32_e32 v2, v7, v2
	v_exp_f32_e32 v11, v3
	v_sub_f32_e32 v3, v72, v34
	v_add_f32_e32 v2, v8, v2
	v_exp_f32_e32 v12, v3
	v_sub_f32_e32 v3, v73, v34
	v_add_f32_e32 v2, v9, v2
	v_exp_f32_e32 v13, v3
	v_sub_f32_e32 v3, v74, v34
	v_add_f32_e32 v2, v10, v2
	v_exp_f32_e32 v67, v3
	v_sub_f32_e32 v3, v75, v34
	v_add_f32_e32 v2, v11, v2
	v_exp_f32_e32 v107, v3
	v_sub_f32_e32 v3, v76, v34
	v_add_f32_e32 v2, v12, v2
	v_exp_f32_e32 v76, v3
	v_sub_f32_e32 v3, v77, v34
	v_add_f32_e32 v2, v13, v2
	v_exp_f32_e32 v77, v3
	v_sub_f32_e32 v3, v78, v34
	v_add_f32_e32 v2, v67, v2
	v_exp_f32_e32 v78, v3
	v_sub_f32_e32 v3, v79, v34
	v_add_f32_e32 v2, v107, v2
	v_exp_f32_e32 v79, v3
	v_sub_f32_e32 v3, v80, v34
	v_add_f32_e32 v2, v76, v2
	v_exp_f32_e32 v80, v3
	v_sub_f32_e32 v3, v81, v34
	v_add_f32_e32 v2, v77, v2
	v_exp_f32_e32 v81, v3
	v_sub_f32_e32 v3, v150, v34
	v_add_f32_e32 v2, v78, v2
	v_exp_f32_e32 v150, v3
	v_sub_f32_e32 v3, v151, v34
	v_add_f32_e32 v2, v79, v2
	v_exp_f32_e32 v151, v3
	v_sub_f32_e32 v3, v152, v34
	v_add_f32_e32 v2, v80, v2
	v_exp_f32_e32 v152, v3
	v_sub_f32_e32 v3, v153, v34
	v_add_f32_e32 v2, v81, v2
	v_exp_f32_e32 v153, v3
	v_sub_f32_e32 v3, v154, v34
	v_add_f32_e32 v2, v150, v2
	v_exp_f32_e32 v154, v3
	v_sub_f32_e32 v3, v155, v34
	v_add_f32_e32 v2, v151, v2
	v_exp_f32_e32 v155, v3
	v_sub_f32_e32 v3, v156, v34
	v_add_f32_e32 v2, v152, v2
	v_exp_f32_e32 v156, v3
	v_sub_f32_e32 v3, v157, v34
	v_add_f32_e32 v2, v153, v2
	v_exp_f32_e32 v157, v3
	v_sub_f32_e32 v3, v159, v34
	v_add_f32_e32 v2, v154, v2
	v_exp_f32_e32 v159, v3
	v_sub_f32_e32 v3, v169, v34
	v_add_f32_e32 v2, v155, v2
	v_exp_f32_e32 v169, v3
	v_sub_f32_e32 v3, v224, v34
	v_add_f32_e32 v2, v156, v2
	v_exp_f32_e32 v224, v3
	v_sub_f32_e32 v3, v225, v34
	v_add_f32_e32 v2, v157, v2
	v_exp_f32_e32 v225, v3
	v_sub_f32_e32 v3, v226, v34
	v_add_f32_e32 v2, v159, v2
	v_exp_f32_e32 v226, v3
	v_sub_f32_e32 v3, v227, v34
	v_add_f32_e32 v2, v169, v2
	v_exp_f32_e32 v227, v3
	v_sub_f32_e32 v3, v228, v34
	v_add_f32_e32 v2, v224, v2
	v_exp_f32_e32 v228, v3
	v_sub_f32_e32 v3, v229, v34
	v_add_f32_e32 v2, v225, v2
	v_exp_f32_e32 v229, v3
	v_sub_f32_e32 v3, v230, v34
	v_add_f32_e32 v2, v226, v2
	v_exp_f32_e32 v230, v3
	v_sub_f32_e32 v3, v231, v34
	v_add_f32_e32 v2, v227, v2
	v_exp_f32_e32 v231, v3
	v_sub_f32_e32 v3, v232, v34
	v_add_f32_e32 v2, v228, v2
	v_exp_f32_e32 v232, v3
	v_sub_f32_e32 v3, v233, v34
	v_add_f32_e32 v2, v229, v2
	v_exp_f32_e32 v233, v3
	v_sub_f32_e32 v3, v234, v34
	v_add_f32_e32 v2, v230, v2
	v_exp_f32_e32 v234, v3
	v_sub_f32_e32 v3, v235, v34
	v_add_f32_e32 v2, v231, v2
	v_exp_f32_e32 v235, v3
	v_sub_f32_e32 v3, v236, v34
	v_add_f32_e32 v2, v232, v2
	v_exp_f32_e32 v236, v3
	v_sub_f32_e32 v3, v237, v34
	v_add_f32_e32 v2, v233, v2
	v_exp_f32_e32 v237, v3
	v_sub_f32_e32 v3, v238, v34
	v_add_f32_e32 v2, v234, v2
	v_exp_f32_e32 v238, v3
	v_sub_f32_e32 v3, v239, v34
	v_add_f32_e32 v2, v235, v2
	v_exp_f32_e32 v239, v3
	v_sub_f32_e32 v3, v240, v34
	v_add_f32_e32 v2, v236, v2
	v_exp_f32_e32 v240, v3
	v_add_f32_e32 v2, v237, v2
	v_add_f32_e32 v2, v238, v2
	v_add_f32_e32 v2, v239, v2
	v_add_f32_e32 v14, v240, v2
	v_add_u32_e32 v2, v200, v199
	v_add_u32_e32 v247, 0xc000, v2
	ds_read2_b64 v[2:5], v247 offset1:2
	v_cvt_pk_bf16_f32 v68, v6, v7
	v_cvt_pk_bf16_f32 v69, v8, v9
	v_cvt_pk_bf16_f32 v70, v10, v11
	v_cvt_pk_bf16_f32 v71, v12, v13
	v_sub_f32_e32 v15, v241, v34
	v_exp_f32_e32 v241, v15
	s_waitcnt lgkmcnt(0)
	v_mfma_f32_32x32x16_bf16 v[18:33], v[2:5], v[68:71], 0
	v_add_u32_e32 v2, v200, v201
	v_add_u32_e32 v248, 0xc000, v2
	ds_read2_b64 v[72:75], v248 offset1:2
	v_sub_f32_e32 v15, v242, v34
	v_exp_f32_e32 v242, v15
	v_sub_f32_e32 v2, v243, v34
	v_exp_f32_e32 v243, v2
	v_sub_f32_e32 v2, v244, v34
	v_exp_f32_e32 v244, v2
	v_add_f32_e32 v2, v241, v14
	v_add_f32_e32 v2, v242, v2
	v_add_f32_e32 v2, v243, v2
	v_add_f32_e32 v249, v244, v2
	s_waitcnt lgkmcnt(0)
	v_mfma_f32_32x32x16_bf16 v[2:17], v[72:75], v[68:71], 0
	ds_read2_b64 v[68:71], v247 offset0:4 offset1:6
	v_sub_f32_e32 v72, v245, v34
	v_exp_f32_e32 v245, v72
	v_sub_f32_e32 v72, v246, v34
	v_exp_f32_e32 v246, v72
	v_cvt_pk_bf16_f32 v72, v67, v107
	v_cvt_pk_bf16_f32 v73, v76, v77
	v_cvt_pk_bf16_f32 v74, v78, v79
	v_cvt_pk_bf16_f32 v75, v80, v81
	v_sub_f32_e32 v65, v65, v34
	v_exp_f32_e32 v76, v65
	s_waitcnt lgkmcnt(0)
	v_mfma_f32_32x32x16_bf16 v[18:33], v[68:71], v[72:75], v[18:33]
	ds_read2_b64 v[68:71], v248 offset0:4 offset1:6
	v_sub_f32_e32 v65, v66, v34
	v_exp_f32_e32 v77, v65
	v_add_f32_e32 v65, v245, v249
	v_add_f32_e32 v65, v246, v65
	v_add_f32_e32 v65, v76, v65
	v_add_f32_e32 v78, v77, v65
	v_add_u32_e32 v65, v202, v199
	v_add_u32_e32 v65, 0xc000, v65
	s_waitcnt lgkmcnt(0)
	v_mfma_f32_32x32x16_bf16 v[2:17], v[68:71], v[72:75], v[2:17]
	ds_read2_b64 v[66:69], v65 offset1:2
	v_sub_f32_e32 v63, v63, v34
	v_exp_f32_e32 v74, v63
	v_sub_f32_e32 v63, v64, v34
	v_exp_f32_e32 v75, v63
	v_add_u32_e32 v63, v202, v201
	v_cvt_pk_bf16_f32 v70, v150, v151
	v_cvt_pk_bf16_f32 v71, v152, v153
	v_cvt_pk_bf16_f32 v72, v154, v155
	v_cvt_pk_bf16_f32 v73, v156, v157
	v_add_u32_e32 v63, 0xc000, v63
	v_sub_f32_e32 v61, v61, v34
	s_waitcnt lgkmcnt(0)
; #define LASP __attribute__((address_space(3)))
; __device__ __forceinline__ unsigned cvtpk(float lo, float hi) { return pk2(lo, hi); }
; __device__ __forceinline__ void attn_phase_mfma(const Ctx& c, unsigned char* lds_raw, bool do_store) {
;     ...
;     #pragma unroll
;         for (int kb = 0; kb < 5; ++kb)
;     #pragma unroll
;             for (int s2 = 0; s2 < 2; ++s2) {
;                 u32x4 pw;
;     #pragma unroll
;                 for (int e = 0; e < 4; ++e) pw[e] = cvtpk(sacc[kb][8 * s2 + 2 * e], sacc[kb][8 * s2 + 2 * e + 1]);
;                 const bf16x8 pf = __builtin_bit_cast(bf16x8, pw);
;                 const int kp = (32 * wave + 32 * kb + 16 * s2 + 4 * h) >> 1;
;     #pragma unroll
;                 for (int db = 0; db < 2; ++db) {
;                     const LASP unsigned* vp = Vt + (32 * db + rq) * 194 + kp;
;                     const u32x2 g0 = *(const LASP u32x2*)vp, g1 = *(const LASP u32x2*)(vp + 4);
;                     const u32x4 aw = (u32x4){g0.x, g0.y, g1.x, g1.y};
;                     oacc[db] = mfma32_g(__builtin_bit_cast(bf16x8, aw), pf, oacc[db]);
;                 }
;             }
	v_mfma_f32_32x32x16_bf16 v[18:33], v[66:69], v[70:73], v[18:33]
	ds_read2_b64 v[64:67], v63 offset1:2
	v_exp_f32_e32 v79, v61
	v_sub_f32_e32 v61, v62, v34
	v_exp_f32_e32 v80, v61
	v_add_f32_e32 v61, v74, v78
	v_add_f32_e32 v61, v75, v61
	v_add_f32_e32 v61, v79, v61
	v_add_f32_e32 v78, v80, v61
	v_add_u32_e32 v61, v203, v199
	v_add_u32_e32 v61, 0xc000, v61
	s_waitcnt lgkmcnt(0)
	v_mfma_f32_32x32x16_bf16 v[2:17], v[64:67], v[70:73], v[2:17]
	ds_read2_b64 v[62:65], v61 offset1:2
	v_sub_f32_e32 v59, v59, v34
	v_exp_f32_e32 v70, v59
	v_sub_f32_e32 v59, v60, v34
	v_exp_f32_e32 v71, v59
	v_add_u32_e32 v59, v203, v201
	v_cvt_pk_bf16_f32 v66, v159, v169
	v_cvt_pk_bf16_f32 v67, v224, v225
	v_cvt_pk_bf16_f32 v68, v226, v227
	v_cvt_pk_bf16_f32 v69, v228, v229
	v_add_u32_e32 v59, 0xc000, v59
	v_sub_f32_e32 v57, v57, v34
	s_waitcnt lgkmcnt(0)
	v_mfma_f32_32x32x16_bf16 v[18:33], v[62:65], v[66:69], v[18:33]
	ds_read2_b64 v[60:63], v59 offset1:2
	v_exp_f32_e32 v72, v57
	v_sub_f32_e32 v57, v58, v34
	v_exp_f32_e32 v73, v57
	v_add_f32_e32 v57, v70, v78
	v_add_f32_e32 v57, v71, v57
	v_add_f32_e32 v57, v72, v57
	v_add_f32_e32 v78, v73, v57
	v_add_u32_e32 v57, v204, v199
	v_add_u32_e32 v57, 0xc000, v57
	s_waitcnt lgkmcnt(0)
	v_mfma_f32_32x32x16_bf16 v[2:17], v[60:63], v[66:69], v[2:17]
	ds_read2_b64 v[58:61], v57 offset1:2
	v_sub_f32_e32 v55, v55, v34
	v_exp_f32_e32 v66, v55
	v_sub_f32_e32 v55, v56, v34
	v_exp_f32_e32 v67, v55
	v_add_u32_e32 v55, v204, v201
	v_cvt_pk_bf16_f32 v62, v230, v231
	v_cvt_pk_bf16_f32 v63, v232, v233
	v_cvt_pk_bf16_f32 v64, v234, v235
	v_cvt_pk_bf16_f32 v65, v236, v237
	v_add_u32_e32 v55, 0xc000, v55
	v_sub_f32_e32 v53, v53, v34
	s_waitcnt lgkmcnt(0)
	v_mfma_f32_32x32x16_bf16 v[18:33], v[58:61], v[62:65], v[18:33]
	ds_read2_b64 v[56:59], v55 offset1:2
	v_exp_f32_e32 v68, v53
	v_sub_f32_e32 v53, v54, v34
	v_exp_f32_e32 v69, v53
	v_add_f32_e32 v53, v66, v78
	v_add_f32_e32 v53, v67, v53
	v_add_f32_e32 v53, v68, v53
	v_add_f32_e32 v78, v69, v53
	v_add_u32_e32 v53, v205, v199
	v_add_u32_e32 v53, 0xc000, v53
	s_waitcnt lgkmcnt(0)
	v_mfma_f32_32x32x16_bf16 v[2:17], v[56:59], v[62:65], v[2:17]
	ds_read2_b64 v[54:57], v53 offset1:2
	v_sub_f32_e32 v51, v51, v34
	v_exp_f32_e32 v62, v51
	v_sub_f32_e32 v51, v52, v34
	v_exp_f32_e32 v63, v51
	v_add_u32_e32 v51, v205, v201
	v_cvt_pk_bf16_f32 v58, v238, v239
	v_cvt_pk_bf16_f32 v59, v240, v241
	v_cvt_pk_bf16_f32 v60, v242, v243
	v_cvt_pk_bf16_f32 v61, v244, v245
	v_add_u32_e32 v51, 0xc000, v51
	v_sub_f32_e32 v49, v49, v34
	s_waitcnt lgkmcnt(0)
	v_mfma_f32_32x32x16_bf16 v[18:33], v[54:57], v[58:61], v[18:33]
	ds_read2_b64 v[52:55], v51 offset1:2
	v_exp_f32_e32 v64, v49
	v_sub_f32_e32 v49, v50, v34
	v_exp_f32_e32 v65, v49
	v_add_f32_e32 v49, v62, v78
	v_add_f32_e32 v49, v63, v49
	v_add_f32_e32 v49, v64, v49
	v_add_f32_e32 v78, v65, v49
	v_add_u32_e32 v49, v206, v199
	v_add_u32_e32 v49, 0xc000, v49
	s_waitcnt lgkmcnt(0)
	v_mfma_f32_32x32x16_bf16 v[2:17], v[52:55], v[58:61], v[2:17]
	ds_read2_b64 v[50:53], v49 offset1:2
	v_sub_f32_e32 v47, v47, v34
	v_exp_f32_e32 v58, v47
	v_sub_f32_e32 v47, v48, v34
	v_exp_f32_e32 v59, v47
	v_add_u32_e32 v47, v206, v201
	v_cvt_pk_bf16_f32 v54, v246, v76
	v_cvt_pk_bf16_f32 v55, v77, v74
	v_cvt_pk_bf16_f32 v56, v75, v79
	v_cvt_pk_bf16_f32 v57, v80, v70
	v_add_u32_e32 v47, 0xc000, v47
	v_sub_f32_e32 v45, v45, v34
	s_waitcnt lgkmcnt(0)
	v_mfma_f32_32x32x16_bf16 v[18:33], v[50:53], v[54:57], v[18:33]
	ds_read2_b64 v[48:51], v47 offset1:2
	v_exp_f32_e32 v60, v45
	v_sub_f32_e32 v45, v46, v34
	v_exp_f32_e32 v61, v45
	v_add_f32_e32 v45, v58, v78
	v_add_f32_e32 v45, v59, v45
	v_add_f32_e32 v45, v60, v45
	v_add_f32_e32 v70, v61, v45
	v_add_u32_e32 v45, v207, v199
	v_add_u32_e32 v45, 0xc000, v45
	s_waitcnt lgkmcnt(0)
	v_mfma_f32_32x32x16_bf16 v[2:17], v[48:51], v[54:57], v[2:17]
	ds_read2_b64 v[46:49], v45 offset1:2
	v_sub_f32_e32 v43, v43, v34
	v_exp_f32_e32 v54, v43
	v_sub_f32_e32 v43, v44, v34
	v_exp_f32_e32 v55, v43
	v_add_u32_e32 v43, v207, v201
	v_cvt_pk_bf16_f32 v50, v71, v72
	v_cvt_pk_bf16_f32 v51, v73, v66
	v_cvt_pk_bf16_f32 v52, v67, v68
	v_cvt_pk_bf16_f32 v53, v69, v62
	v_add_u32_e32 v43, 0xc000, v43
	v_sub_f32_e32 v41, v41, v34
	s_waitcnt lgkmcnt(0)
	v_mfma_f32_32x32x16_bf16 v[18:33], v[46:49], v[50:53], v[18:33]
	ds_read2_b64 v[44:47], v43 offset1:2
	v_exp_f32_e32 v56, v41
	v_sub_f32_e32 v41, v42, v34
	v_exp_f32_e32 v57, v41
	v_add_f32_e32 v41, v54, v70
	v_add_f32_e32 v41, v55, v41
	v_add_f32_e32 v41, v56, v41
	v_add_f32_e32 v62, v57, v41
	v_add_u32_e32 v41, v208, v199
	v_add_u32_e32 v41, 0xc000, v41
	s_waitcnt lgkmcnt(0)
	v_mfma_f32_32x32x16_bf16 v[2:17], v[44:47], v[50:53], v[2:17]
	ds_read2_b64 v[42:45], v41 offset1:2
	v_sub_f32_e32 v39, v39, v34
	v_exp_f32_e32 v50, v39
	v_sub_f32_e32 v39, v40, v34
	v_exp_f32_e32 v51, v39
	v_add_u32_e32 v39, v208, v201
	v_cvt_pk_bf16_f32 v46, v63, v64
	v_cvt_pk_bf16_f32 v47, v65, v58
	v_cvt_pk_bf16_f32 v48, v59, v60
	v_cvt_pk_bf16_f32 v49, v61, v54
	v_add_u32_e32 v39, 0xc000, v39
	v_sub_f32_e32 v36, v36, v34
	s_waitcnt lgkmcnt(0)
; #define LASP __attribute__((address_space(3)))
; __device__ __forceinline__ unsigned cvtpk(float lo, float hi) { return pk2(lo, hi); }
; __device__ __forceinline__ void attn_phase_mfma(const Ctx& c, unsigned char* lds_raw, bool do_store) {
;     ...
;         lsum += __shfl_xor(lsum, 32);
;         f32x16 oacc[2];
;     #pragma unroll
;         for (int db = 0; db < 2; ++db)
;     #pragma unroll
;             for (int e = 0; e < 16; ++e) oacc[db][e] = 0.f;
;     #pragma unroll
;         for (int kb = 0; kb < 5; ++kb)
;     #pragma unroll
;             for (int s2 = 0; s2 < 2; ++s2) {
;                 u32x4 pw;
;     #pragma unroll
;                 for (int e = 0; e < 4; ++e) pw[e] = cvtpk(sacc[kb][8 * s2 + 2 * e], sacc[kb][8 * s2 + 2 * e + 1]);
;                 const bf16x8 pf = __builtin_bit_cast(bf16x8, pw);
;                 const int kp = (32 * wave + 32 * kb + 16 * s2 + 4 * h) >> 1;
;     #pragma unroll
;                 for (int db = 0; db < 2; ++db) {
;                     const LASP unsigned* vp = Vt + (32 * db + rq) * 194 + kp;
;                     const u32x2 g0 = *(const LASP u32x2*)vp, g1 = *(const LASP u32x2*)(vp + 4);
;                     const u32x4 aw = (u32x4){g0.x, g0.y, g1.x, g1.y};
;                     oacc[db] = mfma32_g(__builtin_bit_cast(bf16x8, aw), pf, oacc[db]);
;                 }
;             }
;         asm volatile("s_nop 15\n\ts_nop 15" : "+v"(oacc[0]), "+v"(oacc[1]));
;         if (do_store) {
;             const float inv = 1.f / lsum;
;     #pragma unroll
;             for (int db = 0; db < 2; ++db)
;     #pragma unroll
;                 for (int g4 = 0; g4 < 4; ++g4) {
;                     const u32x2 w = (u32x2){cvtpk(oacc[db][4 * g4] * inv, oacc[db][4 * g4 + 1] * inv), cvtpk(oacc[db][4 * g4 + 2] * inv, oacc[db][4 * g4 + 3] * inv)};
;                     *(u32x2*)(qrow + 32 * db + 8 * g4 + 4 * h) = w;
;                 }
;             if (h == 0) c.LSE[((size_t)g * MT + tokq) * 4 + hI] = mx * 0.69314718f + __logf(lsum);
;         }
;         __syncthreads();
;         if (un >= NAT) break;
;         u = un;
;     }
	v_mfma_f32_32x32x16_bf16 v[18:33], v[42:45], v[46:49], v[18:33]
	ds_read2_b64 v[40:43], v39 offset1:2
	v_exp_f32_e32 v45, v36
	v_sub_f32_e32 v36, v37, v34
	v_exp_f32_e32 v52, v36
	v_sub_f32_e32 v36, v38, v34
	v_exp_f32_e32 v53, v36
	v_add_u32_e32 v36, v209, v199
	v_add_f32_e32 v39, v50, v62
	v_add_u32_e32 v36, 0xc000, v36
	v_add_f32_e32 v44, v51, v39
	s_waitcnt lgkmcnt(0)
	v_mfma_f32_32x32x16_bf16 v[2:17], v[40:43], v[46:49], v[2:17]
	ds_read2_b64 v[36:39], v36 offset1:2
	v_add_f32_e32 v40, v45, v44
	v_add_f32_e32 v40, v52, v40
	v_add_f32_e32 v44, v53, v40
	v_cvt_pk_bf16_f32 v40, v55, v56
	v_cvt_pk_bf16_f32 v41, v57, v50
	v_cvt_pk_bf16_f32 v42, v51, v45
	v_cvt_pk_bf16_f32 v43, v52, v53
	ds_bpermute_b32 v35, v35, v44
	s_waitcnt lgkmcnt(0)
	v_add_f32_e32 v35, v44, v35
	v_mfma_f32_32x32x16_bf16 v[18:33], v[36:39], v[40:43], v[18:33]
	v_add_u32_e32 v36, v209, v201
	v_add_u32_e32 v36, 0xc000, v36
	ds_read2_b64 v[36:39], v36 offset1:2
	v_div_scale_f32 v44, s[0:1], v35, v35, 1.0
	v_rcp_f32_e32 v45, v44
	s_waitcnt lgkmcnt(0)
	v_mfma_f32_32x32x16_bf16 v[2:17], v[36:39], v[40:43], v[2:17]
	v_fma_f32 v36, -v44, v45, 1.0
	v_fmac_f32_e32 v45, v36, v45
	v_div_scale_f32 v36, vcc, 1.0, v35, 1.0
	v_mul_f32_e32 v37, v36, v45
	v_fma_f32 v38, -v44, v37, v36
	v_fmac_f32_e32 v37, v38, v45
	v_fma_f32 v36, -v44, v37, v36
	v_div_fmas_f32 v36, v36, v45, v37
	s_nop 15
	s_nop 15
	v_div_fixup_f32 v36, v36, v35, 1.0
	v_lshlrev_b32_e32 v38, 1, v166
	v_and_b32_e32 v39, 32, v0
	v_lshrrev_b32_e32 v39, 2, v39
	v_add_u32_e32 v38, v38, v39
	v_mov_b32_e32 v39, v106
	v_lshl_add_u64 v[38:39], v[174:175], 0, v[38:39]
	v_pk_mul_f32 v[18:19], v[18:19], v[36:37] op_sel_hi:[1,0]
	v_pk_mul_f32 v[20:21], v[20:21], v[36:37] op_sel_hi:[1,0]
	v_cvt_pk_bf16_f32 v18, v18, v19
	v_cvt_pk_bf16_f32 v19, v20, v21
	v_pk_mul_f32 v[20:21], v[22:23], v[36:37] op_sel_hi:[1,0]
	v_pk_mul_f32 v[22:23], v[24:25], v[36:37] op_sel_hi:[1,0]
	v_cvt_pk_bf16_f32 v20, v20, v21
	v_cvt_pk_bf16_f32 v21, v22, v23
	v_pk_mul_f32 v[2:3], v[2:3], v[36:37] op_sel_hi:[1,0]
	v_pk_mul_f32 v[4:5], v[4:5], v[36:37] op_sel_hi:[1,0]
	v_permlane32_swap_b32_e32 v18, v20
	v_permlane32_swap_b32_e32 v19, v21
	v_cvt_pk_bf16_f32 v2, v2, v3
	v_cvt_pk_bf16_f32 v3, v4, v5
	v_pk_mul_f32 v[4:5], v[6:7], v[36:37] op_sel_hi:[1,0]
	v_pk_mul_f32 v[6:7], v[8:9], v[36:37] op_sel_hi:[1,0]
	global_store_dwordx4 v[38:39], v[18:21], off offset:1536
	v_cvt_pk_bf16_f32 v4, v4, v5
	v_cvt_pk_bf16_f32 v5, v6, v7
	v_pk_mul_f32 v[22:23], v[26:27], v[36:37] op_sel_hi:[1,0]
	v_pk_mul_f32 v[24:25], v[28:29], v[36:37] op_sel_hi:[1,0]
	v_permlane32_swap_b32_e32 v2, v4
	v_permlane32_swap_b32_e32 v3, v5
	v_cvt_pk_bf16_f32 v22, v22, v23
	v_cvt_pk_bf16_f32 v23, v24, v25
	v_pk_mul_f32 v[24:25], v[30:31], v[36:37] op_sel_hi:[1,0]
	v_pk_mul_f32 v[26:27], v[32:33], v[36:37] op_sel_hi:[1,0]
	global_store_dwordx4 v[38:39], v[2:5], off offset:1600
	v_cvt_pk_bf16_f32 v24, v24, v25
	v_cvt_pk_bf16_f32 v25, v26, v27
	v_pk_mul_f32 v[6:7], v[10:11], v[36:37] op_sel_hi:[1,0]
	v_pk_mul_f32 v[8:9], v[12:13], v[36:37] op_sel_hi:[1,0]
	v_permlane32_swap_b32_e32 v22, v24
	v_permlane32_swap_b32_e32 v23, v25
	v_cvt_pk_bf16_f32 v6, v6, v7
	v_cvt_pk_bf16_f32 v7, v8, v9
	v_pk_mul_f32 v[8:9], v[14:15], v[36:37] op_sel_hi:[1,0]
	v_pk_mul_f32 v[10:11], v[16:17], v[36:37] op_sel_hi:[1,0]
	global_store_dwordx4 v[38:39], v[22:25], off offset:1568
	v_cvt_pk_bf16_f32 v8, v8, v9
	v_cvt_pk_bf16_f32 v9, v10, v11
	s_nop 1
	v_permlane32_swap_b32_e32 v6, v8
	v_permlane32_swap_b32_e32 v7, v9
	global_store_dwordx4 v[38:39], v[6:9], off offset:1632
	s_mov_b64 s[0:1], exec
	v_readlane_b32 s10, v255, 15
	v_readlane_b32 s11, v255, 16
	s_and_b64 s[10:11], s[0:1], s[10:11]
	s_mov_b64 exec, s[10:11]
	s_cbranch_execz .LBB0_358
	s_mov_b32 s3, 0x800000
	v_cmp_gt_f32_e32 vcc, s3, v35
	s_mov_b32 s3, 0x3f317217
	s_ashr_i32 s89, s88, 31
	v_cndmask_b32_e64 v2, 0, 32, vcc
	v_ldexp_f32 v2, v35, v2
	v_log_f32_e32 v2, v2
	v_cndmask_b32_e32 v3, 0, v223, vcc
	s_lshl_b64 s[10:11], s[88:89], 19
	v_mul_f32_e32 v4, 0x3f317217, v2
	v_fma_f32 v4, v2, s3, -v4
	s_mov_b32 s3, 0x7f800000
	v_fmac_f32_e32 v4, 0x3377d1cf, v2
	v_cmp_lt_f32_e64 vcc, |v2|, s3
	v_readlane_b32 s3, v255, 13
	v_fmac_f32_e32 v4, 0x3f317217, v2
	s_add_u32 s10, s3, s10
	v_readlane_b32 s3, v255, 14
	v_cndmask_b32_e32 v2, v2, v4, vcc
	s_addc_u32 s11, s3, s11
	v_sub_f32_e32 v4, v2, v3
	v_lshl_add_u64 v[2:3], v[108:109], 4, s[10:11]
	s_lshl_b32 s96, s2, 2
	v_fmac_f32_e32 v4, 0x3f317218, v34
	v_lshl_add_u64 v[2:3], v[2:3], 0, s[96:97]
	global_store_dword v[2:3], v4, off
	s_branch .LBB0_358
	s_nop 0
.Lattn_exit_bar_a:
	s_barrier

; __device__ __forceinline__ float bflo(unsigned w) { return __uint_as_float(w << 16); }
; __device__ __forceinline__ float bfhi(unsigned w) { return __uint_as_float(w & 0xffff0000u); }
; __device__ __forceinline__ unsigned pk2(float lo, float hi) { const f32x2n v = {lo, hi}; return __builtin_bit_cast(unsigned, __builtin_convertvector(v, bf16x2n)); }
; #define LASP __attribute__((address_space(3)))
; __device__ __forceinline__ void attn_phase_mfma(const Ctx& c, unsigned char* lds_raw, bool do_store) {
;     ...
;         for (int i = 0; i < 3; ++i) {
;             const int id = t + 512 * i, row = id >> 2, dc = id & 3;
;             const h16x8 kcv = tkc[i], ksv = tks[i];
;             u32x4 olo, ohi;
; #pragma unroll
;             for (int e = 0; e < 4; ++e) {
;                 const float l0 = bflo(ka[i][e]), l1 = bfhi(ka[i][e]), h0 = bflo(kb2[i][e]), h1 = bfhi(kb2[i][e]);
;                 const float cc0 = (float)kcv[2 * e], cc1 = (float)kcv[2 * e + 1], ss0 = (float)ksv[2 * e], ss1 = (float)ksv[2 * e + 1];
;                 olo[e] = pk2(l0 * cc0 - h0 * ss0, l1 * cc1 - h1 * ss1);
;                 ohi[e] = pk2(h0 * cc0 + l0 * ss0, h1 * cc1 + l1 * ss1);
;             }
;             *(LASP u32x4*)(Kt + row * 128 + ((dc ^ (row & 7)) << 4)) = olo;
;             *(LASP u32x4*)(Kt + row * 128 + (((4 + dc) ^ (row & 7)) << 4)) = ohi;
;             const int rp = id % 192, dc8 = id / 192;
; #pragma unroll
;             for (int e = 0; e < 4; ++e) {
;                 Vt[(8 * dc8 + 2 * e) * 194 + rp] = __builtin_amdgcn_perm(vb[i][e], va[i][e], 0x05040100u);
;                 Vt[(8 * dc8 + 2 * e + 1) * 194 + rp] = __builtin_amdgcn_perm(vb[i][e], va[i][e], 0x07060302u);
;             }
.LBB0_1719:
	s_mul_hi_i32 s0, s33, 0x2aaaaaab
	s_lshr_b32 s1, s0, 31
	s_ashr_i32 s0, s0, 5
	s_add_i32 s0, s0, s1
	s_mul_i32 s1, s0, 0xffffff40
	s_add_i32 s1, s33, s1
	s_ashr_i32 s88, s1, 6
	s_lshl_b32 s96, s88, 1
	s_lshr_b32 s3, 16, s96
	s_and_b32 s2, s1, 15
	s_sub_i32 s9, 4, s96
	s_add_i32 s3, s3, -1
	s_lshr_b32 s10, s2, s9
	s_and_b32 s2, s3, s2
	s_lshl_b32 s9, s2, 8
	s_sub_i32 s89, s9, 64
	v_add_u32_e32 v18, s9, v180
	v_add_u32_e32 v34, s89, v1
	v_lshlrev_b32_e32 v18, s96, v18
	v_lshlrev_b32_e32 v34, s96, v34
	v_add_u32_e32 v58, s10, v18
	v_add_u32_e32 v34, s10, v34
	v_lshlrev_b32_e32 v18, 6, v58
	v_med3_i32 v34, v34, 0, v221
	v_ashrrev_i32_e32 v19, 31, v18
	v_lshlrev_b32_e32 v34, 7, v34
	v_mov_b32_e32 v35, v106
	v_lshl_add_u64 v[18:19], v[18:19], 1, v[170:171]
	v_lshl_add_u64 v[34:35], v[172:173], 0, v[34:35]
	global_load_dwordx4 v[30:33], v[18:19], off
	global_load_dwordx4 v[22:25], v[18:19], off offset:32
	global_load_dwordx4 v[26:29], v[18:19], off offset:64
	s_nop 0
	global_load_dwordx4 v[18:21], v[18:19], off offset:96
	s_nop 0
	global_load_dwordx4 v[54:57], v[34:35], off
	global_load_dwordx4 v[50:53], v[34:35], off offset:64
	v_add_u32_e32 v34, s89, v176
	v_lshlrev_b32_e32 v34, s96, v34
	v_add_u32_e32 v34, s10, v34
	v_med3_i32 v34, v34, 0, v221
	v_lshlrev_b32_e32 v34, 7, v34
	v_mov_b32_e32 v35, v106
	v_lshl_add_u64 v[34:35], v[172:173], 0, v[34:35]
	global_load_dwordx4 v[46:49], v[34:35], off
	global_load_dwordx4 v[42:45], v[34:35], off offset:64
	v_add_u32_e32 v34, s89, v178
	v_lshlrev_b32_e32 v34, s96, v34
	v_add_u32_e32 v34, s10, v34
	v_med3_i32 v34, v34, 0, v221
	v_lshlrev_b32_e32 v34, 7, v34
	v_mov_b32_e32 v35, v106
	v_lshl_add_u64 v[34:35], v[172:173], 0, v[34:35]
	global_load_dwordx4 v[38:41], v[34:35], off
	s_nop 0
	global_load_dwordx4 v[34:37], v[34:35], off offset:64
	s_barrier
	v_lshlrev_b32_e32 v62, 16, v86
	v_and_b32_e32 v63, 0xffff0000, v86
	v_lshlrev_b32_e32 v60, 16, v90
	v_and_b32_e32 v61, 0xffff0000, v90
	v_readlane_b32 s2, v255, 12
	s_add_i32 s33, s33, s2
	s_cmpk_gt_i32 s33, 0x5ff
	v_perm_b32 v250, v94, v82, s6
	v_perm_b32 v251, v94, v82, s7
	v_add_u32_e32 v252, 0xc000, v181
	ds_write2_b32 v252, v250, v251 offset1:194
	v_perm_b32 v250, v95, v83, s6
	v_perm_b32 v251, v95, v83, s7
	v_add_u32_e32 v252, 0xc600, v181
	ds_write2_b32 v252, v250, v251 offset0:4 offset1:198
	v_perm_b32 v250, v96, v84, s6
	v_perm_b32 v251, v96, v84, s7
	v_add_u32_e32 v252, 0xcc00, v181
	ds_write2_b32 v252, v250, v251 offset0:8 offset1:202
	v_perm_b32 v250, v97, v85, s6
	v_perm_b32 v251, v97, v85, s7
	v_add_u32_e32 v252, 0xd200, v181
	ds_write2_b32 v252, v250, v251 offset0:12 offset1:206
	v_perm_b32 v250, v114, v110, s6
	v_perm_b32 v251, v114, v110, s7
	v_add_u32_e32 v252, 0xc800, v182
	ds_write2_b32 v252, v250, v251 offset1:194
	v_perm_b32 v250, v115, v111, s6
	v_perm_b32 v251, v115, v111, s7
	v_add_u32_e32 v252, 0xce00, v182
	ds_write2_b32 v252, v250, v251 offset0:4 offset1:198
	v_perm_b32 v250, v116, v112, s6
	v_perm_b32 v251, v116, v112, s7
	v_add_u32_e32 v252, 0xd400, v182
	ds_write2_b32 v252, v250, v251 offset0:8 offset1:202
	v_perm_b32 v250, v117, v113, s6
	v_perm_b32 v251, v117, v113, s7
	v_add_u32_e32 v252, 0xda00, v182
	ds_write2_b32 v252, v250, v251 offset0:12 offset1:206
	v_perm_b32 v250, v146, v126, s6
	v_perm_b32 v251, v146, v126, s7
	v_add_u32_e32 v252, 0xd000, v183
	ds_write2_b32 v252, v250, v251 offset1:194
	v_perm_b32 v250, v147, v127, s6
	v_perm_b32 v251, v147, v127, s7
	v_add_u32_e32 v252, 0xd600, v183
	ds_write2_b32 v252, v250, v251 offset0:4 offset1:198
	v_perm_b32 v250, v148, v128, s6
	v_perm_b32 v251, v148, v128, s7
	v_add_u32_e32 v252, 0xdc00, v183
	ds_write2_b32 v252, v250, v251 offset0:8 offset1:202
	v_perm_b32 v250, v149, v129, s6
	v_perm_b32 v251, v149, v129, s7
	v_add_u32_e32 v252, 0xe200, v183
	ds_write2_b32 v252, v250, v251 offset0:12 offset1:206
	s_waitcnt vmcnt(5)
	v_cvt_f32_f16_e32 v64, v54
	s_waitcnt vmcnt(4)
	v_cvt_f32_f16_e32 v66, v50
	v_cvt_f32_f16_sdwa v67, v50 dst_sel:DWORD dst_unused:UNUSED_PAD src0_sel:WORD_1
	v_cvt_f32_f16_sdwa v65, v54 dst_sel:DWORD dst_unused:UNUSED_PAD src0_sel:WORD_1
	v_pk_mul_f32 v[68:69], v[62:63], v[66:67]
	s_nop 0
	v_pk_fma_f32 v[68:69], v[60:61], v[64:65], v[68:69] neg_lo:[0,0,1] neg_hi:[0,0,1]
	v_pk_mul_f32 v[60:61], v[60:61], v[66:67]
	v_cvt_f32_f16_e32 v66, v51
	v_cvt_f32_f16_sdwa v67, v51 dst_sel:DWORD dst_unused:UNUSED_PAD src0_sel:WORD_1
	v_pk_fma_f32 v[60:61], v[62:63], v[64:65], v[60:61]
	v_cvt_f32_f16_e32 v64, v55
	v_cvt_f32_f16_sdwa v65, v55 dst_sel:DWORD dst_unused:UNUSED_PAD src0_sel:WORD_1
	v_lshlrev_b32_e32 v62, 16, v87
	v_and_b32_e32 v63, 0xffff0000, v87
	v_cvt_pk_bf16_f32 v50, v68, v69
	v_cvt_pk_bf16_f32 v54, v60, v61
	v_lshlrev_b32_e32 v60, 16, v91
	v_and_b32_e32 v61, 0xffff0000, v91
	v_pk_mul_f32 v[68:69], v[62:63], v[66:67]
	s_nop 0
	v_pk_fma_f32 v[68:69], v[60:61], v[64:65], v[68:69] neg_lo:[0,0,1] neg_hi:[0,0,1]
	v_pk_mul_f32 v[60:61], v[60:61], v[66:67]
	v_cvt_f32_f16_e32 v66, v52
	v_cvt_f32_f16_sdwa v67, v52 dst_sel:DWORD dst_unused:UNUSED_PAD src0_sel:WORD_1
	v_pk_fma_f32 v[60:61], v[62:63], v[64:65], v[60:61]
	v_cvt_f32_f16_e32 v64, v56
	v_cvt_f32_f16_sdwa v65, v56 dst_sel:DWORD dst_unused:UNUSED_PAD src0_sel:WORD_1
	v_lshlrev_b32_e32 v62, 16, v88
	v_and_b32_e32 v63, 0xffff0000, v88
	v_cvt_pk_bf16_f32 v51, v68, v69
	v_cvt_pk_bf16_f32 v55, v60, v61
	v_lshlrev_b32_e32 v60, 16, v92
	v_and_b32_e32 v61, 0xffff0000, v92
	v_pk_mul_f32 v[68:69], v[62:63], v[66:67]
	s_nop 0
	v_pk_fma_f32 v[68:69], v[60:61], v[64:65], v[68:69] neg_lo:[0,0,1] neg_hi:[0,0,1]
	v_pk_mul_f32 v[60:61], v[60:61], v[66:67]
	v_cvt_f32_f16_e32 v66, v53
	v_cvt_f32_f16_sdwa v67, v53 dst_sel:DWORD dst_unused:UNUSED_PAD src0_sel:WORD_1
	v_pk_fma_f32 v[60:61], v[62:63], v[64:65], v[60:61]
	v_cvt_f32_f16_e32 v64, v57
	v_cvt_f32_f16_sdwa v65, v57 dst_sel:DWORD dst_unused:UNUSED_PAD src0_sel:WORD_1
	v_lshlrev_b32_e32 v62, 16, v89
	v_and_b32_e32 v63, 0xffff0000, v89
	v_cvt_pk_bf16_f32 v52, v68, v69
	v_cvt_pk_bf16_f32 v56, v60, v61
	v_lshlrev_b32_e32 v60, 16, v93
	v_and_b32_e32 v61, 0xffff0000, v93
	v_pk_mul_f32 v[68:69], v[62:63], v[66:67]
	s_nop 0
	v_pk_fma_f32 v[68:69], v[60:61], v[64:65], v[68:69] neg_lo:[0,0,1] neg_hi:[0,0,1]
	v_pk_mul_f32 v[60:61], v[60:61], v[66:67]
	v_cvt_pk_bf16_f32 v53, v68, v69
	v_pk_fma_f32 v[60:61], v[62:63], v[64:65], v[60:61]
	s_nop 0
	v_cvt_pk_bf16_f32 v57, v60, v61
	ds_write_b128 v210, v[50:53]
	ds_write_b128 v211, v[54:57]
	s_waitcnt vmcnt(2)
; __device__ __forceinline__ float bflo(unsigned w) { return __uint_as_float(w << 16); }
; __device__ __forceinline__ float bfhi(unsigned w) { return __uint_as_float(w & 0xffff0000u); }
; __device__ __forceinline__ unsigned pk2(float lo, float hi) { const f32x2n v = {lo, hi}; return __builtin_bit_cast(unsigned, __builtin_convertvector(v, bf16x2n)); }
; #define LASP __attribute__((address_space(3)))
; __device__ __forceinline__ void attn_phase_mfma(const Ctx& c, unsigned char* lds_raw, bool do_store) {
;     ...
;         for (int i = 0; i < 3; ++i) {
;             const int id = t + 512 * i, row = id >> 2, dc = id & 3;
;             const h16x8 kcv = tkc[i], ksv = tks[i];
;             u32x4 olo, ohi;
; #pragma unroll
;             for (int e = 0; e < 4; ++e) {
;                 const float l0 = bflo(ka[i][e]), l1 = bfhi(ka[i][e]), h0 = bflo(kb2[i][e]), h1 = bfhi(kb2[i][e]);
;                 const float cc0 = (float)kcv[2 * e], cc1 = (float)kcv[2 * e + 1], ss0 = (float)ksv[2 * e], ss1 = (float)ksv[2 * e + 1];
;                 olo[e] = pk2(l0 * cc0 - h0 * ss0, l1 * cc1 - h1 * ss1);
;                 ohi[e] = pk2(h0 * cc0 + l0 * ss0, h1 * cc1 + l1 * ss1);
;             }
;             *(LASP u32x4*)(Kt + row * 128 + ((dc ^ (row & 7)) << 4)) = olo;
;             *(LASP u32x4*)(Kt + row * 128 + (((4 + dc) ^ (row & 7)) << 4)) = ohi;
;             const int rp = id % 192, dc8 = id / 192;
; #pragma unroll
;             for (int e = 0; e < 4; ++e) {
;                 Vt[(8 * dc8 + 2 * e) * 194 + rp] = __builtin_amdgcn_perm(vb[i][e], va[i][e], 0x05040100u);
;                 Vt[(8 * dc8 + 2 * e + 1) * 194 + rp] = __builtin_amdgcn_perm(vb[i][e], va[i][e], 0x07060302u);
;             }
;         }
;         __syncthreads();
	v_cvt_f32_f16_e32 v56, v42
	v_cvt_f32_f16_sdwa v57, v42 dst_sel:DWORD dst_unused:UNUSED_PAD src0_sel:WORD_1
	v_cvt_f32_f16_e32 v54, v46
	v_cvt_f32_f16_sdwa v55, v46 dst_sel:DWORD dst_unused:UNUSED_PAD src0_sel:WORD_1
	v_lshlrev_b32_e32 v52, 16, v98
	v_and_b32_e32 v53, 0xffff0000, v98
	v_lshlrev_b32_e32 v50, 16, v102
	v_and_b32_e32 v51, 0xffff0000, v102
	v_pk_mul_f32 v[60:61], v[52:53], v[56:57]
	s_nop 0
	v_pk_fma_f32 v[60:61], v[50:51], v[54:55], v[60:61] neg_lo:[0,0,1] neg_hi:[0,0,1]
	v_pk_mul_f32 v[50:51], v[50:51], v[56:57]
	v_cvt_f32_f16_e32 v56, v43
	v_cvt_f32_f16_sdwa v57, v43 dst_sel:DWORD dst_unused:UNUSED_PAD src0_sel:WORD_1
	v_pk_fma_f32 v[50:51], v[52:53], v[54:55], v[50:51]
	v_cvt_f32_f16_e32 v54, v47
	v_cvt_f32_f16_sdwa v55, v47 dst_sel:DWORD dst_unused:UNUSED_PAD src0_sel:WORD_1
	v_lshlrev_b32_e32 v52, 16, v99
	v_and_b32_e32 v53, 0xffff0000, v99
	v_cvt_pk_bf16_f32 v42, v60, v61
	v_cvt_pk_bf16_f32 v46, v50, v51
	v_lshlrev_b32_e32 v50, 16, v103
	v_and_b32_e32 v51, 0xffff0000, v103
	v_pk_mul_f32 v[60:61], v[52:53], v[56:57]
	s_nop 0
	v_pk_fma_f32 v[60:61], v[50:51], v[54:55], v[60:61] neg_lo:[0,0,1] neg_hi:[0,0,1]
	v_pk_mul_f32 v[50:51], v[50:51], v[56:57]
	v_cvt_f32_f16_e32 v56, v44
	v_cvt_f32_f16_sdwa v57, v44 dst_sel:DWORD dst_unused:UNUSED_PAD src0_sel:WORD_1
	v_pk_fma_f32 v[50:51], v[52:53], v[54:55], v[50:51]
	v_cvt_f32_f16_e32 v54, v48
	v_cvt_f32_f16_sdwa v55, v48 dst_sel:DWORD dst_unused:UNUSED_PAD src0_sel:WORD_1
	v_lshlrev_b32_e32 v52, 16, v100
	v_and_b32_e32 v53, 0xffff0000, v100
	v_cvt_pk_bf16_f32 v43, v60, v61
	v_cvt_pk_bf16_f32 v47, v50, v51
	v_lshlrev_b32_e32 v50, 16, v104
	v_and_b32_e32 v51, 0xffff0000, v104
	v_pk_mul_f32 v[60:61], v[52:53], v[56:57]
	s_nop 0
	v_pk_fma_f32 v[60:61], v[50:51], v[54:55], v[60:61] neg_lo:[0,0,1] neg_hi:[0,0,1]
	v_pk_mul_f32 v[50:51], v[50:51], v[56:57]
	v_cvt_f32_f16_e32 v56, v45
	v_cvt_f32_f16_sdwa v57, v45 dst_sel:DWORD dst_unused:UNUSED_PAD src0_sel:WORD_1
	v_pk_fma_f32 v[50:51], v[52:53], v[54:55], v[50:51]
	v_cvt_f32_f16_e32 v54, v49
	v_cvt_f32_f16_sdwa v55, v49 dst_sel:DWORD dst_unused:UNUSED_PAD src0_sel:WORD_1
	v_lshlrev_b32_e32 v52, 16, v101
	v_and_b32_e32 v53, 0xffff0000, v101
	v_cvt_pk_bf16_f32 v44, v60, v61
	v_cvt_pk_bf16_f32 v48, v50, v51
	v_lshlrev_b32_e32 v50, 16, v105
	v_and_b32_e32 v51, 0xffff0000, v105
	v_pk_mul_f32 v[60:61], v[52:53], v[56:57]
	s_nop 0
	v_pk_fma_f32 v[60:61], v[50:51], v[54:55], v[60:61] neg_lo:[0,0,1] neg_hi:[0,0,1]
	v_pk_mul_f32 v[50:51], v[50:51], v[56:57]
	v_cvt_pk_bf16_f32 v45, v60, v61
	v_pk_fma_f32 v[50:51], v[52:53], v[54:55], v[50:51]
	s_nop 0
	v_cvt_pk_bf16_f32 v49, v50, v51
	ds_write_b128 v212, v[42:45]
	ds_write_b128 v213, v[46:49]
	s_waitcnt vmcnt(0)
	v_cvt_f32_f16_e32 v48, v34
	v_cvt_f32_f16_sdwa v49, v34 dst_sel:DWORD dst_unused:UNUSED_PAD src0_sel:WORD_1
	v_cvt_f32_f16_e32 v46, v38
	v_cvt_f32_f16_sdwa v47, v38 dst_sel:DWORD dst_unused:UNUSED_PAD src0_sel:WORD_1
	v_lshlrev_b32_e32 v44, 16, v118
	v_and_b32_e32 v45, 0xffff0000, v118
	v_lshlrev_b32_e32 v42, 16, v122
	v_and_b32_e32 v43, 0xffff0000, v122
	v_pk_mul_f32 v[50:51], v[44:45], v[48:49]
	s_nop 0
	v_pk_fma_f32 v[50:51], v[42:43], v[46:47], v[50:51] neg_lo:[0,0,1] neg_hi:[0,0,1]
	v_pk_mul_f32 v[42:43], v[42:43], v[48:49]
	v_cvt_f32_f16_e32 v48, v35
	v_cvt_f32_f16_sdwa v49, v35 dst_sel:DWORD dst_unused:UNUSED_PAD src0_sel:WORD_1
	v_pk_fma_f32 v[42:43], v[44:45], v[46:47], v[42:43]
	v_cvt_f32_f16_e32 v46, v39
	v_cvt_f32_f16_sdwa v47, v39 dst_sel:DWORD dst_unused:UNUSED_PAD src0_sel:WORD_1
	v_lshlrev_b32_e32 v44, 16, v119
	v_and_b32_e32 v45, 0xffff0000, v119
	v_cvt_pk_bf16_f32 v34, v50, v51
	v_cvt_pk_bf16_f32 v38, v42, v43
	v_lshlrev_b32_e32 v42, 16, v123
	v_and_b32_e32 v43, 0xffff0000, v123
	v_pk_mul_f32 v[50:51], v[44:45], v[48:49]
	s_nop 0
	v_pk_fma_f32 v[50:51], v[42:43], v[46:47], v[50:51] neg_lo:[0,0,1] neg_hi:[0,0,1]
	v_pk_mul_f32 v[42:43], v[42:43], v[48:49]
	v_cvt_f32_f16_e32 v48, v36
	v_cvt_f32_f16_sdwa v49, v36 dst_sel:DWORD dst_unused:UNUSED_PAD src0_sel:WORD_1
	v_pk_fma_f32 v[42:43], v[44:45], v[46:47], v[42:43]
	v_cvt_f32_f16_e32 v46, v40
	v_cvt_f32_f16_sdwa v47, v40 dst_sel:DWORD dst_unused:UNUSED_PAD src0_sel:WORD_1
	v_lshlrev_b32_e32 v44, 16, v120
	v_and_b32_e32 v45, 0xffff0000, v120
	v_cvt_pk_bf16_f32 v35, v50, v51
	v_cvt_pk_bf16_f32 v39, v42, v43
	v_lshlrev_b32_e32 v42, 16, v124
	v_and_b32_e32 v43, 0xffff0000, v124
	v_pk_mul_f32 v[50:51], v[44:45], v[48:49]
	s_nop 0
	v_pk_fma_f32 v[50:51], v[42:43], v[46:47], v[50:51] neg_lo:[0,0,1] neg_hi:[0,0,1]
	v_pk_mul_f32 v[42:43], v[42:43], v[48:49]
	v_cvt_f32_f16_e32 v48, v37
	v_cvt_f32_f16_sdwa v49, v37 dst_sel:DWORD dst_unused:UNUSED_PAD src0_sel:WORD_1
	v_pk_fma_f32 v[42:43], v[44:45], v[46:47], v[42:43]
	v_cvt_f32_f16_e32 v46, v41
	v_cvt_f32_f16_sdwa v47, v41 dst_sel:DWORD dst_unused:UNUSED_PAD src0_sel:WORD_1
	v_lshlrev_b32_e32 v44, 16, v121
	v_and_b32_e32 v45, 0xffff0000, v121
	v_cvt_pk_bf16_f32 v36, v50, v51
	v_cvt_pk_bf16_f32 v40, v42, v43
	v_lshlrev_b32_e32 v42, 16, v125
	v_and_b32_e32 v43, 0xffff0000, v125
	v_pk_mul_f32 v[50:51], v[44:45], v[48:49]
	s_nop 0
	v_pk_fma_f32 v[50:51], v[42:43], v[46:47], v[50:51] neg_lo:[0,0,1] neg_hi:[0,0,1]
	v_pk_mul_f32 v[42:43], v[42:43], v[48:49]
	v_cvt_pk_bf16_f32 v37, v50, v51
	v_pk_fma_f32 v[42:43], v[44:45], v[46:47], v[42:43]
	s_nop 0
	v_cvt_pk_bf16_f32 v41, v42, v43
	ds_write_b128 v214, v[34:37]
	ds_write_b128 v215, v[38:41]
	s_waitcnt lgkmcnt(0)
	s_barrier
; __device__ __forceinline__ void attn_phase_mfma(const Ctx& c, unsigned char* lds_raw, bool do_store) {
;     ...
;         const int un = u + G;
;         if (un < NAT) ATT_PREFETCH(un);
	s_cbranch_scc1 .LBB0_1739
	s_mul_hi_i32 s2, s33, 0x2aaaaaab
	s_lshr_b32 s3, s2, 31
	s_ashr_i32 s2, s2, 5
	s_add_i32 s2, s2, s3
	s_mul_i32 s3, s2, 0xffffff40
	s_add_i32 s3, s33, s3
	s_ashr_i32 s11, s3, 6
	s_lshl_b32 s10, s11, 1
	s_lshr_b32 s13, 16, s10
	s_and_b32 s3, s3, 15
	s_sub_i32 s12, 4, s10
	s_add_i32 s13, s13, -1
	s_lshr_b32 s12, s3, s12
	s_and_b32 s3, s13, s3
	s_lshl_b32 s13, s3, 8
	s_ashr_i32 s3, s2, 31
	v_add_u32_e32 v34, s13, v180
	s_lshl_b64 s[94:95], s[2:3], 12
	v_lshlrev_b32_e32 v34, s10, v34
	s_or_b32 s90, s94, s12
	s_mov_b32 s91, s95
	v_ashrrev_i32_e32 v35, 31, v34
	v_lshl_add_u64 v[34:35], s[90:91], 0, v[34:35]
	v_mov_b64_e32 v[36:37], s[92:93]
	v_mad_u64_u32 v[36:37], s[2:3], v34, s8, v[36:37]
	s_lshl_b32 s2, s11, 8
	s_and_b32 s3, s4, 0xc0
	s_or_b32 s2, s2, s3
	v_mad_i32_i24 v37, v35, s8, v37
	s_ashr_i32 s3, s2, 31
	v_lshl_add_u64 v[34:35], s[2:3], 1, v[36:37]
	v_mov_b32_e32 v169, v106
	v_lshl_add_u64 v[34:35], v[34:35], 0, v[168:169]
	global_load_dwordx4 v[142:145], v[34:35], off offset:1536
	global_load_dwordx4 v[138:141], v[34:35], off offset:1568
	global_load_dwordx4 v[134:137], v[34:35], off offset:1600
	global_load_dwordx4 v[130:133], v[34:35], off offset:1632
	s_sub_i32 s13, s13, 64
	s_lshr_b32 s11, 0x1000, s10
	v_add_u32_e32 v34, s13, v1
	v_mov_b32_e32 v84, v106
	v_mov_b32_e32 v85, v106
	v_cmp_lt_i32_e32 vcc, -1, v34
	v_cmp_gt_i32_e64 s[74:75], s11, v34
	v_mov_b32_e32 v82, v106
	v_mov_b32_e32 v83, v106
	v_mov_b64_e32 v[88:89], v[84:85]
	v_mov_b64_e32 v[92:93], v[84:85]
	s_and_b64 vcc, vcc, s[74:75]
	v_mov_b64_e32 v[86:87], v[82:83]
	v_mov_b64_e32 v[90:91], v[82:83]
	s_and_saveexec_b64 s[74:75], vcc
	s_cbranch_execz .LBB0_1722
	v_lshlrev_b32_e32 v34, s10, v34
	v_add_u32_e32 v34, s12, v34
	v_mov_b32_e32 v35, v106
	v_lshl_add_u64 v[34:35], s[94:95], 0, v[34:35]
	v_mov_b64_e32 v[36:37], s[92:93]
	v_mad_u64_u32 v[36:37], vcc, v34, s8, v[36:37]
	v_mad_i32_i24 v37, v35, s8, v37
	v_lshl_add_u64 v[34:35], s[2:3], 1, v[36:37]
	v_mov_b32_e32 v159, v106
	v_lshl_add_u64 v[34:35], v[34:35], 0, v[158:159]
	global_load_dwordx4 v[90:93], v[34:35], off offset:3072
	global_load_dwordx4 v[86:89], v[34:35], off offset:3136

; __device__ __forceinline__ float bflo(unsigned w) { return __uint_as_float(w << 16); }
; __device__ __forceinline__ float bfhi(unsigned w) { return __uint_as_float(w & 0xffff0000u); }
; #define LASP __attribute__((address_space(3)))
; __device__ __forceinline__ void attn_phase_mfma(const Ctx& c, unsigned char* lds_raw, bool do_store) {
;     ...
;         const AttnU A = attn_decode(u);
;     ...
;         const int iq = i0 + 32 * wave + rq, posq = r + d * iq;
;         const size_t tokq = (size_t)b * SEQ + posq;
;         bf16_t* qrow = c.Z + tokq * DIN + ZQ + hh * 64;
;         bf16x8 qf[4];
;         {
;             const u32x4 q0 = qn[0], q1 = qn[1], q2 = qn[2], q3 = qn[3];
;             const h16x8 cav = tq[0], cbv = tq[1], sav = tq[2], sbv = tq[3];
;             const float sc = 0.125f * 1.44269504f;
;             u32x4 o0, o1, o2, o3;
;     #pragma unroll
;             for (int e = 0; e < 4; ++e) {
;                 const float ca_0 = (float)cav[2 * e], ca_1 = (float)cav[2 * e + 1], sa_0 = (float)sav[2 * e], sa_1 = (float)sav[2 * e + 1];
;                 const float cb_0 = (float)cbv[2 * e], cb_1 = (float)cbv[2 * e + 1], sb_0 = (float)sbv[2 * e], sb_1 = (float)sbv[2 * e + 1];
;                 const float a0 = bflo(q0[e]), a1 = bfhi(q0[e]), b0 = bflo(q2[e]), b1 = bfhi(q2[e]);
;                 const float e0 = bflo(q1[e]), e1 = bfhi(q1[e]), f0 = bflo(q3[e]), f1 = bfhi(q3[e]);
;                 o0[e] = pk2((a0 * ca_0 - b0 * sa_0) * sc, (a1 * ca_1 - b1 * sa_1) * sc);
;                 o2[e] = pk2((b0 * ca_0 + a0 * sa_0) * sc, (b1 * ca_1 + a1 * sa_1) * sc);
;                 o1[e] = pk2((e0 * cb_0 - f0 * sb_0) * sc, (e1 * cb_1 - f1 * sb_1) * sc);
;                 o3[e] = pk2((f0 * cb_0 + e0 * sb_0) * sc, (f1 * cb_1 + e1 * sb_1) * sc);
;             }
;             qf[0] = __builtin_bit_cast(bf16x8, o0); qf[1] = __builtin_bit_cast(bf16x8, o1); qf[2] = __builtin_bit_cast(bf16x8, o2); qf[3] = __builtin_bit_cast(bf16x8, o3);
;         }
;     ...
;         for (int s4 = 0; s4 < 4; ++s4) {
;     #pragma unroll
;             for (int kb = 0; kb < 5; ++kb) {
;                 const int row = 32 * wave + 32 * kb + rq;
;                 const bf16x8 kf = *(const LASP bf16x8*)(Kt + row * 128 + (((2 * s4 + h) ^ (row & 7)) << 4));
;                 sacc[kb] = mfma32_g(kf, qf[s4], sacc[kb]);
.LBB0_1739:
	s_bfe_u32 s2, s1, 0x20004
	s_ashr_i32 s1, s0, 31
	s_lshl_b64 s[0:1], s[0:1], 12
	v_ashrrev_i32_e32 v59, 31, v58
	v_lshl_add_u64 v[108:109], s[0:1], 0, v[58:59]
	v_mov_b64_e32 v[34:35], s[92:93]
	v_cvt_f32_f16_sdwa v37, v26 dst_sel:DWORD dst_unused:UNUSED_PAD src0_sel:WORD_1
	v_cvt_f32_f16_e32 v36, v26
	v_mad_u64_u32 v[174:175], s[0:1], v108, s8, v[34:35]
	v_cvt_f32_f16_sdwa v35, v30 dst_sel:DWORD dst_unused:UNUSED_PAD src0_sel:WORD_1
	v_cvt_f32_f16_e32 v34, v30
	v_lshlrev_b32_e32 v38, 16, v10
	v_and_b32_e32 v39, 0xffff0000, v10
	v_lshlrev_b32_e32 v40, 16, v14
	v_and_b32_e32 v41, 0xffff0000, v14
	v_pk_mul_f32 v[42:43], v[40:41], v[36:37]
	v_pk_mul_f32 v[36:37], v[38:39], v[36:37]
	v_pk_fma_f32 v[42:43], v[38:39], v[34:35], v[42:43] neg_lo:[0,0,1] neg_hi:[0,0,1]
	v_pk_fma_f32 v[34:35], v[40:41], v[34:35], v[36:37]
	v_cvt_f32_f16_sdwa v37, v18 dst_sel:DWORD dst_unused:UNUSED_PAD src0_sel:WORD_1
	v_pk_mul_f32 v[34:35], v[34:35], s[72:73] op_sel_hi:[1,0]
	v_cvt_f32_f16_e32 v36, v18
	v_cvt_pk_bf16_f32 v150, v34, v35
	v_cvt_f32_f16_sdwa v35, v22 dst_sel:DWORD dst_unused:UNUSED_PAD src0_sel:WORD_1
	v_cvt_f32_f16_e32 v34, v22
	v_pk_mul_f32 v[42:43], v[42:43], s[72:73] op_sel_hi:[1,0]
	v_lshlrev_b32_e32 v38, 16, v2
	v_and_b32_e32 v39, 0xffff0000, v2
	v_lshlrev_b32_e32 v40, 16, v6
	v_and_b32_e32 v41, 0xffff0000, v6
	v_cvt_pk_bf16_f32 v224, v42, v43
	v_pk_mul_f32 v[42:43], v[40:41], v[36:37]
	v_pk_mul_f32 v[36:37], v[38:39], v[36:37]
	v_pk_fma_f32 v[42:43], v[38:39], v[34:35], v[42:43] neg_lo:[0,0,1] neg_hi:[0,0,1]
	v_pk_fma_f32 v[34:35], v[40:41], v[34:35], v[36:37]
	v_cvt_f32_f16_e32 v30, v27
	v_pk_mul_f32 v[34:35], v[34:35], s[72:73] op_sel_hi:[1,0]
	v_lshlrev_b32_e32 v14, 16, v15
	v_cvt_pk_bf16_f32 v154, v34, v35
	v_cvt_f32_f16_sdwa v35, v31 dst_sel:DWORD dst_unused:UNUSED_PAD src0_sel:WORD_1
	v_cvt_f32_f16_e32 v34, v31
	v_cvt_f32_f16_sdwa v31, v27 dst_sel:DWORD dst_unused:UNUSED_PAD src0_sel:WORD_1
	v_and_b32_e32 v15, 0xffff0000, v15
	v_lshlrev_b32_e32 v10, 16, v11
	v_and_b32_e32 v11, 0xffff0000, v11
	v_pk_mul_f32 v[26:27], v[14:15], v[30:31]
	v_lshlrev_b32_e32 v6, 16, v7
	v_pk_fma_f32 v[26:27], v[10:11], v[34:35], v[26:27] neg_lo:[0,0,1] neg_hi:[0,0,1]
	v_pk_mul_f32 v[10:11], v[10:11], v[30:31]
	v_and_b32_e32 v7, 0xffff0000, v7
	v_pk_fma_f32 v[10:11], v[14:15], v[34:35], v[10:11]
	v_cvt_f32_f16_sdwa v15, v19 dst_sel:DWORD dst_unused:UNUSED_PAD src0_sel:WORD_1
	v_pk_mul_f32 v[10:11], v[10:11], s[72:73] op_sel_hi:[1,0]
	v_cvt_f32_f16_e32 v14, v19
	v_cvt_pk_bf16_f32 v151, v10, v11
	v_cvt_f32_f16_sdwa v11, v23 dst_sel:DWORD dst_unused:UNUSED_PAD src0_sel:WORD_1
	v_cvt_f32_f16_e32 v10, v23
	v_lshlrev_b32_e32 v2, 16, v3
	v_and_b32_e32 v3, 0xffff0000, v3
	v_pk_mul_f32 v[18:19], v[6:7], v[14:15]
	v_pk_mul_f32 v[26:27], v[26:27], s[72:73] op_sel_hi:[1,0]
	v_pk_fma_f32 v[18:19], v[2:3], v[10:11], v[18:19] neg_lo:[0,0,1] neg_hi:[0,0,1]
	v_pk_mul_f32 v[2:3], v[2:3], v[14:15]
	v_pk_mul_f32 v[18:19], v[18:19], s[72:73] op_sel_hi:[1,0]
	v_pk_fma_f32 v[2:3], v[6:7], v[10:11], v[2:3]
	v_cvt_f32_f16_sdwa v7, v28 dst_sel:DWORD dst_unused:UNUSED_PAD src0_sel:WORD_1
	v_pk_mul_f32 v[2:3], v[2:3], s[72:73] op_sel_hi:[1,0]
	v_cvt_f32_f16_e32 v6, v28
	v_cvt_pk_bf16_f32 v155, v2, v3
	v_cvt_f32_f16_sdwa v3, v32 dst_sel:DWORD dst_unused:UNUSED_PAD src0_sel:WORD_1
	v_cvt_f32_f16_e32 v2, v32
	v_lshlrev_b32_e32 v14, 16, v16
	v_and_b32_e32 v15, 0xffff0000, v16
	v_cvt_pk_bf16_f32 v229, v18, v19
	v_lshlrev_b32_e32 v10, 16, v12
	v_and_b32_e32 v11, 0xffff0000, v12
	v_pk_mul_f32 v[18:19], v[14:15], v[6:7]
	v_cvt_pk_bf16_f32 v225, v26, v27
	v_pk_fma_f32 v[18:19], v[10:11], v[2:3], v[18:19] neg_lo:[0,0,1] neg_hi:[0,0,1]
	v_cvt_f32_f16_sdwa v23, v29 dst_sel:DWORD dst_unused:UNUSED_PAD src0_sel:WORD_1
	v_cvt_f32_f16_e32 v22, v29
	ds_read_b128 v[26:29], v216
	v_pk_mul_f32 v[18:19], v[18:19], s[72:73] op_sel_hi:[1,0]
	v_lshlrev_b32_e32 v16, 16, v17
	v_cvt_pk_bf16_f32 v226, v18, v19
	v_cvt_f32_f16_sdwa v19, v33 dst_sel:DWORD dst_unused:UNUSED_PAD src0_sel:WORD_1
	v_cvt_f32_f16_e32 v18, v33
	v_and_b32_e32 v17, 0xffff0000, v17
	v_pk_mul_f32 v[6:7], v[10:11], v[6:7]
	v_lshlrev_b32_e32 v30, 16, v13
	v_and_b32_e32 v31, 0xffff0000, v13
	v_pk_mul_f32 v[10:11], v[16:17], v[22:23]
	v_pk_fma_f32 v[2:3], v[14:15], v[2:3], v[6:7]
	v_pk_fma_f32 v[10:11], v[30:31], v[18:19], v[10:11] neg_lo:[0,0,1] neg_hi:[0,0,1]
	v_pk_mul_f32 v[42:43], v[42:43], s[72:73] op_sel_hi:[1,0]
	v_pk_mul_f32 v[10:11], v[10:11], s[72:73] op_sel_hi:[1,0]
	v_pk_mul_f32 v[2:3], v[2:3], s[72:73] op_sel_hi:[1,0]
	v_cvt_pk_bf16_f32 v227, v10, v11
	v_cvt_f32_f16_sdwa v7, v20 dst_sel:DWORD dst_unused:UNUSED_PAD src0_sel:WORD_1
	v_cvt_f32_f16_e32 v6, v20
	s_waitcnt lgkmcnt(0)
	v_mfma_f32_32x32x16_bf16 v[66:81], v[26:29], v[224:227], 0
	ds_read_b128 v[10:13], v216 offset:4096
	v_cvt_pk_bf16_f32 v228, v42, v43
	v_cvt_pk_bf16_f32 v152, v2, v3
	v_cvt_f32_f16_sdwa v3, v24 dst_sel:DWORD dst_unused:UNUSED_PAD src0_sel:WORD_1
	v_cvt_f32_f16_e32 v2, v24
	v_lshlrev_b32_e32 v14, 16, v4
	s_waitcnt lgkmcnt(0)
	v_mfma_f32_32x32x16_bf16 v[50:65], v[10:13], v[224:227], 0
	ds_read_b128 v[10:13], v216 offset:8192
	v_and_b32_e32 v15, 0xffff0000, v4
	v_lshlrev_b32_e32 v26, 16, v8
	v_and_b32_e32 v27, 0xffff0000, v8
	v_pk_mul_f32 v[28:29], v[26:27], v[6:7]
	v_pk_mul_f32 v[6:7], v[14:15], v[6:7]
	s_waitcnt lgkmcnt(0)
; #define LASP __attribute__((address_space(3)))
; __device__ __forceinline__ void attn_phase_mfma(const Ctx& c, unsigned char* lds_raw, bool do_store) {
;     ...
;         for (int s4 = 0; s4 < 4; ++s4) {
;     #pragma unroll
;             for (int kb = 0; kb < 5; ++kb) {
;                 const int row = 32 * wave + 32 * kb + rq;
;                 const bf16x8 kf = *(const LASP bf16x8*)(Kt + row * 128 + (((2 * s4 + h) ^ (row & 7)) << 4));
;                 sacc[kb] = mfma32_g(kf, qf[s4], sacc[kb]);
;             }
;             __builtin_amdgcn_sched_barrier(0);
;         }
;         asm volatile("s_nop 15\n\ts_nop 15" : "+v"(sacc[0]), "+v"(sacc[1]), "+v"(sacc[2]), "+v"(sacc[3]), "+v"(sacc[4]));
;         const int jbase = i0 - 64 + 32 * wave;
;         float mx = -1e30f;
;     #pragma unroll
;         for (int kb = 0; kb < 5; ++kb)
;     #pragma unroll
;             for (int e = 0; e < 16; ++e) {
;                 const int row = (e & 3) + 8 * (e >> 2) + 4 * h, rel = 32 * kb + row - rq, j = jbase + 32 * kb + row;
;                 const bool valid = (rel >= 0) && (rel <= 128) && (j >= 0) && (j < L);
;                 const float sv = valid ? sacc[kb][e] : -1e30f;
;                 sacc[kb][e] = sv; mx = fmaxf(mx, sv);
;             }
	v_mfma_f32_32x32x16_bf16 v[34:49], v[10:13], v[224:227], 0
	ds_read_b128 v[10:13], v216 offset:12288
	v_pk_fma_f32 v[28:29], v[14:15], v[2:3], v[28:29] neg_lo:[0,0,1] neg_hi:[0,0,1]
	v_pk_fma_f32 v[2:3], v[26:27], v[2:3], v[6:7]
	v_pk_mul_f32 v[28:29], v[28:29], s[72:73] op_sel_hi:[1,0]
	v_pk_mul_f32 v[2:3], v[2:3], s[72:73] op_sel_hi:[1,0]
	v_cvt_pk_bf16_f32 v230, v28, v29
	v_cvt_pk_bf16_f32 v156, v2, v3
	v_pk_mul_f32 v[2:3], v[30:31], v[22:23]
	v_cvt_f32_f16_sdwa v7, v21 dst_sel:DWORD dst_unused:UNUSED_PAD src0_sel:WORD_1
	v_pk_fma_f32 v[2:3], v[16:17], v[18:19], v[2:3]
	v_cvt_f32_f16_e32 v6, v21
	v_pk_mul_f32 v[2:3], v[2:3], s[72:73] op_sel_hi:[1,0]
	v_lshlrev_b32_e32 v8, 16, v9
	v_cvt_pk_bf16_f32 v153, v2, v3
	v_cvt_f32_f16_sdwa v3, v25 dst_sel:DWORD dst_unused:UNUSED_PAD src0_sel:WORD_1
	v_cvt_f32_f16_e32 v2, v25
	s_waitcnt lgkmcnt(0)
	v_mfma_f32_32x32x16_bf16 v[18:33], v[10:13], v[224:227], 0
	ds_read_b128 v[232:235], v216 offset:16384
	v_and_b32_e32 v9, 0xffff0000, v9
	v_lshlrev_b32_e32 v4, 16, v5
	v_and_b32_e32 v5, 0xffff0000, v5
	v_pk_mul_f32 v[14:15], v[8:9], v[6:7]
	s_lshl_b32 s0, s88, 8
	s_lshl_b32 s1, s2, 6
	v_pk_fma_f32 v[14:15], v[4:5], v[2:3], v[14:15] neg_lo:[0,0,1] neg_hi:[0,0,1]
	v_pk_mul_f32 v[4:5], v[4:5], v[6:7]
	s_or_b32 s0, s1, s0
	v_pk_fma_f32 v[2:3], v[8:9], v[2:3], v[4:5]
	v_mad_i32_i24 v175, v109, s8, v175
	s_ashr_i32 s1, s0, 31
	v_pk_mul_f32 v[10:11], v[14:15], s[72:73] op_sel_hi:[1,0]
	v_pk_mul_f32 v[2:3], v[2:3], s[72:73] op_sel_hi:[1,0]
	v_cvt_pk_bf16_f32 v231, v10, v11
	v_cvt_pk_bf16_f32 v157, v2, v3
	s_lshr_b32 s3, 0x1000, s96
	v_lshl_add_u64 v[174:175], s[0:1], 1, v[174:175]
	s_waitcnt lgkmcnt(0)
	v_mfma_f32_32x32x16_bf16 v[2:17], v[232:235], v[224:227], 0
	ds_read_b128 v[224:227], v217
	ds_read_b128 v[250:253], v217 offset:4096
	s_waitcnt lgkmcnt(1)
	v_mfma_f32_32x32x16_bf16 v[66:81], v[224:227], v[228:231], v[66:81]
	ds_read_b128 v[224:227], v217 offset:8192
	s_waitcnt lgkmcnt(1)
	v_mfma_f32_32x32x16_bf16 v[50:65], v[250:253], v[228:231], v[50:65]
	ds_read_b128 v[250:253], v217 offset:12288
	s_waitcnt lgkmcnt(1)
	v_mfma_f32_32x32x16_bf16 v[34:49], v[224:227], v[228:231], v[34:49]
	ds_read_b128 v[224:227], v217 offset:16384
	s_waitcnt lgkmcnt(1)
	v_mfma_f32_32x32x16_bf16 v[18:33], v[250:253], v[228:231], v[18:33]
	s_waitcnt lgkmcnt(0)
	v_mfma_f32_32x32x16_bf16 v[2:17], v[224:227], v[228:231], v[2:17]
	ds_read_b128 v[224:227], v218
	ds_read_b128 v[250:253], v218 offset:4096
	s_waitcnt lgkmcnt(1)
	v_mfma_f32_32x32x16_bf16 v[66:81], v[224:227], v[150:153], v[66:81]
	ds_read_b128 v[224:227], v218 offset:8192
	s_waitcnt lgkmcnt(1)
	v_mfma_f32_32x32x16_bf16 v[50:65], v[250:253], v[150:153], v[50:65]
	ds_read_b128 v[250:253], v218 offset:12288
	s_waitcnt lgkmcnt(1)
	v_mfma_f32_32x32x16_bf16 v[34:49], v[224:227], v[150:153], v[34:49]
	ds_read_b128 v[224:227], v218 offset:16384
	s_waitcnt lgkmcnt(1)
	v_mfma_f32_32x32x16_bf16 v[18:33], v[250:253], v[150:153], v[18:33]
	s_waitcnt lgkmcnt(0)
	v_mfma_f32_32x32x16_bf16 v[2:17], v[224:227], v[150:153], v[2:17]
	ds_read_b128 v[150:153], v219
	ds_read_b128 v[250:253], v219 offset:4096
	s_waitcnt lgkmcnt(1)
	v_mfma_f32_32x32x16_bf16 v[66:81], v[150:153], v[154:157], v[66:81]
	ds_read_b128 v[150:153], v219 offset:8192
	s_waitcnt lgkmcnt(1)
	v_mfma_f32_32x32x16_bf16 v[50:65], v[250:253], v[154:157], v[50:65]
	ds_read_b128 v[250:253], v219 offset:12288
	s_waitcnt lgkmcnt(1)
	v_mfma_f32_32x32x16_bf16 v[34:49], v[150:153], v[154:157], v[34:49]
	ds_read_b128 v[150:153], v219 offset:16384
	s_waitcnt lgkmcnt(1)
	v_mfma_f32_32x32x16_bf16 v[18:33], v[250:253], v[154:157], v[18:33]
	s_waitcnt lgkmcnt(0)
	v_mfma_f32_32x32x16_bf16 v[2:17], v[150:153], v[154:157], v[2:17]
	s_add_i32 s0, s89, s73
	s_cmp_gt_i32 s0, -1
	v_readlane_b32 s12, v255, 17
	s_cselect_b64 s[10:11], -1, 0
	v_or_b32_e32 v107, s0, v166
	v_readlane_b32 s13, v255, 18
	s_and_b64 s[12:13], s[12:13], s[10:11]
	v_cmp_gt_i32_e32 vcc, s3, v107
	s_nop 15
	s_nop 15
	s_and_b64 vcc, s[12:13], vcc
	v_readlane_b32 s12, v255, 19
	v_cndmask_b32_e32 v107, v222, v66, vcc
	v_or_b32_e32 v66, s0, v184
	v_readlane_b32 s13, v255, 20
	s_and_b64 s[12:13], s[12:13], s[10:11]
	v_cmp_gt_i32_e32 vcc, s3, v66
	s_and_b64 vcc, s[12:13], vcc
	v_readlane_b32 s12, v255, 21
	v_or_b32_e32 v150, s0, v185
	v_readlane_b32 s13, v255, 22
	v_cndmask_b32_e32 v67, v222, v67, vcc
	s_and_b64 s[12:13], s[12:13], s[10:11]
	v_cmp_gt_i32_e32 vcc, s3, v150
	s_and_b64 vcc, s[12:13], vcc
	v_readlane_b32 s12, v255, 23
	v_or_b32_e32 v150, s0, v186
	v_readlane_b32 s13, v255, 24
	v_cndmask_b32_e32 v68, v222, v68, vcc
	s_and_b64 s[12:13], s[12:13], s[10:11]
	v_cmp_gt_i32_e32 vcc, s3, v150
	s_and_b64 vcc, s[12:13], vcc
	v_or_b32_e32 v150, s0, v187
	v_cndmask_b32_e32 v69, v222, v69, vcc
	s_and_b64 s[12:13], s[14:15], s[10:11]
	v_cmp_gt_i32_e32 vcc, s3, v150
	s_and_b64 vcc, s[12:13], vcc
	v_or_b32_e32 v150, s0, v188
	v_cndmask_b32_e32 v70, v222, v70, vcc
	s_and_b64 s[12:13], s[16:17], s[10:11]
	v_cmp_gt_i32_e32 vcc, s3, v150
	s_and_b64 vcc, s[12:13], vcc
	v_or_b32_e32 v150, s0, v189
	v_cndmask_b32_e32 v71, v222, v71, vcc
	s_and_b64 s[12:13], s[18:19], s[10:11]
	v_cmp_gt_i32_e32 vcc, s3, v150
	s_and_b64 vcc, s[12:13], vcc
	v_or_b32_e32 v150, s0, v190
	v_cndmask_b32_e32 v72, v222, v72, vcc
	s_and_b64 s[12:13], s[20:21], s[10:11]
	v_cmp_gt_i32_e32 vcc, s3, v150
	s_and_b64 vcc, s[12:13], vcc
	v_or_b32_e32 v150, s0, v191
	v_cndmask_b32_e32 v73, v222, v73, vcc
	s_and_b64 s[12:13], s[22:23], s[10:11]
	v_cmp_gt_i32_e32 vcc, s3, v150
	s_and_b64 vcc, s[12:13], vcc
	v_or_b32_e32 v150, s0, v192
	v_cndmask_b32_e32 v74, v222, v74, vcc
	s_and_b64 s[12:13], s[24:25], s[10:11]
; __device__ __forceinline__ void attn_phase_mfma(const Ctx& c, unsigned char* lds_raw, bool do_store) {
;     ...
;         const int jbase = i0 - 64 + 32 * wave;
;         float mx = -1e30f;
;     #pragma unroll
;         for (int kb = 0; kb < 5; ++kb)
;     #pragma unroll
;             for (int e = 0; e < 16; ++e) {
;                 const int row = (e & 3) + 8 * (e >> 2) + 4 * h, rel = 32 * kb + row - rq, j = jbase + 32 * kb + row;
;                 const bool valid = (rel >= 0) && (rel <= 128) && (j >= 0) && (j < L);
;                 const float sv = valid ? sacc[kb][e] : -1e30f;
;                 sacc[kb][e] = sv; mx = fmaxf(mx, sv);
;             }
	v_cmp_gt_i32_e32 vcc, s3, v150
	s_and_b64 vcc, s[12:13], vcc
	v_or_b32_e32 v150, s0, v193
	v_cndmask_b32_e32 v75, v222, v75, vcc
	s_and_b64 s[12:13], s[26:27], s[10:11]
	v_cmp_gt_i32_e32 vcc, s3, v150
	s_and_b64 vcc, s[12:13], vcc
	v_or_b32_e32 v150, s0, v194
	v_cndmask_b32_e32 v76, v222, v76, vcc
	s_and_b64 s[12:13], s[28:29], s[10:11]
	v_cmp_gt_i32_e32 vcc, s3, v150
	s_and_b64 vcc, s[12:13], vcc
	v_or_b32_e32 v150, s0, v195
	v_cndmask_b32_e32 v77, v222, v77, vcc
	s_and_b64 s[12:13], s[30:31], s[10:11]
	v_cmp_gt_i32_e32 vcc, s3, v150
	s_and_b64 vcc, s[12:13], vcc
	v_or_b32_e32 v150, s0, v196
	v_cndmask_b32_e32 v78, v222, v78, vcc
	s_and_b64 s[12:13], s[34:35], s[10:11]
	v_cmp_gt_i32_e32 vcc, s3, v150
	s_and_b64 vcc, s[12:13], vcc
	v_or_b32_e32 v150, s0, v197
	v_cndmask_b32_e32 v79, v222, v79, vcc
	s_and_b64 s[12:13], s[36:37], s[10:11]
	v_cmp_gt_i32_e32 vcc, s3, v150
	s_and_b64 vcc, s[12:13], vcc
	v_or_b32_e32 v150, s0, v198
	s_mov_b32 s1, 0xf149f2ca
	v_cndmask_b32_e32 v80, v222, v80, vcc
	s_and_b64 s[10:11], s[38:39], s[10:11]
	v_cmp_gt_i32_e32 vcc, s3, v150
	v_max3_f32 v66, v107, s1, v67
	s_and_b64 vcc, s[10:11], vcc
	s_add_i32 s1, s0, 32
	s_cmpk_gt_i32 s0, 0xffdf
	v_or_b32_e32 v150, s1, v166
	v_cndmask_b32_e32 v81, v222, v81, vcc
	s_cselect_b64 s[10:11], -1, 0
	v_cmp_gt_i32_e32 vcc, s3, v150
	s_and_b64 vcc, s[10:11], vcc
	s_add_i32 s9, s9, s73
	v_cndmask_b32_e32 v150, v222, v50, vcc
	v_or_b32_e32 v50, s1, v184
	v_cmp_gt_i32_e32 vcc, s3, v50
	s_and_b64 vcc, s[10:11], vcc
	v_max3_f32 v66, v66, v68, v69
	v_cndmask_b32_e32 v151, v222, v51, vcc
	v_or_b32_e32 v51, s1, v185
	v_cmp_gt_i32_e32 vcc, s3, v51
	s_and_b64 vcc, s[10:11], vcc
	v_or_b32_e32 v51, s1, v186
	v_cndmask_b32_e32 v152, v222, v52, vcc
	v_cmp_gt_i32_e32 vcc, s3, v51
	s_and_b64 vcc, s[10:11], vcc
	v_or_b32_e32 v51, s1, v187
	v_cndmask_b32_e32 v153, v222, v53, vcc
	v_cmp_gt_i32_e32 vcc, s3, v51
	s_and_b64 vcc, s[10:11], vcc
	v_or_b32_e32 v51, s1, v188
	v_cndmask_b32_e32 v154, v222, v54, vcc
	v_cmp_gt_i32_e32 vcc, s3, v51
	s_and_b64 vcc, s[10:11], vcc
	v_or_b32_e32 v51, s1, v189
	v_cndmask_b32_e32 v155, v222, v55, vcc
	v_cmp_gt_i32_e32 vcc, s3, v51
	s_and_b64 vcc, s[10:11], vcc
	v_or_b32_e32 v51, s1, v190
	v_cndmask_b32_e32 v156, v222, v56, vcc
	v_cmp_gt_i32_e32 vcc, s3, v51
	s_and_b64 vcc, s[10:11], vcc
	v_or_b32_e32 v51, s1, v191
	v_cndmask_b32_e32 v157, v222, v57, vcc
	v_cmp_gt_i32_e32 vcc, s3, v51
	s_and_b64 vcc, s[10:11], vcc
	v_or_b32_e32 v51, s1, v192
	v_cndmask_b32_e32 v159, v222, v58, vcc
	v_cmp_gt_i32_e32 vcc, s3, v51
	s_and_b64 vcc, s[10:11], vcc
	v_or_b32_e32 v51, s1, v193
	v_cndmask_b32_e32 v169, v222, v59, vcc
	v_cmp_gt_i32_e32 vcc, s3, v51
	s_and_b64 vcc, s[10:11], vcc
	v_or_b32_e32 v51, s1, v194
	v_cndmask_b32_e32 v224, v222, v60, vcc
	v_cmp_gt_i32_e32 vcc, s3, v51
	s_and_b64 vcc, s[10:11], vcc
	v_or_b32_e32 v51, s1, v195
	v_cndmask_b32_e32 v225, v222, v61, vcc
	v_cmp_gt_i32_e32 vcc, s3, v51
	s_and_b64 vcc, s[10:11], vcc
	v_or_b32_e32 v51, s1, v196
	v_cndmask_b32_e32 v226, v222, v62, vcc
	v_cmp_gt_i32_e32 vcc, s3, v51
	s_and_b64 vcc, s[10:11], vcc
	v_or_b32_e32 v51, s1, v197
	v_cndmask_b32_e32 v227, v222, v63, vcc
	v_cmp_gt_i32_e32 vcc, s3, v51
	s_and_b64 vcc, s[10:11], vcc
	v_or_b32_e32 v51, s1, v198
	v_cndmask_b32_e32 v228, v222, v64, vcc
	v_cmp_gt_i32_e32 vcc, s3, v51
	s_and_b64 vcc, s[10:11], vcc
	s_cmp_gt_i32 s9, -1
	v_or_b32_e32 v51, s9, v166
	v_cndmask_b32_e32 v229, v222, v65, vcc
	s_cselect_b64 s[10:11], -1, 0
	v_cmp_gt_i32_e32 vcc, s3, v51
	s_and_b64 vcc, s[10:11], vcc
	s_add_i32 s1, s0, 0x60
	v_cndmask_b32_e32 v230, v222, v34, vcc
	v_or_b32_e32 v34, s9, v184
	v_cmp_gt_i32_e32 vcc, s3, v34
	s_and_b64 vcc, s[10:11], vcc
	v_max3_f32 v66, v66, v70, v71
	v_cndmask_b32_e32 v231, v222, v35, vcc
	v_or_b32_e32 v35, s9, v185
	v_cmp_gt_i32_e32 vcc, s3, v35
	s_and_b64 vcc, s[10:11], vcc
	v_or_b32_e32 v35, s9, v186
	v_cndmask_b32_e32 v232, v222, v36, vcc
	v_cmp_gt_i32_e32 vcc, s3, v35
	s_and_b64 vcc, s[10:11], vcc
	v_or_b32_e32 v35, s9, v187
	v_cndmask_b32_e32 v233, v222, v37, vcc
	v_cmp_gt_i32_e32 vcc, s3, v35
	s_and_b64 vcc, s[10:11], vcc
	v_or_b32_e32 v35, s9, v188
	v_cndmask_b32_e32 v234, v222, v38, vcc
	v_cmp_gt_i32_e32 vcc, s3, v35
	s_and_b64 vcc, s[10:11], vcc
	v_or_b32_e32 v35, s9, v189
	v_cndmask_b32_e32 v235, v222, v39, vcc
	v_cmp_gt_i32_e32 vcc, s3, v35
	s_and_b64 vcc, s[10:11], vcc
	v_or_b32_e32 v35, s9, v190
	v_cndmask_b32_e32 v236, v222, v40, vcc
	v_cmp_gt_i32_e32 vcc, s3, v35
	s_and_b64 vcc, s[10:11], vcc
	v_or_b32_e32 v35, s9, v191
	v_cndmask_b32_e32 v237, v222, v41, vcc
	v_cmp_gt_i32_e32 vcc, s3, v35
	s_and_b64 vcc, s[10:11], vcc
	v_or_b32_e32 v35, s9, v192
	v_cndmask_b32_e32 v238, v222, v42, vcc
	v_cmp_gt_i32_e32 vcc, s3, v35
	s_and_b64 vcc, s[10:11], vcc
	v_or_b32_e32 v35, s9, v193
	v_cndmask_b32_e32 v239, v222, v43, vcc
	v_cmp_gt_i32_e32 vcc, s3, v35
	s_and_b64 vcc, s[10:11], vcc
	v_or_b32_e32 v35, s9, v194
	v_cndmask_b32_e32 v240, v222, v44, vcc
	v_cmp_gt_i32_e32 vcc, s3, v35
	s_and_b64 vcc, s[10:11], vcc
	v_or_b32_e32 v35, s9, v195
	v_cndmask_b32_e32 v241, v222, v45, vcc
	v_cmp_gt_i32_e32 vcc, s3, v35
	s_and_b64 vcc, s[10:11], vcc
	v_or_b32_e32 v35, s9, v196
	v_cndmask_b32_e32 v242, v222, v46, vcc
	v_cmp_gt_i32_e32 vcc, s3, v35
	s_and_b64 vcc, s[10:11], vcc
	v_or_b32_e32 v35, s9, v197
	v_cndmask_b32_e32 v243, v222, v47, vcc
	v_cmp_gt_i32_e32 vcc, s3, v35
	s_and_b64 vcc, s[10:11], vcc
	v_or_b32_e32 v35, s9, v198
	v_cndmask_b32_e32 v244, v222, v48, vcc
	v_cmp_gt_i32_e32 vcc, s3, v35
	s_and_b64 vcc, s[10:11], vcc
	s_cmpk_gt_i32 s0, 0xff9f
	v_or_b32_e32 v35, s1, v166
	v_cndmask_b32_e32 v245, v222, v49, vcc
	s_cselect_b64 s[10:11], -1, 0
; __device__ __forceinline__ void attn_phase_mfma(const Ctx& c, unsigned char* lds_raw, bool do_store) {
;     ...
;         const int jbase = i0 - 64 + 32 * wave;
;         float mx = -1e30f;
;     #pragma unroll
;         for (int kb = 0; kb < 5; ++kb)
;     #pragma unroll
;             for (int e = 0; e < 16; ++e) {
;                 const int row = (e & 3) + 8 * (e >> 2) + 4 * h, rel = 32 * kb + row - rq, j = jbase + 32 * kb + row;
;                 const bool valid = (rel >= 0) && (rel <= 128) && (j >= 0) && (j < L);
;                 const float sv = valid ? sacc[kb][e] : -1e30f;
;                 sacc[kb][e] = sv; mx = fmaxf(mx, sv);
;             }
;         mx = fmaxf(mx, __shfl_xor(mx, 32));
	v_cmp_gt_i32_e32 vcc, s3, v35
	s_and_b64 vcc, s[10:11], vcc
	v_max3_f32 v66, v66, v72, v73
	v_cndmask_b32_e32 v246, v222, v18, vcc
	v_or_b32_e32 v18, s1, v184
	v_cmp_gt_i32_e32 vcc, s3, v18
	v_max3_f32 v66, v66, v74, v75
	s_and_b64 vcc, s[10:11], vcc
	v_max3_f32 v66, v66, v76, v77
	v_cndmask_b32_e32 v65, v222, v19, vcc
	v_or_b32_e32 v19, s1, v185
	v_max3_f32 v66, v66, v78, v79
	v_cmp_gt_i32_e32 vcc, s3, v19
	v_max3_f32 v66, v66, v80, v81
	s_and_b64 vcc, s[10:11], vcc
	v_or_b32_e32 v19, s1, v186
	v_max3_f32 v50, v66, v150, v151
	v_cndmask_b32_e32 v66, v222, v20, vcc
	v_cmp_gt_i32_e32 vcc, s3, v19
	s_and_b64 vcc, s[10:11], vcc
	v_or_b32_e32 v19, s1, v187
	v_cndmask_b32_e32 v63, v222, v21, vcc
	v_cmp_gt_i32_e32 vcc, s3, v19
	s_and_b64 vcc, s[10:11], vcc
	v_or_b32_e32 v19, s1, v188
	v_cndmask_b32_e32 v64, v222, v22, vcc
	v_cmp_gt_i32_e32 vcc, s3, v19
	s_and_b64 vcc, s[10:11], vcc
	v_or_b32_e32 v19, s1, v189
	v_cndmask_b32_e32 v61, v222, v23, vcc
	v_cmp_gt_i32_e32 vcc, s3, v19
	s_and_b64 vcc, s[10:11], vcc
	v_or_b32_e32 v19, s1, v190
	v_cndmask_b32_e32 v62, v222, v24, vcc
	v_cmp_gt_i32_e32 vcc, s3, v19
	s_and_b64 vcc, s[10:11], vcc
	v_or_b32_e32 v19, s1, v191
	v_cndmask_b32_e32 v59, v222, v25, vcc
	v_cmp_gt_i32_e32 vcc, s3, v19
	s_and_b64 vcc, s[10:11], vcc
	v_or_b32_e32 v19, s1, v192
	v_cndmask_b32_e32 v60, v222, v26, vcc
	v_cmp_gt_i32_e32 vcc, s3, v19
	s_and_b64 vcc, s[10:11], vcc
	v_or_b32_e32 v19, s1, v193
	v_cndmask_b32_e32 v57, v222, v27, vcc
	v_cmp_gt_i32_e32 vcc, s3, v19
	s_and_b64 vcc, s[10:11], vcc
	v_or_b32_e32 v19, s1, v194
	v_cndmask_b32_e32 v58, v222, v28, vcc
	v_cmp_gt_i32_e32 vcc, s3, v19
	s_and_b64 vcc, s[10:11], vcc
	v_or_b32_e32 v19, s1, v195
	v_cndmask_b32_e32 v55, v222, v29, vcc
	v_cmp_gt_i32_e32 vcc, s3, v19
	s_and_b64 vcc, s[10:11], vcc
	v_or_b32_e32 v19, s1, v196
	v_cndmask_b32_e32 v56, v222, v30, vcc
	v_cmp_gt_i32_e32 vcc, s3, v19
	s_and_b64 vcc, s[10:11], vcc
	v_or_b32_e32 v19, s1, v197
	v_cndmask_b32_e32 v53, v222, v31, vcc
	v_cmp_gt_i32_e32 vcc, s3, v19
	s_and_b64 vcc, s[10:11], vcc
	v_or_b32_e32 v19, s1, v198
	v_cndmask_b32_e32 v54, v222, v32, vcc
	v_cmp_gt_i32_e32 vcc, s3, v19
	s_and_b64 vcc, s[10:11], vcc
	s_add_i32 s9, s0, 0x80
	s_cmpk_gt_i32 s0, 0xff7f
	s_cselect_b64 s[0:1], -1, 0
	v_or_b32_e32 v19, s9, v166
	v_cndmask_b32_e32 v51, v222, v33, vcc
	s_and_b64 s[10:11], s[40:41], s[0:1]
	v_cmp_gt_i32_e32 vcc, s3, v19
	v_max3_f32 v50, v50, v152, v153
	s_and_b64 vcc, s[10:11], vcc
	v_max3_f32 v50, v50, v154, v155
	v_cndmask_b32_e32 v52, v222, v2, vcc
	v_or_b32_e32 v2, s9, v184
	v_max3_f32 v50, v50, v156, v157
	s_and_b64 s[10:11], s[42:43], s[0:1]
	v_cmp_gt_i32_e32 vcc, s3, v2
	v_max3_f32 v50, v50, v159, v169
	s_and_b64 vcc, s[10:11], vcc
	v_max3_f32 v50, v50, v224, v225
	v_cndmask_b32_e32 v49, v222, v3, vcc
	v_or_b32_e32 v3, s9, v185
	v_max3_f32 v50, v50, v226, v227
	s_and_b64 s[10:11], s[44:45], s[0:1]
	v_cmp_gt_i32_e32 vcc, s3, v3
	v_max3_f32 v50, v50, v228, v229
	s_and_b64 vcc, s[10:11], vcc
	v_or_b32_e32 v3, s9, v186
	v_max3_f32 v34, v50, v230, v231
	v_cndmask_b32_e32 v50, v222, v4, vcc
	s_and_b64 s[10:11], s[46:47], s[0:1]
	v_cmp_gt_i32_e32 vcc, s3, v3
	s_and_b64 vcc, s[10:11], vcc
	v_or_b32_e32 v3, s9, v187
	v_cndmask_b32_e32 v47, v222, v5, vcc
	s_and_b64 s[10:11], s[48:49], s[0:1]
	v_cmp_gt_i32_e32 vcc, s3, v3
	s_and_b64 vcc, s[10:11], vcc
	v_or_b32_e32 v3, s9, v188
	v_cndmask_b32_e32 v48, v222, v6, vcc
	s_and_b64 s[10:11], s[50:51], s[0:1]
	v_cmp_gt_i32_e32 vcc, s3, v3
	s_and_b64 vcc, s[10:11], vcc
	v_or_b32_e32 v3, s9, v189
	v_max3_f32 v34, v34, v232, v233
	v_cndmask_b32_e32 v45, v222, v7, vcc
	s_and_b64 s[10:11], s[52:53], s[0:1]
	v_cmp_gt_i32_e32 vcc, s3, v3
	v_max3_f32 v34, v34, v234, v235
	s_and_b64 vcc, s[10:11], vcc
	v_or_b32_e32 v3, s9, v190
	v_max3_f32 v34, v34, v236, v237
	v_cndmask_b32_e32 v46, v222, v8, vcc
	s_and_b64 s[10:11], s[54:55], s[0:1]
	v_cmp_gt_i32_e32 vcc, s3, v3
	v_max3_f32 v34, v34, v238, v239
	s_and_b64 vcc, s[10:11], vcc
	v_or_b32_e32 v3, s9, v191
	v_max3_f32 v34, v34, v240, v241
	v_cndmask_b32_e32 v43, v222, v9, vcc
	s_and_b64 s[10:11], s[56:57], s[0:1]
	v_cmp_gt_i32_e32 vcc, s3, v3
	v_max3_f32 v34, v34, v242, v243
	s_and_b64 vcc, s[10:11], vcc
	v_or_b32_e32 v3, s9, v192
	v_max3_f32 v34, v34, v244, v245
	v_cndmask_b32_e32 v44, v222, v10, vcc
	s_and_b64 s[10:11], s[58:59], s[0:1]
	v_cmp_gt_i32_e32 vcc, s3, v3
	v_max3_f32 v18, v34, v246, v65
	s_and_b64 vcc, s[10:11], vcc
	v_or_b32_e32 v3, s9, v193
	v_max3_f32 v18, v18, v66, v63
	v_cndmask_b32_e32 v41, v222, v11, vcc
	s_and_b64 s[10:11], s[60:61], s[0:1]
	v_cmp_gt_i32_e32 vcc, s3, v3
	v_max3_f32 v18, v18, v64, v61
	s_and_b64 vcc, s[10:11], vcc
	v_or_b32_e32 v3, s9, v194
	v_max3_f32 v18, v18, v62, v59
	v_cndmask_b32_e32 v42, v222, v12, vcc
	s_and_b64 s[10:11], s[62:63], s[0:1]
	v_cmp_gt_i32_e32 vcc, s3, v3
	v_max3_f32 v18, v18, v60, v57
	s_and_b64 vcc, s[10:11], vcc
	v_or_b32_e32 v3, s9, v195
	v_max3_f32 v18, v18, v58, v55
	v_cndmask_b32_e32 v39, v222, v13, vcc
	s_and_b64 s[10:11], s[64:65], s[0:1]
	v_cmp_gt_i32_e32 vcc, s3, v3
	v_max3_f32 v18, v18, v56, v53
	s_and_b64 vcc, s[10:11], vcc
	v_or_b32_e32 v3, s9, v196
	v_max3_f32 v18, v18, v54, v51
	v_cndmask_b32_e32 v40, v222, v14, vcc
	s_and_b64 s[10:11], s[66:67], s[0:1]
	v_cmp_gt_i32_e32 vcc, s3, v3
	v_max3_f32 v2, v18, v52, v49
	s_and_b64 vcc, s[10:11], vcc
	v_or_b32_e32 v3, s9, v197
	v_max3_f32 v2, v2, v50, v47
	v_cndmask_b32_e32 v36, v222, v15, vcc
	s_and_b64 s[10:11], s[68:69], s[0:1]
	v_cmp_gt_i32_e32 vcc, s3, v3
	v_max3_f32 v2, v2, v48, v45
	s_and_b64 vcc, s[10:11], vcc
	v_or_b32_e32 v3, s9, v198
	v_max3_f32 v2, v2, v46, v43
	v_cndmask_b32_e32 v37, v222, v16, vcc
	s_and_b64 s[0:1], s[70:71], s[0:1]
	v_cmp_gt_i32_e32 vcc, s3, v3
	v_and_b32_e32 v4, 64, v220
	v_max3_f32 v2, v2, v44, v41
	s_and_b64 vcc, s[0:1], vcc
	v_xor_b32_e32 v3, 32, v220
	v_add_u32_e32 v4, 64, v4
	v_max3_f32 v2, v2, v42, v39
	v_cndmask_b32_e32 v38, v222, v17, vcc
	v_cmp_lt_i32_e32 vcc, v3, v4
	v_max3_f32 v2, v2, v40, v36
	v_max3_f32 v2, v2, v37, v38
	v_cndmask_b32_e32 v3, v220, v3, vcc
	v_lshlrev_b32_e32 v35, 2, v3
	ds_bpermute_b32 v3, v35, v2
	s_waitcnt lgkmcnt(0)
; #define LASP __attribute__((address_space(3)))
; __device__ __forceinline__ unsigned cvtpk(float lo, float hi) { return pk2(lo, hi); }
; __device__ __forceinline__ void attn_phase_mfma(const Ctx& c, unsigned char* lds_raw, bool do_store) {
;     ...
;         float lsum = 0.f;
;     #pragma unroll
;         for (int kb = 0; kb < 5; ++kb)
;     #pragma unroll
;             for (int e = 0; e < 16; ++e) { const float p = __builtin_amdgcn_exp2f(sacc[kb][e] - mx); sacc[kb][e] = p; lsum += p; }
;         lsum += __shfl_xor(lsum, 32);
;         f32x16 oacc[2];
;     #pragma unroll
;         for (int db = 0; db < 2; ++db)
;     #pragma unroll
;             for (int e = 0; e < 16; ++e) oacc[db][e] = 0.f;
;     #pragma unroll
;         for (int kb = 0; kb < 5; ++kb)
;     #pragma unroll
;             for (int s2 = 0; s2 < 2; ++s2) {
;                 u32x4 pw;
;     #pragma unroll
;                 for (int e = 0; e < 4; ++e) pw[e] = cvtpk(sacc[kb][8 * s2 + 2 * e], sacc[kb][8 * s2 + 2 * e + 1]);
;                 const bf16x8 pf = __builtin_bit_cast(bf16x8, pw);
;                 const int kp = (32 * wave + 32 * kb + 16 * s2 + 4 * h) >> 1;
;     #pragma unroll
;                 for (int db = 0; db < 2; ++db) {
;                     const LASP unsigned* vp = Vt + (32 * db + rq) * 194 + kp;
;                     const u32x2 g0 = *(const LASP u32x2*)vp, g1 = *(const LASP u32x2*)(vp + 4);
;                     const u32x4 aw = (u32x4){g0.x, g0.y, g1.x, g1.y};
;                     oacc[db] = mfma32_g(__builtin_bit_cast(bf16x8, aw), pf, oacc[db]);
;                 }
;             }
	v_max_f32_e32 v3, v3, v3
	v_max_f32_e32 v34, v2, v3
	v_sub_f32_e32 v2, v107, v34
	v_exp_f32_e32 v6, v2
	v_sub_f32_e32 v2, v67, v34
	v_exp_f32_e32 v7, v2
	v_sub_f32_e32 v2, v68, v34
	v_exp_f32_e32 v8, v2
	v_sub_f32_e32 v3, v69, v34
	v_exp_f32_e32 v9, v3
	v_sub_f32_e32 v3, v70, v34
	v_add_f32_e32 v2, 0, v6
	v_exp_f32_e32 v10, v3
	v_sub_f32_e32 v3, v71, v34
	v_add_f32_e32 v2, v7, v2
	v_exp_f32_e32 v11, v3
	v_sub_f32_e32 v3, v72, v34
	v_add_f32_e32 v2, v8, v2
	v_exp_f32_e32 v12, v3
	v_sub_f32_e32 v3, v73, v34
	v_add_f32_e32 v2, v9, v2
	v_exp_f32_e32 v13, v3
	v_sub_f32_e32 v3, v74, v34
	v_add_f32_e32 v2, v10, v2
	v_exp_f32_e32 v67, v3
	v_sub_f32_e32 v3, v75, v34
	v_add_f32_e32 v2, v11, v2
	v_exp_f32_e32 v107, v3
	v_sub_f32_e32 v3, v76, v34
	v_add_f32_e32 v2, v12, v2
	v_exp_f32_e32 v76, v3
	v_sub_f32_e32 v3, v77, v34
	v_add_f32_e32 v2, v13, v2
	v_exp_f32_e32 v77, v3
	v_sub_f32_e32 v3, v78, v34
	v_add_f32_e32 v2, v67, v2
	v_exp_f32_e32 v78, v3
	v_sub_f32_e32 v3, v79, v34
	v_add_f32_e32 v2, v107, v2
	v_exp_f32_e32 v79, v3
	v_sub_f32_e32 v3, v80, v34
	v_add_f32_e32 v2, v76, v2
	v_exp_f32_e32 v80, v3
	v_sub_f32_e32 v3, v81, v34
	v_add_f32_e32 v2, v77, v2
	v_exp_f32_e32 v81, v3
	v_sub_f32_e32 v3, v150, v34
	v_add_f32_e32 v2, v78, v2
	v_exp_f32_e32 v150, v3
	v_sub_f32_e32 v3, v151, v34
	v_add_f32_e32 v2, v79, v2
	v_exp_f32_e32 v151, v3
	v_sub_f32_e32 v3, v152, v34
	v_add_f32_e32 v2, v80, v2
	v_exp_f32_e32 v152, v3
	v_sub_f32_e32 v3, v153, v34
	v_add_f32_e32 v2, v81, v2
	v_exp_f32_e32 v153, v3
	v_sub_f32_e32 v3, v154, v34
	v_add_f32_e32 v2, v150, v2
	v_exp_f32_e32 v154, v3
	v_sub_f32_e32 v3, v155, v34
	v_add_f32_e32 v2, v151, v2
	v_exp_f32_e32 v155, v3
	v_sub_f32_e32 v3, v156, v34
	v_add_f32_e32 v2, v152, v2
	v_exp_f32_e32 v156, v3
	v_sub_f32_e32 v3, v157, v34
	v_add_f32_e32 v2, v153, v2
	v_exp_f32_e32 v157, v3
	v_sub_f32_e32 v3, v159, v34
	v_add_f32_e32 v2, v154, v2
	v_exp_f32_e32 v159, v3
	v_sub_f32_e32 v3, v169, v34
	v_add_f32_e32 v2, v155, v2
	v_exp_f32_e32 v169, v3
	v_sub_f32_e32 v3, v224, v34
	v_add_f32_e32 v2, v156, v2
	v_exp_f32_e32 v224, v3
	v_sub_f32_e32 v3, v225, v34
	v_add_f32_e32 v2, v157, v2
	v_exp_f32_e32 v225, v3
	v_sub_f32_e32 v3, v226, v34
	v_add_f32_e32 v2, v159, v2
	v_exp_f32_e32 v226, v3
	v_sub_f32_e32 v3, v227, v34
	v_add_f32_e32 v2, v169, v2
	v_exp_f32_e32 v227, v3
	v_sub_f32_e32 v3, v228, v34
	v_add_f32_e32 v2, v224, v2
	v_exp_f32_e32 v228, v3
	v_sub_f32_e32 v3, v229, v34
	v_add_f32_e32 v2, v225, v2
	v_exp_f32_e32 v229, v3
	v_sub_f32_e32 v3, v230, v34
	v_add_f32_e32 v2, v226, v2
	v_exp_f32_e32 v230, v3
	v_sub_f32_e32 v3, v231, v34
	v_add_f32_e32 v2, v227, v2
	v_exp_f32_e32 v231, v3
	v_sub_f32_e32 v3, v232, v34
	v_add_f32_e32 v2, v228, v2
	v_exp_f32_e32 v232, v3
	v_sub_f32_e32 v3, v233, v34
	v_add_f32_e32 v2, v229, v2
	v_exp_f32_e32 v233, v3
	v_sub_f32_e32 v3, v234, v34
	v_add_f32_e32 v2, v230, v2
	v_exp_f32_e32 v234, v3
	v_sub_f32_e32 v3, v235, v34
	v_add_f32_e32 v2, v231, v2
	v_exp_f32_e32 v235, v3
	v_sub_f32_e32 v3, v236, v34
	v_add_f32_e32 v2, v232, v2
	v_exp_f32_e32 v236, v3
	v_sub_f32_e32 v3, v237, v34
	v_add_f32_e32 v2, v233, v2
	v_exp_f32_e32 v237, v3
	v_sub_f32_e32 v3, v238, v34
	v_add_f32_e32 v2, v234, v2
	v_exp_f32_e32 v238, v3
	v_sub_f32_e32 v3, v239, v34
	v_add_f32_e32 v2, v235, v2
	v_exp_f32_e32 v239, v3
	v_sub_f32_e32 v3, v240, v34
	v_add_f32_e32 v2, v236, v2
	v_exp_f32_e32 v240, v3
	v_add_f32_e32 v2, v237, v2
	v_add_f32_e32 v2, v238, v2
	v_add_f32_e32 v2, v239, v2
	v_add_f32_e32 v14, v240, v2
	v_add_u32_e32 v2, v200, v199
	v_add_u32_e32 v247, 0xc000, v2
	ds_read2_b64 v[2:5], v247 offset1:2
	v_cvt_pk_bf16_f32 v68, v6, v7
	v_cvt_pk_bf16_f32 v69, v8, v9
	v_cvt_pk_bf16_f32 v70, v10, v11
	v_cvt_pk_bf16_f32 v71, v12, v13
	v_sub_f32_e32 v15, v241, v34
	v_exp_f32_e32 v241, v15
	s_waitcnt lgkmcnt(0)
	v_mfma_f32_32x32x16_bf16 v[18:33], v[2:5], v[68:71], 0
	v_add_u32_e32 v2, v200, v201
	v_add_u32_e32 v248, 0xc000, v2
	ds_read2_b64 v[72:75], v248 offset1:2
	v_sub_f32_e32 v15, v242, v34
	v_exp_f32_e32 v242, v15
	v_sub_f32_e32 v2, v243, v34
	v_exp_f32_e32 v243, v2
	v_sub_f32_e32 v2, v244, v34
	v_exp_f32_e32 v244, v2
	v_add_f32_e32 v2, v241, v14
	v_add_f32_e32 v2, v242, v2
	v_add_f32_e32 v2, v243, v2
	v_add_f32_e32 v249, v244, v2
	s_waitcnt lgkmcnt(0)
	v_mfma_f32_32x32x16_bf16 v[2:17], v[72:75], v[68:71], 0
	ds_read2_b64 v[68:71], v247 offset0:4 offset1:6
	v_sub_f32_e32 v72, v245, v34
	v_exp_f32_e32 v245, v72
	v_sub_f32_e32 v72, v246, v34
	v_exp_f32_e32 v246, v72
	v_cvt_pk_bf16_f32 v72, v67, v107
	v_cvt_pk_bf16_f32 v73, v76, v77
	v_cvt_pk_bf16_f32 v74, v78, v79
	v_cvt_pk_bf16_f32 v75, v80, v81
	v_sub_f32_e32 v65, v65, v34
	v_exp_f32_e32 v76, v65
	s_waitcnt lgkmcnt(0)
	v_mfma_f32_32x32x16_bf16 v[18:33], v[68:71], v[72:75], v[18:33]
	ds_read2_b64 v[68:71], v248 offset0:4 offset1:6
	v_sub_f32_e32 v65, v66, v34
	v_exp_f32_e32 v77, v65
	v_add_f32_e32 v65, v245, v249
	v_add_f32_e32 v65, v246, v65
	v_add_f32_e32 v65, v76, v65
	v_add_f32_e32 v78, v77, v65
	v_add_u32_e32 v65, v202, v199
	v_add_u32_e32 v65, 0xc000, v65
	s_waitcnt lgkmcnt(0)
	v_mfma_f32_32x32x16_bf16 v[2:17], v[68:71], v[72:75], v[2:17]
	ds_read2_b64 v[66:69], v65 offset1:2
	v_sub_f32_e32 v63, v63, v34
	v_exp_f32_e32 v74, v63
	v_sub_f32_e32 v63, v64, v34
	v_exp_f32_e32 v75, v63
	v_add_u32_e32 v63, v202, v201
	v_cvt_pk_bf16_f32 v70, v150, v151
	v_cvt_pk_bf16_f32 v71, v152, v153
	v_cvt_pk_bf16_f32 v72, v154, v155
	v_cvt_pk_bf16_f32 v73, v156, v157
	v_add_u32_e32 v63, 0xc000, v63
	v_sub_f32_e32 v61, v61, v34
	s_waitcnt lgkmcnt(0)
; #define LASP __attribute__((address_space(3)))
; __device__ __forceinline__ unsigned cvtpk(float lo, float hi) { return pk2(lo, hi); }
; __device__ __forceinline__ void attn_phase_mfma(const Ctx& c, unsigned char* lds_raw, bool do_store) {
;     ...
;     #pragma unroll
;         for (int kb = 0; kb < 5; ++kb)
;     #pragma unroll
;             for (int s2 = 0; s2 < 2; ++s2) {
;                 u32x4 pw;
;     #pragma unroll
;                 for (int e = 0; e < 4; ++e) pw[e] = cvtpk(sacc[kb][8 * s2 + 2 * e], sacc[kb][8 * s2 + 2 * e + 1]);
;                 const bf16x8 pf = __builtin_bit_cast(bf16x8, pw);
;                 const int kp = (32 * wave + 32 * kb + 16 * s2 + 4 * h) >> 1;
;     #pragma unroll
;                 for (int db = 0; db < 2; ++db) {
;                     const LASP unsigned* vp = Vt + (32 * db + rq) * 194 + kp;
;                     const u32x2 g0 = *(const LASP u32x2*)vp, g1 = *(const LASP u32x2*)(vp + 4);
;                     const u32x4 aw = (u32x4){g0.x, g0.y, g1.x, g1.y};
;                     oacc[db] = mfma32_g(__builtin_bit_cast(bf16x8, aw), pf, oacc[db]);
;                 }
;             }
	v_mfma_f32_32x32x16_bf16 v[18:33], v[66:69], v[70:73], v[18:33]
	ds_read2_b64 v[64:67], v63 offset1:2
	v_exp_f32_e32 v79, v61
	v_sub_f32_e32 v61, v62, v34
	v_exp_f32_e32 v80, v61
	v_add_f32_e32 v61, v74, v78
	v_add_f32_e32 v61, v75, v61
	v_add_f32_e32 v61, v79, v61
	v_add_f32_e32 v78, v80, v61
	v_add_u32_e32 v61, v203, v199
	v_add_u32_e32 v61, 0xc000, v61
	s_waitcnt lgkmcnt(0)
	v_mfma_f32_32x32x16_bf16 v[2:17], v[64:67], v[70:73], v[2:17]
	ds_read2_b64 v[62:65], v61 offset1:2
	v_sub_f32_e32 v59, v59, v34
	v_exp_f32_e32 v70, v59
	v_sub_f32_e32 v59, v60, v34
	v_exp_f32_e32 v71, v59
	v_add_u32_e32 v59, v203, v201
	v_cvt_pk_bf16_f32 v66, v159, v169
	v_cvt_pk_bf16_f32 v67, v224, v225
	v_cvt_pk_bf16_f32 v68, v226, v227
	v_cvt_pk_bf16_f32 v69, v228, v229
	v_add_u32_e32 v59, 0xc000, v59
	v_sub_f32_e32 v57, v57, v34
	s_waitcnt lgkmcnt(0)
	v_mfma_f32_32x32x16_bf16 v[18:33], v[62:65], v[66:69], v[18:33]
	ds_read2_b64 v[60:63], v59 offset1:2
	v_exp_f32_e32 v72, v57
	v_sub_f32_e32 v57, v58, v34
	v_exp_f32_e32 v73, v57
	v_add_f32_e32 v57, v70, v78
	v_add_f32_e32 v57, v71, v57
	v_add_f32_e32 v57, v72, v57
	v_add_f32_e32 v78, v73, v57
	v_add_u32_e32 v57, v204, v199
	v_add_u32_e32 v57, 0xc000, v57
	s_waitcnt lgkmcnt(0)
	v_mfma_f32_32x32x16_bf16 v[2:17], v[60:63], v[66:69], v[2:17]
	ds_read2_b64 v[58:61], v57 offset1:2
	v_sub_f32_e32 v55, v55, v34
	v_exp_f32_e32 v66, v55
	v_sub_f32_e32 v55, v56, v34
	v_exp_f32_e32 v67, v55
	v_add_u32_e32 v55, v204, v201
	v_cvt_pk_bf16_f32 v62, v230, v231
	v_cvt_pk_bf16_f32 v63, v232, v233
	v_cvt_pk_bf16_f32 v64, v234, v235
	v_cvt_pk_bf16_f32 v65, v236, v237
	v_add_u32_e32 v55, 0xc000, v55
	v_sub_f32_e32 v53, v53, v34
	s_waitcnt lgkmcnt(0)
	v_mfma_f32_32x32x16_bf16 v[18:33], v[58:61], v[62:65], v[18:33]
	ds_read2_b64 v[56:59], v55 offset1:2
	v_exp_f32_e32 v68, v53
	v_sub_f32_e32 v53, v54, v34
	v_exp_f32_e32 v69, v53
	v_add_f32_e32 v53, v66, v78
	v_add_f32_e32 v53, v67, v53
	v_add_f32_e32 v53, v68, v53
	v_add_f32_e32 v78, v69, v53
	v_add_u32_e32 v53, v205, v199
	v_add_u32_e32 v53, 0xc000, v53
	s_waitcnt lgkmcnt(0)
	v_mfma_f32_32x32x16_bf16 v[2:17], v[56:59], v[62:65], v[2:17]
	ds_read2_b64 v[54:57], v53 offset1:2
	v_sub_f32_e32 v51, v51, v34
	v_exp_f32_e32 v62, v51
	v_sub_f32_e32 v51, v52, v34
	v_exp_f32_e32 v63, v51
	v_add_u32_e32 v51, v205, v201
	v_cvt_pk_bf16_f32 v58, v238, v239
	v_cvt_pk_bf16_f32 v59, v240, v241
	v_cvt_pk_bf16_f32 v60, v242, v243
	v_cvt_pk_bf16_f32 v61, v244, v245
	v_add_u32_e32 v51, 0xc000, v51
	v_sub_f32_e32 v49, v49, v34
	s_waitcnt lgkmcnt(0)
	v_mfma_f32_32x32x16_bf16 v[18:33], v[54:57], v[58:61], v[18:33]
	ds_read2_b64 v[52:55], v51 offset1:2
	v_exp_f32_e32 v64, v49
	v_sub_f32_e32 v49, v50, v34
	v_exp_f32_e32 v65, v49
	v_add_f32_e32 v49, v62, v78
	v_add_f32_e32 v49, v63, v49
	v_add_f32_e32 v49, v64, v49
	v_add_f32_e32 v78, v65, v49
	v_add_u32_e32 v49, v206, v199
	v_add_u32_e32 v49, 0xc000, v49
	s_waitcnt lgkmcnt(0)
	v_mfma_f32_32x32x16_bf16 v[2:17], v[52:55], v[58:61], v[2:17]
	ds_read2_b64 v[50:53], v49 offset1:2
	v_sub_f32_e32 v47, v47, v34
	v_exp_f32_e32 v58, v47
	v_sub_f32_e32 v47, v48, v34
	v_exp_f32_e32 v59, v47
	v_add_u32_e32 v47, v206, v201
	v_cvt_pk_bf16_f32 v54, v246, v76
	v_cvt_pk_bf16_f32 v55, v77, v74
	v_cvt_pk_bf16_f32 v56, v75, v79
	v_cvt_pk_bf16_f32 v57, v80, v70
	v_add_u32_e32 v47, 0xc000, v47
	v_sub_f32_e32 v45, v45, v34
	s_waitcnt lgkmcnt(0)
	v_mfma_f32_32x32x16_bf16 v[18:33], v[50:53], v[54:57], v[18:33]
	ds_read2_b64 v[48:51], v47 offset1:2
	v_exp_f32_e32 v60, v45
	v_sub_f32_e32 v45, v46, v34
	v_exp_f32_e32 v61, v45
	v_add_f32_e32 v45, v58, v78
	v_add_f32_e32 v45, v59, v45
	v_add_f32_e32 v45, v60, v45
	v_add_f32_e32 v70, v61, v45
	v_add_u32_e32 v45, v207, v199
	v_add_u32_e32 v45, 0xc000, v45
	s_waitcnt lgkmcnt(0)
	v_mfma_f32_32x32x16_bf16 v[2:17], v[48:51], v[54:57], v[2:17]
	ds_read2_b64 v[46:49], v45 offset1:2
	v_sub_f32_e32 v43, v43, v34
	v_exp_f32_e32 v54, v43
	v_sub_f32_e32 v43, v44, v34
	v_exp_f32_e32 v55, v43
	v_add_u32_e32 v43, v207, v201
	v_cvt_pk_bf16_f32 v50, v71, v72
	v_cvt_pk_bf16_f32 v51, v73, v66
	v_cvt_pk_bf16_f32 v52, v67, v68
	v_cvt_pk_bf16_f32 v53, v69, v62
	v_add_u32_e32 v43, 0xc000, v43
	v_sub_f32_e32 v41, v41, v34
	s_waitcnt lgkmcnt(0)
	v_mfma_f32_32x32x16_bf16 v[18:33], v[46:49], v[50:53], v[18:33]
	ds_read2_b64 v[44:47], v43 offset1:2
	v_exp_f32_e32 v56, v41
	v_sub_f32_e32 v41, v42, v34
	v_exp_f32_e32 v57, v41
	v_add_f32_e32 v41, v54, v70
	v_add_f32_e32 v41, v55, v41
	v_add_f32_e32 v41, v56, v41
	v_add_f32_e32 v62, v57, v41
	v_add_u32_e32 v41, v208, v199
	v_add_u32_e32 v41, 0xc000, v41
	s_waitcnt lgkmcnt(0)
; #define LASP __attribute__((address_space(3)))
; __device__ __forceinline__ unsigned cvtpk(float lo, float hi) { return pk2(lo, hi); }
; __device__ __forceinline__ void attn_phase_mfma(const Ctx& c, unsigned char* lds_raw, bool do_store) {
;     ...
;         lsum += __shfl_xor(lsum, 32);
;         f32x16 oacc[2];
;     #pragma unroll
;         for (int db = 0; db < 2; ++db)
;     #pragma unroll
;             for (int e = 0; e < 16; ++e) oacc[db][e] = 0.f;
;     #pragma unroll
;         for (int kb = 0; kb < 5; ++kb)
;     #pragma unroll
;             for (int s2 = 0; s2 < 2; ++s2) {
;                 u32x4 pw;
;     #pragma unroll
;                 for (int e = 0; e < 4; ++e) pw[e] = cvtpk(sacc[kb][8 * s2 + 2 * e], sacc[kb][8 * s2 + 2 * e + 1]);
;                 const bf16x8 pf = __builtin_bit_cast(bf16x8, pw);
;                 const int kp = (32 * wave + 32 * kb + 16 * s2 + 4 * h) >> 1;
;     #pragma unroll
;                 for (int db = 0; db < 2; ++db) {
;                     const LASP unsigned* vp = Vt + (32 * db + rq) * 194 + kp;
;                     const u32x2 g0 = *(const LASP u32x2*)vp, g1 = *(const LASP u32x2*)(vp + 4);
;                     const u32x4 aw = (u32x4){g0.x, g0.y, g1.x, g1.y};
;                     oacc[db] = mfma32_g(__builtin_bit_cast(bf16x8, aw), pf, oacc[db]);
;                 }
;             }
;         asm volatile("s_nop 15\n\ts_nop 15" : "+v"(oacc[0]), "+v"(oacc[1]));
;         if (do_store) {
;             const float inv = 1.f / lsum;
;     #pragma unroll
;             for (int db = 0; db < 2; ++db)
;     #pragma unroll
;                 for (int g4 = 0; g4 < 4; ++g4) {
;                     const u32x2 w = (u32x2){cvtpk(oacc[db][4 * g4] * inv, oacc[db][4 * g4 + 1] * inv), cvtpk(oacc[db][4 * g4 + 2] * inv, oacc[db][4 * g4 + 3] * inv)};
;                     *(u32x2*)(qrow + 32 * db + 8 * g4 + 4 * h) = w;
;                 }
;             if (h == 0) c.LSE[((size_t)g * MT + tokq) * 4 + hI] = mx * 0.69314718f + __logf(lsum);
;         }
;         __syncthreads();
;         if (un >= NAT) break;
;         u = un;
;     }
	v_mfma_f32_32x32x16_bf16 v[2:17], v[44:47], v[50:53], v[2:17]
	ds_read2_b64 v[42:45], v41 offset1:2
	v_sub_f32_e32 v39, v39, v34
	v_exp_f32_e32 v50, v39
	v_sub_f32_e32 v39, v40, v34
	v_exp_f32_e32 v51, v39
	v_add_u32_e32 v39, v208, v201
	v_cvt_pk_bf16_f32 v46, v63, v64
	v_cvt_pk_bf16_f32 v47, v65, v58
	v_cvt_pk_bf16_f32 v48, v59, v60
	v_cvt_pk_bf16_f32 v49, v61, v54
	v_add_u32_e32 v39, 0xc000, v39
	v_sub_f32_e32 v36, v36, v34
	s_waitcnt lgkmcnt(0)
	v_mfma_f32_32x32x16_bf16 v[18:33], v[42:45], v[46:49], v[18:33]
	ds_read2_b64 v[40:43], v39 offset1:2
	v_exp_f32_e32 v45, v36
	v_sub_f32_e32 v36, v37, v34
	v_exp_f32_e32 v52, v36
	v_sub_f32_e32 v36, v38, v34
	v_exp_f32_e32 v53, v36
	v_add_u32_e32 v36, v209, v199
	v_add_f32_e32 v39, v50, v62
	v_add_u32_e32 v36, 0xc000, v36
	v_add_f32_e32 v44, v51, v39
	s_waitcnt lgkmcnt(0)
	v_mfma_f32_32x32x16_bf16 v[2:17], v[40:43], v[46:49], v[2:17]
	ds_read2_b64 v[36:39], v36 offset1:2
	v_add_f32_e32 v40, v45, v44
	v_add_f32_e32 v40, v52, v40
	v_add_f32_e32 v44, v53, v40
	v_cvt_pk_bf16_f32 v40, v55, v56
	v_cvt_pk_bf16_f32 v41, v57, v50
	v_cvt_pk_bf16_f32 v42, v51, v45
	v_cvt_pk_bf16_f32 v43, v52, v53
	ds_bpermute_b32 v35, v35, v44
	s_waitcnt lgkmcnt(0)
	v_add_f32_e32 v35, v44, v35
	v_mfma_f32_32x32x16_bf16 v[18:33], v[36:39], v[40:43], v[18:33]
	v_add_u32_e32 v36, v209, v201
	v_add_u32_e32 v36, 0xc000, v36
	ds_read2_b64 v[36:39], v36 offset1:2
	v_div_scale_f32 v44, s[0:1], v35, v35, 1.0
	v_rcp_f32_e32 v45, v44
	s_waitcnt lgkmcnt(0)
	v_mfma_f32_32x32x16_bf16 v[2:17], v[36:39], v[40:43], v[2:17]
	v_fma_f32 v36, -v44, v45, 1.0
	v_fmac_f32_e32 v45, v36, v45
	v_div_scale_f32 v36, vcc, 1.0, v35, 1.0
	v_mul_f32_e32 v37, v36, v45
	v_fma_f32 v38, -v44, v37, v36
	v_fmac_f32_e32 v37, v38, v45
	v_fma_f32 v36, -v44, v37, v36
	v_div_fmas_f32 v36, v36, v45, v37
	s_nop 15
	s_nop 15
	v_div_fixup_f32 v36, v36, v35, 1.0
	v_lshlrev_b32_e32 v38, 1, v166
	v_and_b32_e32 v39, 32, v0
	v_lshrrev_b32_e32 v39, 2, v39
	v_add_u32_e32 v38, v38, v39
	v_mov_b32_e32 v39, v106
	v_lshl_add_u64 v[38:39], v[174:175], 0, v[38:39]
	v_pk_mul_f32 v[18:19], v[18:19], v[36:37] op_sel_hi:[1,0]
	v_pk_mul_f32 v[20:21], v[20:21], v[36:37] op_sel_hi:[1,0]
	v_cvt_pk_bf16_f32 v18, v18, v19
	v_cvt_pk_bf16_f32 v19, v20, v21
	v_pk_mul_f32 v[20:21], v[22:23], v[36:37] op_sel_hi:[1,0]
	v_pk_mul_f32 v[22:23], v[24:25], v[36:37] op_sel_hi:[1,0]
	v_cvt_pk_bf16_f32 v20, v20, v21
	v_cvt_pk_bf16_f32 v21, v22, v23
	v_pk_mul_f32 v[2:3], v[2:3], v[36:37] op_sel_hi:[1,0]
	v_pk_mul_f32 v[4:5], v[4:5], v[36:37] op_sel_hi:[1,0]
	v_permlane32_swap_b32_e32 v18, v20
	v_permlane32_swap_b32_e32 v19, v21
	v_cvt_pk_bf16_f32 v2, v2, v3
	v_cvt_pk_bf16_f32 v3, v4, v5
	v_pk_mul_f32 v[4:5], v[6:7], v[36:37] op_sel_hi:[1,0]
	v_pk_mul_f32 v[6:7], v[8:9], v[36:37] op_sel_hi:[1,0]
	global_store_dwordx4 v[38:39], v[18:21], off offset:1536
	v_cvt_pk_bf16_f32 v4, v4, v5
	v_cvt_pk_bf16_f32 v5, v6, v7
	v_pk_mul_f32 v[22:23], v[26:27], v[36:37] op_sel_hi:[1,0]
	v_pk_mul_f32 v[24:25], v[28:29], v[36:37] op_sel_hi:[1,0]
	v_permlane32_swap_b32_e32 v2, v4
	v_permlane32_swap_b32_e32 v3, v5
	v_cvt_pk_bf16_f32 v22, v22, v23
	v_cvt_pk_bf16_f32 v23, v24, v25
	v_pk_mul_f32 v[24:25], v[30:31], v[36:37] op_sel_hi:[1,0]
	v_pk_mul_f32 v[26:27], v[32:33], v[36:37] op_sel_hi:[1,0]
	global_store_dwordx4 v[38:39], v[2:5], off offset:1600
	v_cvt_pk_bf16_f32 v24, v24, v25
	v_cvt_pk_bf16_f32 v25, v26, v27
	v_pk_mul_f32 v[6:7], v[10:11], v[36:37] op_sel_hi:[1,0]
	v_pk_mul_f32 v[8:9], v[12:13], v[36:37] op_sel_hi:[1,0]
	v_permlane32_swap_b32_e32 v22, v24
	v_permlane32_swap_b32_e32 v23, v25
	v_cvt_pk_bf16_f32 v6, v6, v7
	v_cvt_pk_bf16_f32 v7, v8, v9
	v_pk_mul_f32 v[8:9], v[14:15], v[36:37] op_sel_hi:[1,0]
	v_pk_mul_f32 v[10:11], v[16:17], v[36:37] op_sel_hi:[1,0]
	global_store_dwordx4 v[38:39], v[22:25], off offset:1568
	v_cvt_pk_bf16_f32 v8, v8, v9
	v_cvt_pk_bf16_f32 v9, v10, v11
	s_nop 1
	v_permlane32_swap_b32_e32 v6, v8
	v_permlane32_swap_b32_e32 v7, v9
	global_store_dwordx4 v[38:39], v[6:9], off offset:1632
	s_mov_b64 s[0:1], exec
	v_readlane_b32 s10, v255, 15
	v_readlane_b32 s11, v255, 16
	s_and_b64 s[10:11], s[0:1], s[10:11]
	s_mov_b64 exec, s[10:11]
	s_cbranch_execz .LBB0_1718
	s_mov_b32 s3, 0x800000
	v_cmp_gt_f32_e32 vcc, s3, v35
	s_mov_b32 s3, 0x3f317217
	s_ashr_i32 s89, s88, 31
	v_cndmask_b32_e64 v2, 0, 32, vcc
	v_ldexp_f32 v2, v35, v2
	v_log_f32_e32 v2, v2
	v_cndmask_b32_e32 v3, 0, v223, vcc
	s_lshl_b64 s[10:11], s[88:89], 19
	v_mul_f32_e32 v4, 0x3f317217, v2
	v_fma_f32 v4, v2, s3, -v4
	s_mov_b32 s3, 0x7f800000
	v_fmac_f32_e32 v4, 0x3377d1cf, v2
	v_cmp_lt_f32_e64 vcc, |v2|, s3
	v_readlane_b32 s3, v255, 13
	v_fmac_f32_e32 v4, 0x3f317217, v2
	s_add_u32 s10, s3, s10
	v_readlane_b32 s3, v255, 14
	v_cndmask_b32_e32 v2, v2, v4, vcc
	s_addc_u32 s11, s3, s11
	v_sub_f32_e32 v4, v2, v3
	v_lshl_add_u64 v[2:3], v[108:109], 4, s[10:11]
	s_lshl_b32 s96, s2, 2
	v_fmac_f32_e32 v4, 0x3f317218, v34
	v_lshl_add_u64 v[2:3], v[2:3], 0, s[96:97]
	global_store_dword v[2:3], v4, off
	s_branch .LBB0_1718
	s_nop 0
